# GEMM K-loops: same-accumulator MFMAs adjacent, setprio moved outside barriers, LDS-DMA saddr form (no VALU adds); attention QK counted lgkmcnt waits
# speedup vs baseline: 1.0161x; 1.0161x over previous
; #define PG8_STAGE(bufoff, gbase, voff) do { _Pragma("unroll") for (int _i = 0; _i < 2; ++_i) \
;         __builtin_amdgcn_global_load_lds((const unsigned*)((const char*)(gbase) + (voff)[_i]), (PG8_LAS unsigned*)(lds + (bufoff) + ldsw + _i * 8192), 16, 0, 0); } while (0)
; #define PG8_LDA(dst, b, h) do { _Pragma("unroll") for (int m = 0; m < 4; ++m) _Pragma("unroll") for (int k = 0; k < 2; ++k) dst[m][k] = *(const PG8_LAS bf16x8*)(lds + PG8_SA(b, h) + aoff + m * 2048 + k * 1024); } while (0)
; #define PG8_WAIT_V(n) asm volatile("s_waitcnt vmcnt(" #n ")" ::: "memory")
; #define PG8_WAIT_L(n) asm volatile("s_waitcnt lgkmcnt(" #n ")" ::: "memory")
; #define PG8_BAR __builtin_amdgcn_s_barrier()
; template <class Epi, class Sched, bool ALIGN_EPI = false, bool SP2 = false, bool A_TILED = false>
; __device__ __forceinline__ void gemm_phase(PG8_LAS unsigned char* lds, const Gemm g, const Sched& S, const Epi& E) {
;     ...
;         for (int t = 0; t < nt; t += 2) {
;             const bool last = (t == nt - 2);
;             const char* a1 = cA + (size_t)(t + 1) * kstepA;
;             const char* a2 = last ? nA : cA + (size_t)(t + 2) * kstepA; const char* b2 = last ? nB : cB + (size_t)(t + 2) * kstepB;
;             const char* a3 = a2 + kstepA; const char* b3 = b2 + kstepB;
;             if (last && has_next) S.a_ready(nxt);
;             if constexpr (SP2) {
;             PG8_LDB(B0, 0, 0); PG8_LDB(B1, 0, 1); PG8_SCHED; PG8_LDA(At, 0, 0); PG8_STAGE(PG8_SA(1, 1), a1 + hstepA, voffA);
;             PG8_WAIT_V(8); PG8_WAIT_L(0); PG8_BAR; PG8_MMA(0, 0, At, B0); PG8_MMA(0, 1, At, B1); PG8_BAR; PG8_SCHED;
;             PG8_LDA(At, 0, 1); PG8_STAGE(PG8_SB(0, 0), b2, voffB); PG8_STAGE(PG8_SB(0, 1), b2 + hstepB, voffB); PG8_STAGE(PG8_SA(0, 0), a2, voffA);
;             PG8_WAIT_V(8); PG8_WAIT_L(0); PG8_BAR; PG8_MMA(1, 0, At, B0); PG8_MMA(1, 1, At, B1); PG8_BAR; PG8_SCHED;
;             PG8_LDB(B0, 1, 0); PG8_LDB(B1, 1, 1); PG8_SCHED; PG8_LDA(At, 1, 0); PG8_STAGE(PG8_SA(0, 1), a2 + hstepA, voffA);
;             PG8_WAIT_V(8); PG8_WAIT_L(0); PG8_BAR; PG8_MMA(0, 0, At, B0); PG8_MMA(0, 1, At, B1); PG8_BAR; PG8_SCHED;
;             PG8_LDA(At, 1, 1); PG8_STAGE(PG8_SB(1, 0), b3, voffB); PG8_STAGE(PG8_SB(1, 1), b3 + hstepB, voffB); PG8_STAGE(PG8_SA(1, 0), a3, voffA);
;             PG8_WAIT_V(8); PG8_WAIT_L(0); PG8_BAR; PG8_MMA(1, 0, At, B0); PG8_MMA(1, 1, At, B1); PG8_BAR; PG8_SCHED;
.LBB0_195:
	ds_read_b128 v[168:171], v164
	ds_read_b128 v[172:175], v164 offset:1024
	ds_read_b128 v[176:179], v164 offset:2048
	ds_read_b128 v[180:183], v164 offset:3072
	ds_read_b128 v[184:187], v165
	ds_read_b128 v[188:191], v165 offset:1024
	ds_read_b128 v[192:195], v165 offset:2048
	ds_read_b128 v[196:199], v165 offset:3072
	s_add_u32 s26, s22, 0x4000
	s_addc_u32 s27, s23, 0
	s_cmp_eq_u32 s70, 60
	s_cselect_b32 s30, s59, s26
	s_cselect_b32 s31, s15, s27
	s_cselect_b32 s28, s62, s63
	s_cselect_b32 s29, s13, s69
	s_add_u32 s26, s30, 0x8000
	s_addc_u32 s27, s31, 0
	s_add_i32 m0, s36, 0xc000
	ds_read_b128 v[200:203], v166
	ds_read_b128 v[204:207], v166 offset:1024
	ds_read_b128 v[208:211], v166 offset:2048
	ds_read_b128 v[212:215], v166 offset:3072
	ds_read_b128 v[216:219], v166 offset:4096
	ds_read_b128 v[220:223], v166 offset:5120
	ds_read_b128 v[224:227], v166 offset:6144
	ds_read_b128 v[228:231], v166 offset:7168
	global_load_lds_dwordx4 v156, s[22:23]
	s_add_i32 m0, s36, 0xe000
	s_nop 0
	global_load_lds_dwordx4 v158, s[22:23]
	s_waitcnt vmcnt(8)
	s_waitcnt lgkmcnt(0)
	s_setprio 1
	s_barrier
	v_mfma_f32_16x16x32_bf16 v[126:129], v[168:171], v[200:203], v[126:129]
	v_mfma_f32_16x16x32_bf16 v[126:129], v[172:175], v[204:207], v[126:129]
	v_mfma_f32_16x16x32_bf16 v[118:121], v[176:179], v[200:203], v[118:121]
	v_mfma_f32_16x16x32_bf16 v[118:121], v[180:183], v[204:207], v[118:121]
	v_mfma_f32_16x16x32_bf16 v[122:125], v[184:187], v[200:203], v[122:125]
	v_mfma_f32_16x16x32_bf16 v[122:125], v[188:191], v[204:207], v[122:125]
	v_mfma_f32_16x16x32_bf16 v[114:117], v[192:195], v[200:203], v[114:117]
	v_mfma_f32_16x16x32_bf16 v[114:117], v[196:199], v[204:207], v[114:117]
	v_mfma_f32_16x16x32_bf16 v[110:113], v[168:171], v[208:211], v[110:113]
	v_mfma_f32_16x16x32_bf16 v[110:113], v[172:175], v[212:215], v[110:113]
	v_mfma_f32_16x16x32_bf16 v[102:105], v[176:179], v[208:211], v[102:105]
	v_mfma_f32_16x16x32_bf16 v[102:105], v[180:183], v[212:215], v[102:105]
	v_mfma_f32_16x16x32_bf16 v[106:109], v[184:187], v[208:211], v[106:109]
	v_mfma_f32_16x16x32_bf16 v[106:109], v[188:191], v[212:215], v[106:109]
	v_mfma_f32_16x16x32_bf16 v[98:101], v[192:195], v[208:211], v[98:101]
	v_mfma_f32_16x16x32_bf16 v[98:101], v[196:199], v[212:215], v[98:101]
	v_mfma_f32_16x16x32_bf16 v[94:97], v[168:171], v[216:219], v[94:97]
	v_mfma_f32_16x16x32_bf16 v[94:97], v[172:175], v[220:223], v[94:97]
	v_mfma_f32_16x16x32_bf16 v[86:89], v[176:179], v[216:219], v[86:89]
	v_mfma_f32_16x16x32_bf16 v[86:89], v[180:183], v[220:223], v[86:89]
	v_mfma_f32_16x16x32_bf16 v[90:93], v[184:187], v[216:219], v[90:93]
	v_mfma_f32_16x16x32_bf16 v[90:93], v[188:191], v[220:223], v[90:93]
	v_mfma_f32_16x16x32_bf16 v[82:85], v[192:195], v[216:219], v[82:85]
	v_mfma_f32_16x16x32_bf16 v[82:85], v[196:199], v[220:223], v[82:85]
	v_mfma_f32_16x16x32_bf16 v[78:81], v[168:171], v[224:227], v[78:81]
	v_mfma_f32_16x16x32_bf16 v[78:81], v[172:175], v[228:231], v[78:81]
	v_mfma_f32_16x16x32_bf16 v[70:73], v[176:179], v[224:227], v[70:73]
	v_mfma_f32_16x16x32_bf16 v[70:73], v[180:183], v[228:231], v[70:73]
	v_mfma_f32_16x16x32_bf16 v[74:77], v[184:187], v[224:227], v[74:77]
	v_mfma_f32_16x16x32_bf16 v[74:77], v[188:191], v[228:231], v[74:77]
	v_mfma_f32_16x16x32_bf16 v[66:69], v[192:195], v[224:227], v[66:69]
	v_mfma_f32_16x16x32_bf16 v[66:69], v[196:199], v[228:231], v[66:69]
	s_barrier
	s_setprio 0
	s_add_i32 s71, s45, s34
	s_mov_b32 m0, s71
	ds_read_b128 v[200:203], v166 offset:16384
	ds_read_b128 v[204:207], v166 offset:17408
	ds_read_b128 v[208:211], v166 offset:18432
	ds_read_b128 v[212:215], v166 offset:19456
	ds_read_b128 v[216:219], v166 offset:20480
	ds_read_b128 v[220:223], v166 offset:21504
	ds_read_b128 v[224:227], v166 offset:22528
	ds_read_b128 v[228:231], v166 offset:23552
	global_load_lds_dwordx4 v132, s[28:29]
	s_add_i32 m0, s71, 0x2000
	s_add_u32 s72, s28, 0x4000
	s_addc_u32 s73, s29, 0
	s_add_i32 s71, s58, s34
	global_load_lds_dwordx4 v136, s[28:29]
	s_mov_b32 m0, s71
	s_nop 0
	global_load_lds_dwordx4 v132, s[72:73]
	s_add_i32 m0, s71, 0x2000
	s_nop 0
	global_load_lds_dwordx4 v136, s[72:73]
	s_mov_b32 m0, s36
	s_nop 0
	global_load_lds_dwordx4 v130, s[30:31]
	s_mov_b32 m0, s37
	s_nop 0
	global_load_lds_dwordx4 v134, s[30:31]
	s_waitcnt vmcnt(8)
	s_waitcnt lgkmcnt(0)
	s_setprio 1
	s_barrier
	v_mfma_f32_16x16x32_bf16 v[62:65], v[168:171], v[200:203], v[62:65]
	v_mfma_f32_16x16x32_bf16 v[62:65], v[172:175], v[204:207], v[62:65]
	v_mfma_f32_16x16x32_bf16 v[54:57], v[176:179], v[200:203], v[54:57]
	v_mfma_f32_16x16x32_bf16 v[54:57], v[180:183], v[204:207], v[54:57]
	v_mfma_f32_16x16x32_bf16 v[58:61], v[184:187], v[200:203], v[58:61]
	v_mfma_f32_16x16x32_bf16 v[58:61], v[188:191], v[204:207], v[58:61]
	v_mfma_f32_16x16x32_bf16 v[50:53], v[192:195], v[200:203], v[50:53]
	v_mfma_f32_16x16x32_bf16 v[50:53], v[196:199], v[204:207], v[50:53]
	v_mfma_f32_16x16x32_bf16 v[46:49], v[168:171], v[208:211], v[46:49]
	v_mfma_f32_16x16x32_bf16 v[46:49], v[172:175], v[212:215], v[46:49]
	v_mfma_f32_16x16x32_bf16 v[38:41], v[176:179], v[208:211], v[38:41]
	v_mfma_f32_16x16x32_bf16 v[38:41], v[180:183], v[212:215], v[38:41]
	v_mfma_f32_16x16x32_bf16 v[42:45], v[184:187], v[208:211], v[42:45]
	v_mfma_f32_16x16x32_bf16 v[42:45], v[188:191], v[212:215], v[42:45]
	v_mfma_f32_16x16x32_bf16 v[34:37], v[192:195], v[208:211], v[34:37]
	v_mfma_f32_16x16x32_bf16 v[34:37], v[196:199], v[212:215], v[34:37]
	v_mfma_f32_16x16x32_bf16 v[30:33], v[168:171], v[216:219], v[30:33]
	v_mfma_f32_16x16x32_bf16 v[30:33], v[172:175], v[220:223], v[30:33]
	v_mfma_f32_16x16x32_bf16 v[22:25], v[176:179], v[216:219], v[22:25]
	v_mfma_f32_16x16x32_bf16 v[22:25], v[180:183], v[220:223], v[22:25]
	v_mfma_f32_16x16x32_bf16 v[26:29], v[184:187], v[216:219], v[26:29]
	v_mfma_f32_16x16x32_bf16 v[26:29], v[188:191], v[220:223], v[26:29]
	v_mfma_f32_16x16x32_bf16 v[18:21], v[192:195], v[216:219], v[18:21]
	v_mfma_f32_16x16x32_bf16 v[18:21], v[196:199], v[220:223], v[18:21]
	v_mfma_f32_16x16x32_bf16 v[14:17], v[168:171], v[224:227], v[14:17]
	v_mfma_f32_16x16x32_bf16 v[14:17], v[172:175], v[228:231], v[14:17]
	v_mfma_f32_16x16x32_bf16 v[6:9], v[176:179], v[224:227], v[6:9]
	v_mfma_f32_16x16x32_bf16 v[6:9], v[180:183], v[228:231], v[6:9]
	v_mfma_f32_16x16x32_bf16 v[10:13], v[184:187], v[224:227], v[10:13]
	v_mfma_f32_16x16x32_bf16 v[10:13], v[188:191], v[228:231], v[10:13]
	v_mfma_f32_16x16x32_bf16 v[2:5], v[192:195], v[224:227], v[2:5]
	v_mfma_f32_16x16x32_bf16 v[2:5], v[196:199], v[228:231], v[2:5]
	s_barrier
; #define PG8_STAGE(bufoff, gbase, voff) do { _Pragma("unroll") for (int _i = 0; _i < 2; ++_i) \
;         __builtin_amdgcn_global_load_lds((const unsigned*)((const char*)(gbase) + (voff)[_i]), (PG8_LAS unsigned*)(lds + (bufoff) + ldsw + _i * 8192), 16, 0, 0); } while (0)
; #define PG8_LDA(dst, b, h) do { _Pragma("unroll") for (int m = 0; m < 4; ++m) _Pragma("unroll") for (int k = 0; k < 2; ++k) dst[m][k] = *(const PG8_LAS bf16x8*)(lds + PG8_SA(b, h) + aoff + m * 2048 + k * 1024); } while (0)
; #define PG8_WAIT_V(n) asm volatile("s_waitcnt vmcnt(" #n ")" ::: "memory")
; #define PG8_WAIT_L(n) asm volatile("s_waitcnt lgkmcnt(" #n ")" ::: "memory")
; #define PG8_BAR __builtin_amdgcn_s_barrier()
; template <class Epi, class Sched, bool ALIGN_EPI = false, bool SP2 = false, bool A_TILED = false>
; __device__ __forceinline__ void gemm_phase(PG8_LAS unsigned char* lds, const Gemm g, const Sched& S, const Epi& E) {
;     ...
;         for (int t = 0; t < nt; t += 2) {
;             const bool last = (t == nt - 2);
;             const char* a1 = cA + (size_t)(t + 1) * kstepA;
;             const char* a2 = last ? nA : cA + (size_t)(t + 2) * kstepA; const char* b2 = last ? nB : cB + (size_t)(t + 2) * kstepB;
;             const char* a3 = a2 + kstepA; const char* b3 = b2 + kstepB;
;             if (last && has_next) S.a_ready(nxt);
;             if constexpr (SP2) {
;             PG8_LDB(B0, 0, 0); PG8_LDB(B1, 0, 1); PG8_SCHED; PG8_LDA(At, 0, 0); PG8_STAGE(PG8_SA(1, 1), a1 + hstepA, voffA);
;             PG8_WAIT_V(8); PG8_WAIT_L(0); PG8_BAR; PG8_MMA(0, 0, At, B0); PG8_MMA(0, 1, At, B1); PG8_BAR; PG8_SCHED;
;             PG8_LDA(At, 0, 1); PG8_STAGE(PG8_SB(0, 0), b2, voffB); PG8_STAGE(PG8_SB(0, 1), b2 + hstepB, voffB); PG8_STAGE(PG8_SA(0, 0), a2, voffA);
;             PG8_WAIT_V(8); PG8_WAIT_L(0); PG8_BAR; PG8_MMA(1, 0, At, B0); PG8_MMA(1, 1, At, B1); PG8_BAR; PG8_SCHED;
;             PG8_LDB(B0, 1, 0); PG8_LDB(B1, 1, 1); PG8_SCHED; PG8_LDA(At, 1, 0); PG8_STAGE(PG8_SA(0, 1), a2 + hstepA, voffA);
;             PG8_WAIT_V(8); PG8_WAIT_L(0); PG8_BAR; PG8_MMA(0, 0, At, B0); PG8_MMA(0, 1, At, B1); PG8_BAR; PG8_SCHED;
;             PG8_LDA(At, 1, 1); PG8_STAGE(PG8_SB(1, 0), b3, voffB); PG8_STAGE(PG8_SB(1, 1), b3 + hstepB, voffB); PG8_STAGE(PG8_SA(1, 0), a3, voffA);
;             PG8_WAIT_V(8); PG8_WAIT_L(0); PG8_BAR; PG8_MMA(1, 0, At, B0); PG8_MMA(1, 1, At, B1); PG8_BAR; PG8_SCHED;
	s_setprio 0
	s_add_i32 s71, 0, 0x18000
	v_add_u32_e32 v167, s71, v1
	s_add_i32 s72, 0, 0x1c000
	ds_read_b128 v[168:171], v167
	ds_read_b128 v[172:175], v167 offset:1024
	ds_read_b128 v[176:179], v167 offset:2048
	ds_read_b128 v[180:183], v167 offset:3072
	v_add_u32_e32 v167, s72, v1
	ds_read_b128 v[184:187], v167
	ds_read_b128 v[188:191], v167 offset:1024
	ds_read_b128 v[192:195], v167 offset:2048
	ds_read_b128 v[196:199], v167 offset:3072
	s_add_u32 s30, s30, 0x4000
	s_addc_u32 s31, s31, 0
	s_mov_b32 m0, s38
	ds_read_b128 v[200:203], v166 offset:32768
	ds_read_b128 v[204:207], v166 offset:33792
	ds_read_b128 v[208:211], v166 offset:34816
	ds_read_b128 v[212:215], v166 offset:35840
	ds_read_b128 v[216:219], v166 offset:36864
	ds_read_b128 v[220:223], v166 offset:37888
	ds_read_b128 v[224:227], v166 offset:38912
	ds_read_b128 v[228:231], v166 offset:39936
	global_load_lds_dwordx4 v130, s[30:31]
	s_mov_b32 m0, s39
	s_nop 0
	global_load_lds_dwordx4 v134, s[30:31]
	s_waitcnt vmcnt(8)
	s_waitcnt lgkmcnt(0)
	s_setprio 1
	s_barrier
	v_mfma_f32_16x16x32_bf16 v[126:129], v[168:171], v[200:203], v[126:129]
	v_mfma_f32_16x16x32_bf16 v[126:129], v[172:175], v[204:207], v[126:129]
	v_mfma_f32_16x16x32_bf16 v[118:121], v[176:179], v[200:203], v[118:121]
	v_mfma_f32_16x16x32_bf16 v[118:121], v[180:183], v[204:207], v[118:121]
	v_mfma_f32_16x16x32_bf16 v[122:125], v[184:187], v[200:203], v[122:125]
	v_mfma_f32_16x16x32_bf16 v[122:125], v[188:191], v[204:207], v[122:125]
	v_mfma_f32_16x16x32_bf16 v[114:117], v[192:195], v[200:203], v[114:117]
	v_mfma_f32_16x16x32_bf16 v[114:117], v[196:199], v[204:207], v[114:117]
	v_mfma_f32_16x16x32_bf16 v[110:113], v[168:171], v[208:211], v[110:113]
	v_mfma_f32_16x16x32_bf16 v[110:113], v[172:175], v[212:215], v[110:113]
	v_mfma_f32_16x16x32_bf16 v[102:105], v[176:179], v[208:211], v[102:105]
	v_mfma_f32_16x16x32_bf16 v[102:105], v[180:183], v[212:215], v[102:105]
	v_mfma_f32_16x16x32_bf16 v[106:109], v[184:187], v[208:211], v[106:109]
	v_mfma_f32_16x16x32_bf16 v[106:109], v[188:191], v[212:215], v[106:109]
	v_mfma_f32_16x16x32_bf16 v[98:101], v[192:195], v[208:211], v[98:101]
	v_mfma_f32_16x16x32_bf16 v[98:101], v[196:199], v[212:215], v[98:101]
	v_mfma_f32_16x16x32_bf16 v[94:97], v[168:171], v[216:219], v[94:97]
	v_mfma_f32_16x16x32_bf16 v[94:97], v[172:175], v[220:223], v[94:97]
	v_mfma_f32_16x16x32_bf16 v[86:89], v[176:179], v[216:219], v[86:89]
	v_mfma_f32_16x16x32_bf16 v[86:89], v[180:183], v[220:223], v[86:89]
	v_mfma_f32_16x16x32_bf16 v[90:93], v[184:187], v[216:219], v[90:93]
	v_mfma_f32_16x16x32_bf16 v[90:93], v[188:191], v[220:223], v[90:93]
	v_mfma_f32_16x16x32_bf16 v[82:85], v[192:195], v[216:219], v[82:85]
	v_mfma_f32_16x16x32_bf16 v[82:85], v[196:199], v[220:223], v[82:85]
	v_mfma_f32_16x16x32_bf16 v[78:81], v[168:171], v[224:227], v[78:81]
	v_mfma_f32_16x16x32_bf16 v[78:81], v[172:175], v[228:231], v[78:81]
	v_mfma_f32_16x16x32_bf16 v[70:73], v[176:179], v[224:227], v[70:73]
	v_mfma_f32_16x16x32_bf16 v[70:73], v[180:183], v[228:231], v[70:73]
	v_mfma_f32_16x16x32_bf16 v[74:77], v[184:187], v[224:227], v[74:77]
	v_mfma_f32_16x16x32_bf16 v[74:77], v[188:191], v[228:231], v[74:77]
	v_mfma_f32_16x16x32_bf16 v[66:69], v[192:195], v[224:227], v[66:69]
	v_mfma_f32_16x16x32_bf16 v[66:69], v[196:199], v[228:231], v[66:69]
	s_barrier
	s_setprio 0
	s_add_u32 s30, s28, 0x8000
	s_addc_u32 s31, s29, 0
	s_add_i32 s71, s71, s34
	s_mov_b32 m0, s71
	ds_read_b128 v[200:203], v166 offset:49152
	ds_read_b128 v[204:207], v166 offset:50176
	ds_read_b128 v[208:211], v166 offset:51200
	ds_read_b128 v[212:215], v166 offset:52224
	ds_read_b128 v[216:219], v166 offset:53248
	ds_read_b128 v[220:223], v166 offset:54272
	ds_read_b128 v[224:227], v166 offset:55296
	ds_read_b128 v[228:231], v166 offset:56320
	global_load_lds_dwordx4 v132, s[30:31]
	s_add_i32 m0, s71, 0x2000
	s_add_u32 s28, s28, 0xc000
	v_lshl_add_u64 v[232:233], s[30:31], 0, v[136:137]
	s_addc_u32 s29, s29, 0
	s_add_i32 s30, s72, s34
	global_load_lds_dwordx4 v[232:233], off
	s_mov_b32 m0, s30
	s_nop 0
	global_load_lds_dwordx4 v132, s[28:29]
	s_add_i32 m0, s30, 0x2000
	s_nop 0
	global_load_lds_dwordx4 v136, s[28:29]
	s_mov_b32 m0, s43
	s_nop 0
	global_load_lds_dwordx4 v130, s[26:27]
	s_mov_b32 m0, s44
	s_nop 0
	global_load_lds_dwordx4 v134, s[26:27]
	s_waitcnt vmcnt(8)
	s_waitcnt lgkmcnt(0)
	s_setprio 1
	s_barrier
	v_mfma_f32_16x16x32_bf16 v[62:65], v[168:171], v[200:203], v[62:65]
	v_mfma_f32_16x16x32_bf16 v[62:65], v[172:175], v[204:207], v[62:65]
	v_mfma_f32_16x16x32_bf16 v[54:57], v[176:179], v[200:203], v[54:57]
	v_mfma_f32_16x16x32_bf16 v[54:57], v[180:183], v[204:207], v[54:57]
	v_mfma_f32_16x16x32_bf16 v[58:61], v[184:187], v[200:203], v[58:61]
	v_mfma_f32_16x16x32_bf16 v[58:61], v[188:191], v[204:207], v[58:61]
	v_mfma_f32_16x16x32_bf16 v[50:53], v[192:195], v[200:203], v[50:53]
	v_mfma_f32_16x16x32_bf16 v[50:53], v[196:199], v[204:207], v[50:53]
	v_mfma_f32_16x16x32_bf16 v[46:49], v[168:171], v[208:211], v[46:49]
	v_mfma_f32_16x16x32_bf16 v[46:49], v[172:175], v[212:215], v[46:49]
	v_mfma_f32_16x16x32_bf16 v[38:41], v[176:179], v[208:211], v[38:41]
	v_mfma_f32_16x16x32_bf16 v[38:41], v[180:183], v[212:215], v[38:41]
	v_mfma_f32_16x16x32_bf16 v[42:45], v[184:187], v[208:211], v[42:45]
	v_mfma_f32_16x16x32_bf16 v[42:45], v[188:191], v[212:215], v[42:45]
	v_mfma_f32_16x16x32_bf16 v[34:37], v[192:195], v[208:211], v[34:37]
	v_mfma_f32_16x16x32_bf16 v[34:37], v[196:199], v[212:215], v[34:37]
	v_mfma_f32_16x16x32_bf16 v[30:33], v[168:171], v[216:219], v[30:33]
	v_mfma_f32_16x16x32_bf16 v[30:33], v[172:175], v[220:223], v[30:33]
	v_mfma_f32_16x16x32_bf16 v[22:25], v[176:179], v[216:219], v[22:25]
	v_mfma_f32_16x16x32_bf16 v[22:25], v[180:183], v[220:223], v[22:25]
	v_mfma_f32_16x16x32_bf16 v[26:29], v[184:187], v[216:219], v[26:29]
	v_mfma_f32_16x16x32_bf16 v[26:29], v[188:191], v[220:223], v[26:29]
	v_mfma_f32_16x16x32_bf16 v[18:21], v[192:195], v[216:219], v[18:21]
	v_mfma_f32_16x16x32_bf16 v[18:21], v[196:199], v[220:223], v[18:21]
	v_mfma_f32_16x16x32_bf16 v[14:17], v[168:171], v[224:227], v[14:17]
	v_mfma_f32_16x16x32_bf16 v[14:17], v[172:175], v[228:231], v[14:17]
	v_mfma_f32_16x16x32_bf16 v[6:9], v[176:179], v[224:227], v[6:9]
	v_mfma_f32_16x16x32_bf16 v[6:9], v[180:183], v[228:231], v[6:9]
	v_mfma_f32_16x16x32_bf16 v[10:13], v[184:187], v[224:227], v[10:13]
	v_mfma_f32_16x16x32_bf16 v[10:13], v[188:191], v[228:231], v[10:13]
	v_mfma_f32_16x16x32_bf16 v[2:5], v[192:195], v[224:227], v[2:5]
	v_mfma_f32_16x16x32_bf16 v[2:5], v[196:199], v[228:231], v[2:5]
	s_barrier
	s_setprio 0
	s_add_i32 s70, s70, 2
	s_add_u32 s22, s22, 0x10000
	s_addc_u32 s23, s23, 0
	s_add_u32 s63, s63, 0x10000
	s_addc_u32 s69, s69, 0
	s_cmp_gt_u32 s70, 61
	s_cbranch_scc0 .LBB0_195
	s_and_b64 vcc, exec, s[10:11]
	s_cbranch_vccz .LBB0_198
	s_barrier

; #define PG8_STAGE(bufoff, gbase, voff) do { _Pragma("unroll") for (int _i = 0; _i < 2; ++_i) \
;         __builtin_amdgcn_global_load_lds((const unsigned*)((const char*)(gbase) + (voff)[_i]), (PG8_LAS unsigned*)(lds + (bufoff) + ldsw + _i * 8192), 16, 0, 0); } while (0)
; #define PG8_LDA(dst, b, h) do { _Pragma("unroll") for (int m = 0; m < 4; ++m) _Pragma("unroll") for (int k = 0; k < 2; ++k) dst[m][k] = *(const PG8_LAS bf16x8*)(lds + PG8_SA(b, h) + aoff + m * 2048 + k * 1024); } while (0)
; #define PG8_WAIT_V(n) asm volatile("s_waitcnt vmcnt(" #n ")" ::: "memory")
; #define PG8_WAIT_L(n) asm volatile("s_waitcnt lgkmcnt(" #n ")" ::: "memory")
; #define PG8_BAR __builtin_amdgcn_s_barrier()
; template <class Epi, class Sched, bool ALIGN_EPI = false, bool SP2 = false, bool A_TILED = false>
; __device__ __forceinline__ void gemm_phase(PG8_LAS unsigned char* lds, const Gemm g, const Sched& S, const Epi& E) {
;     ...
;         for (int t = 0; t < nt; t += 2) {
;             const bool last = (t == nt - 2);
;             const char* a1 = cA + (size_t)(t + 1) * kstepA;
;             const char* a2 = last ? nA : cA + (size_t)(t + 2) * kstepA; const char* b2 = last ? nB : cB + (size_t)(t + 2) * kstepB;
;             const char* a3 = a2 + kstepA; const char* b3 = b2 + kstepB;
;             if (last && has_next) S.a_ready(nxt);
;             if constexpr (SP2) {
;             PG8_LDB(B0, 0, 0); PG8_LDB(B1, 0, 1); PG8_SCHED; PG8_LDA(At, 0, 0); PG8_STAGE(PG8_SA(1, 1), a1 + hstepA, voffA);
;             PG8_WAIT_V(8); PG8_WAIT_L(0); PG8_BAR; PG8_MMA(0, 0, At, B0); PG8_MMA(0, 1, At, B1); PG8_BAR; PG8_SCHED;
;             PG8_LDA(At, 0, 1); PG8_STAGE(PG8_SB(0, 0), b2, voffB); PG8_STAGE(PG8_SB(0, 1), b2 + hstepB, voffB); PG8_STAGE(PG8_SA(0, 0), a2, voffA);
;             PG8_WAIT_V(8); PG8_WAIT_L(0); PG8_BAR; PG8_MMA(1, 0, At, B0); PG8_MMA(1, 1, At, B1); PG8_BAR; PG8_SCHED;
;             PG8_LDB(B0, 1, 0); PG8_LDB(B1, 1, 1); PG8_SCHED; PG8_LDA(At, 1, 0); PG8_STAGE(PG8_SA(0, 1), a2 + hstepA, voffA);
;             PG8_WAIT_V(8); PG8_WAIT_L(0); PG8_BAR; PG8_MMA(0, 0, At, B0); PG8_MMA(0, 1, At, B1); PG8_BAR; PG8_SCHED;
;             PG8_LDA(At, 1, 1); PG8_STAGE(PG8_SB(1, 0), b3, voffB); PG8_STAGE(PG8_SB(1, 1), b3 + hstepB, voffB); PG8_STAGE(PG8_SA(1, 0), a3, voffA);
;             PG8_WAIT_V(8); PG8_WAIT_L(0); PG8_BAR; PG8_MMA(1, 0, At, B0); PG8_MMA(1, 1, At, B1); PG8_BAR; PG8_SCHED;
.LBB0_274:
	ds_read_b128 v[130:133], v197
	ds_read_b128 v[134:137], v197 offset:1024
	ds_read_b128 v[138:141], v197 offset:2048
	ds_read_b128 v[142:145], v197 offset:3072
	ds_read_b128 v[146:149], v240
	ds_read_b128 v[150:153], v240 offset:1024
	ds_read_b128 v[154:157], v240 offset:2048
	ds_read_b128 v[158:161], v240 offset:3072
	s_add_u32 s38, s36, 0x4000
	s_addc_u32 s39, s37, 0
	s_cmpk_eq_i32 s70, 0xa8
	s_cselect_b32 s42, s4, s38
	s_cselect_b32 s43, s5, s39
	s_cselect_b32 s40, s30, s33
	s_cselect_b32 s41, s31, s35
	s_add_u32 s38, s42, 0x8000
	s_addc_u32 s39, s43, 0
	s_add_i32 m0, s62, 0xc000
	ds_read_b128 v[162:165], v241
	ds_read_b128 v[166:169], v241 offset:1024
	ds_read_b128 v[170:173], v241 offset:2048
	ds_read_b128 v[174:177], v241 offset:3072
	ds_read_b128 v[178:181], v241 offset:4096
	ds_read_b128 v[182:185], v241 offset:5120
	ds_read_b128 v[186:189], v241 offset:6144
	ds_read_b128 v[222:225], v241 offset:7168
	global_load_lds_dwordx4 v214, s[36:37]
	s_add_i32 m0, s62, 0xe000
	s_nop 0
	global_load_lds_dwordx4 v216, s[36:37]
	s_waitcnt vmcnt(8)
	s_waitcnt lgkmcnt(0)
	s_setprio 1
	s_barrier
	v_mfma_f32_16x16x32_bf16 v[90:93], v[130:133], v[162:165], v[90:93]
	v_mfma_f32_16x16x32_bf16 v[90:93], v[134:137], v[166:169], v[90:93]
	v_mfma_f32_16x16x32_bf16 v[98:101], v[138:141], v[162:165], v[98:101]
	v_mfma_f32_16x16x32_bf16 v[98:101], v[142:145], v[166:169], v[98:101]
	v_mfma_f32_16x16x32_bf16 v[106:109], v[146:149], v[162:165], v[106:109]
	v_mfma_f32_16x16x32_bf16 v[106:109], v[150:153], v[166:169], v[106:109]
	v_mfma_f32_16x16x32_bf16 v[114:117], v[154:157], v[162:165], v[114:117]
	v_mfma_f32_16x16x32_bf16 v[114:117], v[158:161], v[166:169], v[114:117]
	v_mfma_f32_16x16x32_bf16 v[122:125], v[130:133], v[170:173], v[122:125]
	v_mfma_f32_16x16x32_bf16 v[122:125], v[134:137], v[174:177], v[122:125]
	v_mfma_f32_16x16x32_bf16 v[126:129], v[138:141], v[170:173], v[126:129]
	v_mfma_f32_16x16x32_bf16 v[126:129], v[142:145], v[174:177], v[126:129]
	v_mfma_f32_16x16x32_bf16 v[118:121], v[146:149], v[170:173], v[118:121]
	v_mfma_f32_16x16x32_bf16 v[118:121], v[150:153], v[174:177], v[118:121]
	v_mfma_f32_16x16x32_bf16 v[110:113], v[154:157], v[170:173], v[110:113]
	v_mfma_f32_16x16x32_bf16 v[110:113], v[158:161], v[174:177], v[110:113]
	v_mfma_f32_16x16x32_bf16 v[102:105], v[130:133], v[178:181], v[102:105]
	v_mfma_f32_16x16x32_bf16 v[102:105], v[134:137], v[182:185], v[102:105]
	v_mfma_f32_16x16x32_bf16 v[94:97], v[138:141], v[178:181], v[94:97]
	v_mfma_f32_16x16x32_bf16 v[94:97], v[142:145], v[182:185], v[94:97]
	v_mfma_f32_16x16x32_bf16 v[86:89], v[146:149], v[178:181], v[86:89]
	v_mfma_f32_16x16x32_bf16 v[86:89], v[150:153], v[182:185], v[86:89]
	v_mfma_f32_16x16x32_bf16 v[82:85], v[154:157], v[178:181], v[82:85]
	v_mfma_f32_16x16x32_bf16 v[82:85], v[158:161], v[182:185], v[82:85]
	v_mfma_f32_16x16x32_bf16 v[78:81], v[130:133], v[186:189], v[78:81]
	v_mfma_f32_16x16x32_bf16 v[78:81], v[134:137], v[222:225], v[78:81]
	v_mfma_f32_16x16x32_bf16 v[74:77], v[138:141], v[186:189], v[74:77]
	v_mfma_f32_16x16x32_bf16 v[74:77], v[142:145], v[222:225], v[74:77]
	v_mfma_f32_16x16x32_bf16 v[70:73], v[146:149], v[186:189], v[70:73]
	v_mfma_f32_16x16x32_bf16 v[70:73], v[150:153], v[222:225], v[70:73]
	v_mfma_f32_16x16x32_bf16 v[66:69], v[154:157], v[186:189], v[66:69]
	v_mfma_f32_16x16x32_bf16 v[66:69], v[158:161], v[222:225], v[66:69]
	s_barrier
	s_setprio 0
	s_add_i32 s72, s83, s59
	s_mov_b32 m0, s72
	ds_read_b128 v[162:165], v241 offset:16384
	ds_read_b128 v[166:169], v241 offset:17408
	ds_read_b128 v[170:173], v241 offset:18432
	ds_read_b128 v[174:177], v241 offset:19456
	ds_read_b128 v[178:181], v241 offset:20480
	ds_read_b128 v[182:185], v241 offset:21504
	ds_read_b128 v[186:189], v241 offset:22528
	ds_read_b128 v[222:225], v241 offset:23552
	global_load_lds_dwordx4 v190, s[40:41]
	s_add_i32 m0, s72, 0x2000
	s_add_u32 s72, s40, 0x4000
	s_addc_u32 s73, s41, 0
	s_add_i32 s74, s84, s59
	global_load_lds_dwordx4 v192, s[40:41]
	s_mov_b32 m0, s74
	s_nop 0
	global_load_lds_dwordx4 v190, s[72:73]
	s_add_i32 m0, s74, 0x2000
	s_nop 0
	global_load_lds_dwordx4 v192, s[72:73]
	s_mov_b32 m0, s62
	s_nop 0
	global_load_lds_dwordx4 v190, s[42:43]
	s_mov_b32 m0, s63
	s_nop 0
	global_load_lds_dwordx4 v192, s[42:43]
	s_waitcnt vmcnt(8)
	s_waitcnt lgkmcnt(0)
	s_setprio 1
	s_barrier
	v_mfma_f32_16x16x32_bf16 v[62:65], v[130:133], v[162:165], v[62:65]
	v_mfma_f32_16x16x32_bf16 v[62:65], v[134:137], v[166:169], v[62:65]
	v_mfma_f32_16x16x32_bf16 v[58:61], v[138:141], v[162:165], v[58:61]
	v_mfma_f32_16x16x32_bf16 v[58:61], v[142:145], v[166:169], v[58:61]
	v_mfma_f32_16x16x32_bf16 v[54:57], v[146:149], v[162:165], v[54:57]
	v_mfma_f32_16x16x32_bf16 v[54:57], v[150:153], v[166:169], v[54:57]
	v_mfma_f32_16x16x32_bf16 v[50:53], v[154:157], v[162:165], v[50:53]
	v_mfma_f32_16x16x32_bf16 v[50:53], v[158:161], v[166:169], v[50:53]
	v_mfma_f32_16x16x32_bf16 v[46:49], v[130:133], v[170:173], v[46:49]
	v_mfma_f32_16x16x32_bf16 v[46:49], v[134:137], v[174:177], v[46:49]
	v_mfma_f32_16x16x32_bf16 v[42:45], v[138:141], v[170:173], v[42:45]
	v_mfma_f32_16x16x32_bf16 v[42:45], v[142:145], v[174:177], v[42:45]
	v_mfma_f32_16x16x32_bf16 v[38:41], v[146:149], v[170:173], v[38:41]
	v_mfma_f32_16x16x32_bf16 v[38:41], v[150:153], v[174:177], v[38:41]
	v_mfma_f32_16x16x32_bf16 v[34:37], v[154:157], v[170:173], v[34:37]
	v_mfma_f32_16x16x32_bf16 v[34:37], v[158:161], v[174:177], v[34:37]
	v_mfma_f32_16x16x32_bf16 v[30:33], v[130:133], v[178:181], v[30:33]
	v_mfma_f32_16x16x32_bf16 v[30:33], v[134:137], v[182:185], v[30:33]
	v_mfma_f32_16x16x32_bf16 v[26:29], v[138:141], v[178:181], v[26:29]
	v_mfma_f32_16x16x32_bf16 v[26:29], v[142:145], v[182:185], v[26:29]
	v_mfma_f32_16x16x32_bf16 v[22:25], v[146:149], v[178:181], v[22:25]
	v_mfma_f32_16x16x32_bf16 v[22:25], v[150:153], v[182:185], v[22:25]
	v_mfma_f32_16x16x32_bf16 v[18:21], v[154:157], v[178:181], v[18:21]
	v_mfma_f32_16x16x32_bf16 v[18:21], v[158:161], v[182:185], v[18:21]
	v_mfma_f32_16x16x32_bf16 v[14:17], v[130:133], v[186:189], v[14:17]
	v_mfma_f32_16x16x32_bf16 v[14:17], v[134:137], v[222:225], v[14:17]
	v_mfma_f32_16x16x32_bf16 v[10:13], v[138:141], v[186:189], v[10:13]
	v_mfma_f32_16x16x32_bf16 v[10:13], v[142:145], v[222:225], v[10:13]
	v_mfma_f32_16x16x32_bf16 v[6:9], v[146:149], v[186:189], v[6:9]
	v_mfma_f32_16x16x32_bf16 v[6:9], v[150:153], v[222:225], v[6:9]
	v_mfma_f32_16x16x32_bf16 v[2:5], v[154:157], v[186:189], v[2:5]
	v_mfma_f32_16x16x32_bf16 v[2:5], v[158:161], v[222:225], v[2:5]
	s_barrier
; #define PG8_STAGE(bufoff, gbase, voff) do { _Pragma("unroll") for (int _i = 0; _i < 2; ++_i) \
;         __builtin_amdgcn_global_load_lds((const unsigned*)((const char*)(gbase) + (voff)[_i]), (PG8_LAS unsigned*)(lds + (bufoff) + ldsw + _i * 8192), 16, 0, 0); } while (0)
; #define PG8_LDA(dst, b, h) do { _Pragma("unroll") for (int m = 0; m < 4; ++m) _Pragma("unroll") for (int k = 0; k < 2; ++k) dst[m][k] = *(const PG8_LAS bf16x8*)(lds + PG8_SA(b, h) + aoff + m * 2048 + k * 1024); } while (0)
; #define PG8_WAIT_V(n) asm volatile("s_waitcnt vmcnt(" #n ")" ::: "memory")
; #define PG8_WAIT_L(n) asm volatile("s_waitcnt lgkmcnt(" #n ")" ::: "memory")
; #define PG8_BAR __builtin_amdgcn_s_barrier()
; template <class Epi, class Sched, bool ALIGN_EPI = false, bool SP2 = false, bool A_TILED = false>
; __device__ __forceinline__ void gemm_phase(PG8_LAS unsigned char* lds, const Gemm g, const Sched& S, const Epi& E) {
;     ...
;         for (int t = 0; t < nt; t += 2) {
;             const bool last = (t == nt - 2);
;             const char* a1 = cA + (size_t)(t + 1) * kstepA;
;             const char* a2 = last ? nA : cA + (size_t)(t + 2) * kstepA; const char* b2 = last ? nB : cB + (size_t)(t + 2) * kstepB;
;             const char* a3 = a2 + kstepA; const char* b3 = b2 + kstepB;
;             if (last && has_next) S.a_ready(nxt);
;             if constexpr (SP2) {
;             PG8_LDB(B0, 0, 0); PG8_LDB(B1, 0, 1); PG8_SCHED; PG8_LDA(At, 0, 0); PG8_STAGE(PG8_SA(1, 1), a1 + hstepA, voffA);
;             PG8_WAIT_V(8); PG8_WAIT_L(0); PG8_BAR; PG8_MMA(0, 0, At, B0); PG8_MMA(0, 1, At, B1); PG8_BAR; PG8_SCHED;
;             PG8_LDA(At, 0, 1); PG8_STAGE(PG8_SB(0, 0), b2, voffB); PG8_STAGE(PG8_SB(0, 1), b2 + hstepB, voffB); PG8_STAGE(PG8_SA(0, 0), a2, voffA);
;             PG8_WAIT_V(8); PG8_WAIT_L(0); PG8_BAR; PG8_MMA(1, 0, At, B0); PG8_MMA(1, 1, At, B1); PG8_BAR; PG8_SCHED;
;             PG8_LDB(B0, 1, 0); PG8_LDB(B1, 1, 1); PG8_SCHED; PG8_LDA(At, 1, 0); PG8_STAGE(PG8_SA(0, 1), a2 + hstepA, voffA);
;             PG8_WAIT_V(8); PG8_WAIT_L(0); PG8_BAR; PG8_MMA(0, 0, At, B0); PG8_MMA(0, 1, At, B1); PG8_BAR; PG8_SCHED;
;             PG8_LDA(At, 1, 1); PG8_STAGE(PG8_SB(1, 0), b3, voffB); PG8_STAGE(PG8_SB(1, 1), b3 + hstepB, voffB); PG8_STAGE(PG8_SA(1, 0), a3, voffA);
;             PG8_WAIT_V(8); PG8_WAIT_L(0); PG8_BAR; PG8_MMA(1, 0, At, B0); PG8_MMA(1, 1, At, B1); PG8_BAR; PG8_SCHED;
	s_setprio 0
	s_add_i32 s72, 0, 0x18000
	s_add_i32 s73, 0, 0x1c000
	v_add_u32_e32 v142, s72, v238
	v_add_u32_e32 v158, s73, v238
	ds_read_b128 v[130:133], v142
	ds_read_b128 v[134:137], v142 offset:1024
	ds_read_b128 v[138:141], v142 offset:2048
	ds_read_b128 v[142:145], v142 offset:3072
	ds_read_b128 v[146:149], v158
	ds_read_b128 v[150:153], v158 offset:1024
	ds_read_b128 v[154:157], v158 offset:2048
	ds_read_b128 v[158:161], v158 offset:3072
	s_add_u32 s42, s42, 0x4000
	s_addc_u32 s43, s43, 0
	s_mov_b32 m0, s69
	ds_read_b128 v[162:165], v241 offset:32768
	ds_read_b128 v[166:169], v241 offset:33792
	ds_read_b128 v[170:173], v241 offset:34816
	ds_read_b128 v[174:177], v241 offset:35840
	ds_read_b128 v[178:181], v241 offset:36864
	ds_read_b128 v[182:185], v241 offset:37888
	ds_read_b128 v[186:189], v241 offset:38912
	ds_read_b128 v[222:225], v241 offset:39936
	global_load_lds_dwordx4 v190, s[42:43]
	s_mov_b32 m0, s71
	s_nop 0
	global_load_lds_dwordx4 v192, s[42:43]
	s_waitcnt vmcnt(8)
	s_waitcnt lgkmcnt(0)
	s_setprio 1
	s_barrier
	v_mfma_f32_16x16x32_bf16 v[90:93], v[130:133], v[162:165], v[90:93]
	v_mfma_f32_16x16x32_bf16 v[90:93], v[134:137], v[166:169], v[90:93]
	v_mfma_f32_16x16x32_bf16 v[98:101], v[138:141], v[162:165], v[98:101]
	v_mfma_f32_16x16x32_bf16 v[98:101], v[142:145], v[166:169], v[98:101]
	v_mfma_f32_16x16x32_bf16 v[106:109], v[146:149], v[162:165], v[106:109]
	v_mfma_f32_16x16x32_bf16 v[106:109], v[150:153], v[166:169], v[106:109]
	v_mfma_f32_16x16x32_bf16 v[114:117], v[154:157], v[162:165], v[114:117]
	v_mfma_f32_16x16x32_bf16 v[114:117], v[158:161], v[166:169], v[114:117]
	v_mfma_f32_16x16x32_bf16 v[122:125], v[130:133], v[170:173], v[122:125]
	v_mfma_f32_16x16x32_bf16 v[122:125], v[134:137], v[174:177], v[122:125]
	v_mfma_f32_16x16x32_bf16 v[126:129], v[138:141], v[170:173], v[126:129]
	v_mfma_f32_16x16x32_bf16 v[126:129], v[142:145], v[174:177], v[126:129]
	v_mfma_f32_16x16x32_bf16 v[118:121], v[146:149], v[170:173], v[118:121]
	v_mfma_f32_16x16x32_bf16 v[118:121], v[150:153], v[174:177], v[118:121]
	v_mfma_f32_16x16x32_bf16 v[110:113], v[154:157], v[170:173], v[110:113]
	v_mfma_f32_16x16x32_bf16 v[110:113], v[158:161], v[174:177], v[110:113]
	v_mfma_f32_16x16x32_bf16 v[102:105], v[130:133], v[178:181], v[102:105]
	v_mfma_f32_16x16x32_bf16 v[102:105], v[134:137], v[182:185], v[102:105]
	v_mfma_f32_16x16x32_bf16 v[94:97], v[138:141], v[178:181], v[94:97]
	v_mfma_f32_16x16x32_bf16 v[94:97], v[142:145], v[182:185], v[94:97]
	v_mfma_f32_16x16x32_bf16 v[86:89], v[146:149], v[178:181], v[86:89]
	v_mfma_f32_16x16x32_bf16 v[86:89], v[150:153], v[182:185], v[86:89]
	v_mfma_f32_16x16x32_bf16 v[82:85], v[154:157], v[178:181], v[82:85]
	v_mfma_f32_16x16x32_bf16 v[82:85], v[158:161], v[182:185], v[82:85]
	v_mfma_f32_16x16x32_bf16 v[78:81], v[130:133], v[186:189], v[78:81]
	v_mfma_f32_16x16x32_bf16 v[78:81], v[134:137], v[222:225], v[78:81]
	v_mfma_f32_16x16x32_bf16 v[74:77], v[138:141], v[186:189], v[74:77]
	v_mfma_f32_16x16x32_bf16 v[74:77], v[142:145], v[222:225], v[74:77]
	v_mfma_f32_16x16x32_bf16 v[70:73], v[146:149], v[186:189], v[70:73]
	v_mfma_f32_16x16x32_bf16 v[70:73], v[150:153], v[222:225], v[70:73]
	v_mfma_f32_16x16x32_bf16 v[66:69], v[154:157], v[186:189], v[66:69]
	v_mfma_f32_16x16x32_bf16 v[66:69], v[158:161], v[222:225], v[66:69]
	s_barrier
	s_setprio 0
	s_add_u32 s42, s40, 0x8000
	s_addc_u32 s43, s41, 0
	s_add_i32 s72, s72, s59
	s_mov_b32 m0, s72
	ds_read_b128 v[162:165], v241 offset:49152
	ds_read_b128 v[166:169], v241 offset:50176
	ds_read_b128 v[170:173], v241 offset:51200
	ds_read_b128 v[174:177], v241 offset:52224
	ds_read_b128 v[178:181], v241 offset:53248
	ds_read_b128 v[182:185], v241 offset:54272
	ds_read_b128 v[186:189], v241 offset:55296
	ds_read_b128 v[222:225], v241 offset:56320
	global_load_lds_dwordx4 v190, s[42:43]
	s_add_i32 m0, s72, 0x2000
	s_add_u32 s40, s40, 0xc000
	v_lshl_add_u64 v[226:227], s[42:43], 0, v[192:193]
	s_addc_u32 s41, s41, 0
	s_add_i32 s42, s73, s59
	global_load_lds_dwordx4 v[226:227], off
	s_mov_b32 m0, s42
	s_nop 0
	global_load_lds_dwordx4 v190, s[40:41]
	s_add_i32 m0, s42, 0x2000
	s_nop 0
	global_load_lds_dwordx4 v192, s[40:41]
	s_mov_b32 m0, s80
	s_nop 0
	global_load_lds_dwordx4 v190, s[38:39]
	s_mov_b32 m0, s81
	s_nop 0
	global_load_lds_dwordx4 v192, s[38:39]
	s_waitcnt vmcnt(8)
	s_waitcnt lgkmcnt(0)
	s_setprio 1
	s_barrier
	v_mfma_f32_16x16x32_bf16 v[62:65], v[130:133], v[162:165], v[62:65]
	v_mfma_f32_16x16x32_bf16 v[62:65], v[134:137], v[166:169], v[62:65]
	v_mfma_f32_16x16x32_bf16 v[58:61], v[138:141], v[162:165], v[58:61]
	v_mfma_f32_16x16x32_bf16 v[58:61], v[142:145], v[166:169], v[58:61]
	v_mfma_f32_16x16x32_bf16 v[54:57], v[146:149], v[162:165], v[54:57]
	v_mfma_f32_16x16x32_bf16 v[54:57], v[150:153], v[166:169], v[54:57]
	v_mfma_f32_16x16x32_bf16 v[50:53], v[154:157], v[162:165], v[50:53]
	v_mfma_f32_16x16x32_bf16 v[50:53], v[158:161], v[166:169], v[50:53]
	v_mfma_f32_16x16x32_bf16 v[46:49], v[130:133], v[170:173], v[46:49]
	v_mfma_f32_16x16x32_bf16 v[46:49], v[134:137], v[174:177], v[46:49]
	v_mfma_f32_16x16x32_bf16 v[42:45], v[138:141], v[170:173], v[42:45]
	v_mfma_f32_16x16x32_bf16 v[42:45], v[142:145], v[174:177], v[42:45]
	v_mfma_f32_16x16x32_bf16 v[38:41], v[146:149], v[170:173], v[38:41]
	v_mfma_f32_16x16x32_bf16 v[38:41], v[150:153], v[174:177], v[38:41]
	v_mfma_f32_16x16x32_bf16 v[34:37], v[154:157], v[170:173], v[34:37]
	v_mfma_f32_16x16x32_bf16 v[34:37], v[158:161], v[174:177], v[34:37]
	v_mfma_f32_16x16x32_bf16 v[30:33], v[130:133], v[178:181], v[30:33]
	v_mfma_f32_16x16x32_bf16 v[30:33], v[134:137], v[182:185], v[30:33]
	v_mfma_f32_16x16x32_bf16 v[26:29], v[138:141], v[178:181], v[26:29]
	v_mfma_f32_16x16x32_bf16 v[26:29], v[142:145], v[182:185], v[26:29]
	v_mfma_f32_16x16x32_bf16 v[22:25], v[146:149], v[178:181], v[22:25]
	v_mfma_f32_16x16x32_bf16 v[22:25], v[150:153], v[182:185], v[22:25]
	v_mfma_f32_16x16x32_bf16 v[18:21], v[154:157], v[178:181], v[18:21]
	v_mfma_f32_16x16x32_bf16 v[18:21], v[158:161], v[182:185], v[18:21]
	v_mfma_f32_16x16x32_bf16 v[14:17], v[130:133], v[186:189], v[14:17]
	v_mfma_f32_16x16x32_bf16 v[14:17], v[134:137], v[222:225], v[14:17]
	v_mfma_f32_16x16x32_bf16 v[10:13], v[138:141], v[186:189], v[10:13]
	v_mfma_f32_16x16x32_bf16 v[10:13], v[142:145], v[222:225], v[10:13]
	v_mfma_f32_16x16x32_bf16 v[6:9], v[146:149], v[186:189], v[6:9]
	v_mfma_f32_16x16x32_bf16 v[6:9], v[150:153], v[222:225], v[6:9]
	v_mfma_f32_16x16x32_bf16 v[2:5], v[154:157], v[186:189], v[2:5]
	v_mfma_f32_16x16x32_bf16 v[2:5], v[158:161], v[222:225], v[2:5]
	s_barrier
	s_setprio 0
	s_add_i32 s70, s70, 2
	s_add_u32 s36, s36, 0x10000
	s_addc_u32 s37, s37, 0
	s_add_u32 s33, s33, 0x10000
	s_addc_u32 s35, s35, 0
	s_cmpk_gt_u32 s70, 0xa9
	s_cbranch_scc0 .LBB0_274
	s_and_b64 vcc, exec, s[16:17]
	s_cbranch_vccz .LBB0_277
	s_barrier

; #define PG8_STAGE(bufoff, gbase, voff) do { _Pragma("unroll") for (int _i = 0; _i < 2; ++_i) \
;         __builtin_amdgcn_global_load_lds((const unsigned*)((const char*)(gbase) + (voff)[_i]), (PG8_LAS unsigned*)(lds + (bufoff) + ldsw + _i * 8192), 16, 0, 0); } while (0)
; #define PG8_LDA(dst, b, h) do { _Pragma("unroll") for (int m = 0; m < 4; ++m) _Pragma("unroll") for (int k = 0; k < 2; ++k) dst[m][k] = *(const PG8_LAS bf16x8*)(lds + PG8_SA(b, h) + aoff + m * 2048 + k * 1024); } while (0)
; #define PG8_WAIT_V(n) asm volatile("s_waitcnt vmcnt(" #n ")" ::: "memory")
; #define PG8_WAIT_L(n) asm volatile("s_waitcnt lgkmcnt(" #n ")" ::: "memory")
; #define PG8_BAR __builtin_amdgcn_s_barrier()
; template <class Epi, class Sched, bool ALIGN_EPI = false, bool SP2 = false, bool A_TILED = false>
; __device__ __forceinline__ void gemm_phase(PG8_LAS unsigned char* lds, const Gemm g, const Sched& S, const Epi& E) {
;     ...
;         for (int t = 0; t < nt; t += 2) {
;             const bool last = (t == nt - 2);
;             const char* a1 = cA + (size_t)(t + 1) * kstepA;
;             const char* a2 = last ? nA : cA + (size_t)(t + 2) * kstepA; const char* b2 = last ? nB : cB + (size_t)(t + 2) * kstepB;
;             const char* a3 = a2 + kstepA; const char* b3 = b2 + kstepB;
;             if (last && has_next) S.a_ready(nxt);
;             if constexpr (SP2) {
;             PG8_LDB(B0, 0, 0); PG8_LDB(B1, 0, 1); PG8_SCHED; PG8_LDA(At, 0, 0); PG8_STAGE(PG8_SA(1, 1), a1 + hstepA, voffA);
;             PG8_WAIT_V(8); PG8_WAIT_L(0); PG8_BAR; PG8_MMA(0, 0, At, B0); PG8_MMA(0, 1, At, B1); PG8_BAR; PG8_SCHED;
;             PG8_LDA(At, 0, 1); PG8_STAGE(PG8_SB(0, 0), b2, voffB); PG8_STAGE(PG8_SB(0, 1), b2 + hstepB, voffB); PG8_STAGE(PG8_SA(0, 0), a2, voffA);
;             PG8_WAIT_V(8); PG8_WAIT_L(0); PG8_BAR; PG8_MMA(1, 0, At, B0); PG8_MMA(1, 1, At, B1); PG8_BAR; PG8_SCHED;
;             PG8_LDB(B0, 1, 0); PG8_LDB(B1, 1, 1); PG8_SCHED; PG8_LDA(At, 1, 0); PG8_STAGE(PG8_SA(0, 1), a2 + hstepA, voffA);
;             PG8_WAIT_V(8); PG8_WAIT_L(0); PG8_BAR; PG8_MMA(0, 0, At, B0); PG8_MMA(0, 1, At, B1); PG8_BAR; PG8_SCHED;
;             PG8_LDA(At, 1, 1); PG8_STAGE(PG8_SB(1, 0), b3, voffB); PG8_STAGE(PG8_SB(1, 1), b3 + hstepB, voffB); PG8_STAGE(PG8_SA(1, 0), a3, voffA);
;             PG8_WAIT_V(8); PG8_WAIT_L(0); PG8_BAR; PG8_MMA(1, 0, At, B0); PG8_MMA(1, 1, At, B1); PG8_BAR; PG8_SCHED;
.LBB0_356:
	ds_read_b128 v[156:159], v170
	ds_read_b128 v[160:163], v170 offset:1024
	ds_read_b128 v[164:167], v170 offset:2048
	ds_read_b128 v[176:179], v170 offset:3072
	ds_read_b128 v[180:183], v171
	ds_read_b128 v[184:187], v171 offset:1024
	ds_read_b128 v[188:191], v171 offset:2048
	ds_read_b128 v[192:195], v171 offset:3072
	s_add_u32 s10, s8, 0x4000
	s_addc_u32 s11, s9, 0
	s_cmp_eq_u32 s58, 60
	s_cselect_b32 s44, s5, s10
	s_cselect_b32 s45, s3, s11
	s_cselect_b32 s12, s33, s37
	s_cselect_b32 s13, s7, s39
	s_add_u32 s10, s44, 0x8000
	s_addc_u32 s11, s45, 0
	s_add_i32 m0, s77, 0xc000
	ds_read_b128 v[196:199], v172
	ds_read_b128 v[200:203], v172 offset:1024
	ds_read_b128 v[204:207], v172 offset:2048
	ds_read_b128 v[208:211], v172 offset:3072
	ds_read_b128 v[212:215], v172 offset:4096
	ds_read_b128 v[216:219], v172 offset:5120
	ds_read_b128 v[220:223], v172 offset:6144
	ds_read_b128 v[224:227], v172 offset:7168
	global_load_lds_dwordx4 v148, s[8:9]
	s_add_i32 m0, s77, 0xe000
	s_nop 0
	global_load_lds_dwordx4 v150, s[8:9]
	s_waitcnt vmcnt(8)
	s_waitcnt lgkmcnt(0)
	s_setprio 1
	s_barrier
	v_mfma_f32_16x16x32_bf16 v[126:129], v[156:159], v[196:199], v[126:129]
	v_mfma_f32_16x16x32_bf16 v[126:129], v[160:163], v[200:203], v[126:129]
	v_mfma_f32_16x16x32_bf16 v[122:125], v[164:167], v[196:199], v[122:125]
	v_mfma_f32_16x16x32_bf16 v[122:125], v[176:179], v[200:203], v[122:125]
	v_mfma_f32_16x16x32_bf16 v[118:121], v[180:183], v[196:199], v[118:121]
	v_mfma_f32_16x16x32_bf16 v[118:121], v[184:187], v[200:203], v[118:121]
	v_mfma_f32_16x16x32_bf16 v[114:117], v[188:191], v[196:199], v[114:117]
	v_mfma_f32_16x16x32_bf16 v[114:117], v[192:195], v[200:203], v[114:117]
	v_mfma_f32_16x16x32_bf16 v[110:113], v[156:159], v[204:207], v[110:113]
	v_mfma_f32_16x16x32_bf16 v[110:113], v[160:163], v[208:211], v[110:113]
	v_mfma_f32_16x16x32_bf16 v[106:109], v[164:167], v[204:207], v[106:109]
	v_mfma_f32_16x16x32_bf16 v[106:109], v[176:179], v[208:211], v[106:109]
	v_mfma_f32_16x16x32_bf16 v[102:105], v[180:183], v[204:207], v[102:105]
	v_mfma_f32_16x16x32_bf16 v[102:105], v[184:187], v[208:211], v[102:105]
	v_mfma_f32_16x16x32_bf16 v[98:101], v[188:191], v[204:207], v[98:101]
	v_mfma_f32_16x16x32_bf16 v[98:101], v[192:195], v[208:211], v[98:101]
	v_mfma_f32_16x16x32_bf16 v[94:97], v[156:159], v[212:215], v[94:97]
	v_mfma_f32_16x16x32_bf16 v[94:97], v[160:163], v[216:219], v[94:97]
	v_mfma_f32_16x16x32_bf16 v[90:93], v[164:167], v[212:215], v[90:93]
	v_mfma_f32_16x16x32_bf16 v[90:93], v[176:179], v[216:219], v[90:93]
	v_mfma_f32_16x16x32_bf16 v[86:89], v[180:183], v[212:215], v[86:89]
	v_mfma_f32_16x16x32_bf16 v[86:89], v[184:187], v[216:219], v[86:89]
	v_mfma_f32_16x16x32_bf16 v[82:85], v[188:191], v[212:215], v[82:85]
	v_mfma_f32_16x16x32_bf16 v[82:85], v[192:195], v[216:219], v[82:85]
	v_mfma_f32_16x16x32_bf16 v[78:81], v[156:159], v[220:223], v[78:81]
	v_mfma_f32_16x16x32_bf16 v[78:81], v[160:163], v[224:227], v[78:81]
	v_mfma_f32_16x16x32_bf16 v[74:77], v[164:167], v[220:223], v[74:77]
	v_mfma_f32_16x16x32_bf16 v[74:77], v[176:179], v[224:227], v[74:77]
	v_mfma_f32_16x16x32_bf16 v[70:73], v[180:183], v[220:223], v[70:73]
	v_mfma_f32_16x16x32_bf16 v[70:73], v[184:187], v[224:227], v[70:73]
	v_mfma_f32_16x16x32_bf16 v[66:69], v[188:191], v[220:223], v[66:69]
	v_mfma_f32_16x16x32_bf16 v[66:69], v[192:195], v[224:227], v[66:69]
	s_barrier
	s_setprio 0
	s_add_i32 s59, s92, s69
	s_mov_b32 m0, s59
	ds_read_b128 v[196:199], v172 offset:16384
	ds_read_b128 v[200:203], v172 offset:17408
	ds_read_b128 v[204:207], v172 offset:18432
	ds_read_b128 v[208:211], v172 offset:19456
	ds_read_b128 v[212:215], v172 offset:20480
	ds_read_b128 v[216:219], v172 offset:21504
	ds_read_b128 v[220:223], v172 offset:22528
	ds_read_b128 v[224:227], v172 offset:23552
	global_load_lds_dwordx4 v134, s[12:13]
	s_add_i32 m0, s59, 0x2000
	s_add_u32 s62, s12, 0x4000
	s_addc_u32 s63, s13, 0
	s_add_i32 s59, s93, s69
	global_load_lds_dwordx4 v138, s[12:13]
	s_mov_b32 m0, s59
	s_nop 0
	global_load_lds_dwordx4 v134, s[62:63]
	s_add_i32 m0, s59, 0x2000
	s_nop 0
	global_load_lds_dwordx4 v138, s[62:63]
	s_mov_b32 m0, s77
	s_nop 0
	global_load_lds_dwordx4 v132, s[44:45]
	s_mov_b32 m0, s84
	s_nop 0
	global_load_lds_dwordx4 v136, s[44:45]
	s_waitcnt vmcnt(8)
	s_waitcnt lgkmcnt(0)
	s_setprio 1
	s_barrier
	v_mfma_f32_16x16x32_bf16 v[62:65], v[156:159], v[196:199], v[62:65]
	v_mfma_f32_16x16x32_bf16 v[62:65], v[160:163], v[200:203], v[62:65]
	v_mfma_f32_16x16x32_bf16 v[58:61], v[164:167], v[196:199], v[58:61]
	v_mfma_f32_16x16x32_bf16 v[58:61], v[176:179], v[200:203], v[58:61]
	v_mfma_f32_16x16x32_bf16 v[54:57], v[180:183], v[196:199], v[54:57]
	v_mfma_f32_16x16x32_bf16 v[54:57], v[184:187], v[200:203], v[54:57]
	v_mfma_f32_16x16x32_bf16 v[50:53], v[188:191], v[196:199], v[50:53]
	v_mfma_f32_16x16x32_bf16 v[50:53], v[192:195], v[200:203], v[50:53]
	v_mfma_f32_16x16x32_bf16 v[46:49], v[156:159], v[204:207], v[46:49]
	v_mfma_f32_16x16x32_bf16 v[46:49], v[160:163], v[208:211], v[46:49]
	v_mfma_f32_16x16x32_bf16 v[42:45], v[164:167], v[204:207], v[42:45]
	v_mfma_f32_16x16x32_bf16 v[42:45], v[176:179], v[208:211], v[42:45]
	v_mfma_f32_16x16x32_bf16 v[38:41], v[180:183], v[204:207], v[38:41]
	v_mfma_f32_16x16x32_bf16 v[38:41], v[184:187], v[208:211], v[38:41]
	v_mfma_f32_16x16x32_bf16 v[34:37], v[188:191], v[204:207], v[34:37]
	v_mfma_f32_16x16x32_bf16 v[34:37], v[192:195], v[208:211], v[34:37]
	v_mfma_f32_16x16x32_bf16 v[30:33], v[156:159], v[212:215], v[30:33]
	v_mfma_f32_16x16x32_bf16 v[30:33], v[160:163], v[216:219], v[30:33]
	v_mfma_f32_16x16x32_bf16 v[26:29], v[164:167], v[212:215], v[26:29]
	v_mfma_f32_16x16x32_bf16 v[26:29], v[176:179], v[216:219], v[26:29]
	v_mfma_f32_16x16x32_bf16 v[22:25], v[180:183], v[212:215], v[22:25]
	v_mfma_f32_16x16x32_bf16 v[22:25], v[184:187], v[216:219], v[22:25]
	v_mfma_f32_16x16x32_bf16 v[18:21], v[188:191], v[212:215], v[18:21]
	v_mfma_f32_16x16x32_bf16 v[18:21], v[192:195], v[216:219], v[18:21]
	v_mfma_f32_16x16x32_bf16 v[14:17], v[156:159], v[220:223], v[14:17]
	v_mfma_f32_16x16x32_bf16 v[14:17], v[160:163], v[224:227], v[14:17]
	v_mfma_f32_16x16x32_bf16 v[10:13], v[164:167], v[220:223], v[10:13]
	v_mfma_f32_16x16x32_bf16 v[10:13], v[176:179], v[224:227], v[10:13]
	v_mfma_f32_16x16x32_bf16 v[6:9], v[180:183], v[220:223], v[6:9]
	v_mfma_f32_16x16x32_bf16 v[6:9], v[184:187], v[224:227], v[6:9]
	v_mfma_f32_16x16x32_bf16 v[2:5], v[188:191], v[220:223], v[2:5]
	v_mfma_f32_16x16x32_bf16 v[2:5], v[192:195], v[224:227], v[2:5]
	s_barrier
; #define PG8_STAGE(bufoff, gbase, voff) do { _Pragma("unroll") for (int _i = 0; _i < 2; ++_i) \
;         __builtin_amdgcn_global_load_lds((const unsigned*)((const char*)(gbase) + (voff)[_i]), (PG8_LAS unsigned*)(lds + (bufoff) + ldsw + _i * 8192), 16, 0, 0); } while (0)
; #define PG8_LDA(dst, b, h) do { _Pragma("unroll") for (int m = 0; m < 4; ++m) _Pragma("unroll") for (int k = 0; k < 2; ++k) dst[m][k] = *(const PG8_LAS bf16x8*)(lds + PG8_SA(b, h) + aoff + m * 2048 + k * 1024); } while (0)
; #define PG8_WAIT_V(n) asm volatile("s_waitcnt vmcnt(" #n ")" ::: "memory")
; #define PG8_WAIT_L(n) asm volatile("s_waitcnt lgkmcnt(" #n ")" ::: "memory")
; #define PG8_BAR __builtin_amdgcn_s_barrier()
; template <class Epi, class Sched, bool ALIGN_EPI = false, bool SP2 = false, bool A_TILED = false>
; __device__ __forceinline__ void gemm_phase(PG8_LAS unsigned char* lds, const Gemm g, const Sched& S, const Epi& E) {
;     ...
;         for (int t = 0; t < nt; t += 2) {
;             const bool last = (t == nt - 2);
;             const char* a1 = cA + (size_t)(t + 1) * kstepA;
;             const char* a2 = last ? nA : cA + (size_t)(t + 2) * kstepA; const char* b2 = last ? nB : cB + (size_t)(t + 2) * kstepB;
;             const char* a3 = a2 + kstepA; const char* b3 = b2 + kstepB;
;             if (last && has_next) S.a_ready(nxt);
;             if constexpr (SP2) {
;             PG8_LDB(B0, 0, 0); PG8_LDB(B1, 0, 1); PG8_SCHED; PG8_LDA(At, 0, 0); PG8_STAGE(PG8_SA(1, 1), a1 + hstepA, voffA);
;             PG8_WAIT_V(8); PG8_WAIT_L(0); PG8_BAR; PG8_MMA(0, 0, At, B0); PG8_MMA(0, 1, At, B1); PG8_BAR; PG8_SCHED;
;             PG8_LDA(At, 0, 1); PG8_STAGE(PG8_SB(0, 0), b2, voffB); PG8_STAGE(PG8_SB(0, 1), b2 + hstepB, voffB); PG8_STAGE(PG8_SA(0, 0), a2, voffA);
;             PG8_WAIT_V(8); PG8_WAIT_L(0); PG8_BAR; PG8_MMA(1, 0, At, B0); PG8_MMA(1, 1, At, B1); PG8_BAR; PG8_SCHED;
;             PG8_LDB(B0, 1, 0); PG8_LDB(B1, 1, 1); PG8_SCHED; PG8_LDA(At, 1, 0); PG8_STAGE(PG8_SA(0, 1), a2 + hstepA, voffA);
;             PG8_WAIT_V(8); PG8_WAIT_L(0); PG8_BAR; PG8_MMA(0, 0, At, B0); PG8_MMA(0, 1, At, B1); PG8_BAR; PG8_SCHED;
;             PG8_LDA(At, 1, 1); PG8_STAGE(PG8_SB(1, 0), b3, voffB); PG8_STAGE(PG8_SB(1, 1), b3 + hstepB, voffB); PG8_STAGE(PG8_SA(1, 0), a3, voffA);
;             PG8_WAIT_V(8); PG8_WAIT_L(0); PG8_BAR; PG8_MMA(1, 0, At, B0); PG8_MMA(1, 1, At, B1); PG8_BAR; PG8_SCHED;
	s_setprio 0
	s_add_i32 s59, 0, 0x18000
	v_add_u32_e32 v130, s59, v143
	s_add_i32 s62, 0, 0x1c000
	ds_read_b128 v[156:159], v130
	ds_read_b128 v[160:163], v130 offset:1024
	ds_read_b128 v[164:167], v130 offset:2048
	ds_read_b128 v[176:179], v130 offset:3072
	v_add_u32_e32 v130, s62, v143
	ds_read_b128 v[180:183], v130
	ds_read_b128 v[184:187], v130 offset:1024
	ds_read_b128 v[188:191], v130 offset:2048
	ds_read_b128 v[192:195], v130 offset:3072
	s_add_u32 s44, s44, 0x4000
	s_addc_u32 s45, s45, 0
	s_mov_b32 m0, s85
	ds_read_b128 v[196:199], v172 offset:32768
	ds_read_b128 v[200:203], v172 offset:33792
	ds_read_b128 v[204:207], v172 offset:34816
	ds_read_b128 v[208:211], v172 offset:35840
	ds_read_b128 v[212:215], v172 offset:36864
	ds_read_b128 v[216:219], v172 offset:37888
	ds_read_b128 v[220:223], v172 offset:38912
	ds_read_b128 v[224:227], v172 offset:39936
	global_load_lds_dwordx4 v132, s[44:45]
	s_mov_b32 m0, s86
	s_nop 0
	global_load_lds_dwordx4 v136, s[44:45]
	s_waitcnt vmcnt(8)
	s_waitcnt lgkmcnt(0)
	s_setprio 1
	s_barrier
	v_mfma_f32_16x16x32_bf16 v[126:129], v[156:159], v[196:199], v[126:129]
	v_mfma_f32_16x16x32_bf16 v[126:129], v[160:163], v[200:203], v[126:129]
	v_mfma_f32_16x16x32_bf16 v[122:125], v[164:167], v[196:199], v[122:125]
	v_mfma_f32_16x16x32_bf16 v[122:125], v[176:179], v[200:203], v[122:125]
	v_mfma_f32_16x16x32_bf16 v[118:121], v[180:183], v[196:199], v[118:121]
	v_mfma_f32_16x16x32_bf16 v[118:121], v[184:187], v[200:203], v[118:121]
	v_mfma_f32_16x16x32_bf16 v[114:117], v[188:191], v[196:199], v[114:117]
	v_mfma_f32_16x16x32_bf16 v[114:117], v[192:195], v[200:203], v[114:117]
	v_mfma_f32_16x16x32_bf16 v[110:113], v[156:159], v[204:207], v[110:113]
	v_mfma_f32_16x16x32_bf16 v[110:113], v[160:163], v[208:211], v[110:113]
	v_mfma_f32_16x16x32_bf16 v[106:109], v[164:167], v[204:207], v[106:109]
	v_mfma_f32_16x16x32_bf16 v[106:109], v[176:179], v[208:211], v[106:109]
	v_mfma_f32_16x16x32_bf16 v[102:105], v[180:183], v[204:207], v[102:105]
	v_mfma_f32_16x16x32_bf16 v[102:105], v[184:187], v[208:211], v[102:105]
	v_mfma_f32_16x16x32_bf16 v[98:101], v[188:191], v[204:207], v[98:101]
	v_mfma_f32_16x16x32_bf16 v[98:101], v[192:195], v[208:211], v[98:101]
	v_mfma_f32_16x16x32_bf16 v[94:97], v[156:159], v[212:215], v[94:97]
	v_mfma_f32_16x16x32_bf16 v[94:97], v[160:163], v[216:219], v[94:97]
	v_mfma_f32_16x16x32_bf16 v[90:93], v[164:167], v[212:215], v[90:93]
	v_mfma_f32_16x16x32_bf16 v[90:93], v[176:179], v[216:219], v[90:93]
	v_mfma_f32_16x16x32_bf16 v[86:89], v[180:183], v[212:215], v[86:89]
	v_mfma_f32_16x16x32_bf16 v[86:89], v[184:187], v[216:219], v[86:89]
	v_mfma_f32_16x16x32_bf16 v[82:85], v[188:191], v[212:215], v[82:85]
	v_mfma_f32_16x16x32_bf16 v[82:85], v[192:195], v[216:219], v[82:85]
	v_mfma_f32_16x16x32_bf16 v[78:81], v[156:159], v[220:223], v[78:81]
	v_mfma_f32_16x16x32_bf16 v[78:81], v[160:163], v[224:227], v[78:81]
	v_mfma_f32_16x16x32_bf16 v[74:77], v[164:167], v[220:223], v[74:77]
	v_mfma_f32_16x16x32_bf16 v[74:77], v[176:179], v[224:227], v[74:77]
	v_mfma_f32_16x16x32_bf16 v[70:73], v[180:183], v[220:223], v[70:73]
	v_mfma_f32_16x16x32_bf16 v[70:73], v[184:187], v[224:227], v[70:73]
	v_mfma_f32_16x16x32_bf16 v[66:69], v[188:191], v[220:223], v[66:69]
	v_mfma_f32_16x16x32_bf16 v[66:69], v[192:195], v[224:227], v[66:69]
	s_barrier
	s_setprio 0
	s_add_u32 s44, s12, 0x8000
	s_addc_u32 s45, s13, 0
	s_add_i32 s59, s59, s69
	s_mov_b32 m0, s59
	ds_read_b128 v[196:199], v172 offset:49152
	ds_read_b128 v[200:203], v172 offset:50176
	ds_read_b128 v[204:207], v172 offset:51200
	ds_read_b128 v[208:211], v172 offset:52224
	ds_read_b128 v[212:215], v172 offset:53248
	ds_read_b128 v[216:219], v172 offset:54272
	ds_read_b128 v[220:223], v172 offset:55296
	ds_read_b128 v[224:227], v172 offset:56320
	global_load_lds_dwordx4 v134, s[44:45]
	s_add_i32 m0, s59, 0x2000
	s_add_u32 s12, s12, 0xc000
	v_lshl_add_u64 v[130:131], s[44:45], 0, v[138:139]
	s_addc_u32 s13, s13, 0
	s_add_i32 s44, s62, s69
	global_load_lds_dwordx4 v[130:131], off
	s_mov_b32 m0, s44
	s_nop 0
	global_load_lds_dwordx4 v134, s[12:13]
	s_add_i32 m0, s44, 0x2000
	s_nop 0
	global_load_lds_dwordx4 v138, s[12:13]
	s_mov_b32 m0, s90
	s_nop 0
	global_load_lds_dwordx4 v132, s[10:11]
	s_mov_b32 m0, s91
	s_nop 0
	global_load_lds_dwordx4 v136, s[10:11]
	s_waitcnt vmcnt(8)
	s_waitcnt lgkmcnt(0)
	s_setprio 1
	s_barrier
	v_mfma_f32_16x16x32_bf16 v[62:65], v[156:159], v[196:199], v[62:65]
	v_mfma_f32_16x16x32_bf16 v[62:65], v[160:163], v[200:203], v[62:65]
	v_mfma_f32_16x16x32_bf16 v[58:61], v[164:167], v[196:199], v[58:61]
	v_mfma_f32_16x16x32_bf16 v[58:61], v[176:179], v[200:203], v[58:61]
	v_mfma_f32_16x16x32_bf16 v[54:57], v[180:183], v[196:199], v[54:57]
	v_mfma_f32_16x16x32_bf16 v[54:57], v[184:187], v[200:203], v[54:57]
	v_mfma_f32_16x16x32_bf16 v[50:53], v[188:191], v[196:199], v[50:53]
	v_mfma_f32_16x16x32_bf16 v[50:53], v[192:195], v[200:203], v[50:53]
	v_mfma_f32_16x16x32_bf16 v[46:49], v[156:159], v[204:207], v[46:49]
	v_mfma_f32_16x16x32_bf16 v[46:49], v[160:163], v[208:211], v[46:49]
	v_mfma_f32_16x16x32_bf16 v[42:45], v[164:167], v[204:207], v[42:45]
	v_mfma_f32_16x16x32_bf16 v[42:45], v[176:179], v[208:211], v[42:45]
	v_mfma_f32_16x16x32_bf16 v[38:41], v[180:183], v[204:207], v[38:41]
	v_mfma_f32_16x16x32_bf16 v[38:41], v[184:187], v[208:211], v[38:41]
	v_mfma_f32_16x16x32_bf16 v[34:37], v[188:191], v[204:207], v[34:37]
	v_mfma_f32_16x16x32_bf16 v[34:37], v[192:195], v[208:211], v[34:37]
	v_mfma_f32_16x16x32_bf16 v[30:33], v[156:159], v[212:215], v[30:33]
	v_mfma_f32_16x16x32_bf16 v[30:33], v[160:163], v[216:219], v[30:33]
	v_mfma_f32_16x16x32_bf16 v[26:29], v[164:167], v[212:215], v[26:29]
	v_mfma_f32_16x16x32_bf16 v[26:29], v[176:179], v[216:219], v[26:29]
	v_mfma_f32_16x16x32_bf16 v[22:25], v[180:183], v[212:215], v[22:25]
	v_mfma_f32_16x16x32_bf16 v[22:25], v[184:187], v[216:219], v[22:25]
	v_mfma_f32_16x16x32_bf16 v[18:21], v[188:191], v[212:215], v[18:21]
	v_mfma_f32_16x16x32_bf16 v[18:21], v[192:195], v[216:219], v[18:21]
	v_mfma_f32_16x16x32_bf16 v[14:17], v[156:159], v[220:223], v[14:17]
	v_mfma_f32_16x16x32_bf16 v[14:17], v[160:163], v[224:227], v[14:17]
	v_mfma_f32_16x16x32_bf16 v[10:13], v[164:167], v[220:223], v[10:13]
	v_mfma_f32_16x16x32_bf16 v[10:13], v[176:179], v[224:227], v[10:13]
	v_mfma_f32_16x16x32_bf16 v[6:9], v[180:183], v[220:223], v[6:9]
	v_mfma_f32_16x16x32_bf16 v[6:9], v[184:187], v[224:227], v[6:9]
	v_mfma_f32_16x16x32_bf16 v[2:5], v[188:191], v[220:223], v[2:5]
	v_mfma_f32_16x16x32_bf16 v[2:5], v[192:195], v[224:227], v[2:5]
	s_barrier
	s_setprio 0
	s_add_i32 s58, s58, 2
	s_add_u32 s8, s8, 0x10000
	s_addc_u32 s9, s9, 0
	s_add_u32 s37, s37, 0x10000
	s_addc_u32 s39, s39, 0
	s_cmp_gt_u32 s58, 61
	s_cbranch_scc0 .LBB0_356
	s_and_b64 vcc, exec, s[30:31]
	s_cbranch_vccz .LBB0_359
	s_barrier

; #define PG8_STAGE(bufoff, gbase, voff) do { _Pragma("unroll") for (int _i = 0; _i < 2; ++_i) \
;         __builtin_amdgcn_global_load_lds((const unsigned*)((const char*)(gbase) + (voff)[_i]), (PG8_LAS unsigned*)(lds + (bufoff) + ldsw + _i * 8192), 16, 0, 0); } while (0)
; #define PG8_LDA(dst, b, h) do { _Pragma("unroll") for (int m = 0; m < 4; ++m) _Pragma("unroll") for (int k = 0; k < 2; ++k) dst[m][k] = *(const PG8_LAS bf16x8*)(lds + PG8_SA(b, h) + aoff + m * 2048 + k * 1024); } while (0)
; #define PG8_WAIT_V(n) asm volatile("s_waitcnt vmcnt(" #n ")" ::: "memory")
; #define PG8_WAIT_L(n) asm volatile("s_waitcnt lgkmcnt(" #n ")" ::: "memory")
; #define PG8_BAR __builtin_amdgcn_s_barrier()
; template <class Epi, class Sched, bool ALIGN_EPI = false, bool SP2 = false, bool A_TILED = false>
; __device__ __forceinline__ void gemm_phase(PG8_LAS unsigned char* lds, const Gemm g, const Sched& S, const Epi& E) {
;     ...
;         for (int t = 0; t < nt; t += 2) {
;             const bool last = (t == nt - 2);
;             const char* a1 = cA + (size_t)(t + 1) * kstepA;
;             const char* a2 = last ? nA : cA + (size_t)(t + 2) * kstepA; const char* b2 = last ? nB : cB + (size_t)(t + 2) * kstepB;
;             const char* a3 = a2 + kstepA; const char* b3 = b2 + kstepB;
;             if (last && has_next) S.a_ready(nxt);
;             if constexpr (SP2) {
;             PG8_LDB(B0, 0, 0); PG8_LDB(B1, 0, 1); PG8_SCHED; PG8_LDA(At, 0, 0); PG8_STAGE(PG8_SA(1, 1), a1 + hstepA, voffA);
;             PG8_WAIT_V(8); PG8_WAIT_L(0); PG8_BAR; PG8_MMA(0, 0, At, B0); PG8_MMA(0, 1, At, B1); PG8_BAR; PG8_SCHED;
;             PG8_LDA(At, 0, 1); PG8_STAGE(PG8_SB(0, 0), b2, voffB); PG8_STAGE(PG8_SB(0, 1), b2 + hstepB, voffB); PG8_STAGE(PG8_SA(0, 0), a2, voffA);
;             PG8_WAIT_V(8); PG8_WAIT_L(0); PG8_BAR; PG8_MMA(1, 0, At, B0); PG8_MMA(1, 1, At, B1); PG8_BAR; PG8_SCHED;
;             PG8_LDB(B0, 1, 0); PG8_LDB(B1, 1, 1); PG8_SCHED; PG8_LDA(At, 1, 0); PG8_STAGE(PG8_SA(0, 1), a2 + hstepA, voffA);
;             PG8_WAIT_V(8); PG8_WAIT_L(0); PG8_BAR; PG8_MMA(0, 0, At, B0); PG8_MMA(0, 1, At, B1); PG8_BAR; PG8_SCHED;
;             PG8_LDA(At, 1, 1); PG8_STAGE(PG8_SB(1, 0), b3, voffB); PG8_STAGE(PG8_SB(1, 1), b3 + hstepB, voffB); PG8_STAGE(PG8_SA(1, 0), a3, voffA);
;             PG8_WAIT_V(8); PG8_WAIT_L(0); PG8_BAR; PG8_MMA(1, 0, At, B0); PG8_MMA(1, 1, At, B1); PG8_BAR; PG8_SCHED;
.LBB0_849:
	ds_read_b128 v[162:165], v159
	ds_read_b128 v[166:169], v159 offset:1024
	ds_read_b128 v[170:173], v159 offset:2048
	ds_read_b128 v[174:177], v159 offset:3072
	ds_read_b128 v[178:181], v160
	ds_read_b128 v[182:185], v160 offset:1024
	ds_read_b128 v[186:189], v160 offset:2048
	ds_read_b128 v[190:193], v160 offset:3072
	s_add_u32 s24, s22, 0xfffc0080
	s_addc_u32 s25, s23, -1
	s_cmp_eq_u32 s58, 12
	s_cselect_b32 s27, s17, s25
	s_cselect_b32 s26, s54, s24
	s_cselect_b32 s25, s15, s57
	s_cselect_b32 s24, s55, s56
	v_lshl_add_u64 v[226:227], s[22:23], 0, v[138:139]
	s_add_i32 m0, s13, 0xc000
	ds_read_b128 v[194:197], v161
	ds_read_b128 v[198:201], v161 offset:1024
	ds_read_b128 v[202:205], v161 offset:2048
	ds_read_b128 v[206:209], v161 offset:3072
	ds_read_b128 v[210:213], v161 offset:4096
	ds_read_b128 v[214:217], v161 offset:5120
	ds_read_b128 v[218:221], v161 offset:6144
	ds_read_b128 v[222:225], v161 offset:7168
	global_load_lds_dwordx4 v[226:227], off
	v_lshl_add_u64 v[226:227], s[22:23], 0, v[140:141]
	s_add_i32 m0, s13, 0xe000
	s_nop 0
	global_load_lds_dwordx4 v[226:227], off
	s_waitcnt vmcnt(8)
	s_waitcnt lgkmcnt(0)
	s_setprio 1
	s_barrier
	v_mfma_f32_16x16x32_bf16 v[126:129], v[162:165], v[194:197], v[126:129]
	v_mfma_f32_16x16x32_bf16 v[126:129], v[166:169], v[198:201], v[126:129]
	v_mfma_f32_16x16x32_bf16 v[122:125], v[170:173], v[194:197], v[122:125]
	v_mfma_f32_16x16x32_bf16 v[122:125], v[174:177], v[198:201], v[122:125]
	v_mfma_f32_16x16x32_bf16 v[110:113], v[178:181], v[194:197], v[110:113]
	v_mfma_f32_16x16x32_bf16 v[110:113], v[182:185], v[198:201], v[110:113]
	v_mfma_f32_16x16x32_bf16 v[106:109], v[186:189], v[194:197], v[106:109]
	v_mfma_f32_16x16x32_bf16 v[106:109], v[190:193], v[198:201], v[106:109]
	v_mfma_f32_16x16x32_bf16 v[118:121], v[162:165], v[202:205], v[118:121]
	v_mfma_f32_16x16x32_bf16 v[118:121], v[166:169], v[206:209], v[118:121]
	v_mfma_f32_16x16x32_bf16 v[114:117], v[170:173], v[202:205], v[114:117]
	v_mfma_f32_16x16x32_bf16 v[114:117], v[174:177], v[206:209], v[114:117]
	v_mfma_f32_16x16x32_bf16 v[94:97], v[178:181], v[202:205], v[94:97]
	v_mfma_f32_16x16x32_bf16 v[94:97], v[182:185], v[206:209], v[94:97]
	v_mfma_f32_16x16x32_bf16 v[90:93], v[186:189], v[202:205], v[90:93]
	v_mfma_f32_16x16x32_bf16 v[90:93], v[190:193], v[206:209], v[90:93]
	v_mfma_f32_16x16x32_bf16 v[102:105], v[162:165], v[210:213], v[102:105]
	v_mfma_f32_16x16x32_bf16 v[102:105], v[166:169], v[214:217], v[102:105]
	v_mfma_f32_16x16x32_bf16 v[98:101], v[170:173], v[210:213], v[98:101]
	v_mfma_f32_16x16x32_bf16 v[98:101], v[174:177], v[214:217], v[98:101]
	v_mfma_f32_16x16x32_bf16 v[78:81], v[178:181], v[210:213], v[78:81]
	v_mfma_f32_16x16x32_bf16 v[78:81], v[182:185], v[214:217], v[78:81]
	v_mfma_f32_16x16x32_bf16 v[74:77], v[186:189], v[210:213], v[74:77]
	v_mfma_f32_16x16x32_bf16 v[74:77], v[190:193], v[214:217], v[74:77]
	v_mfma_f32_16x16x32_bf16 v[86:89], v[162:165], v[218:221], v[86:89]
	v_mfma_f32_16x16x32_bf16 v[86:89], v[166:169], v[222:225], v[86:89]
	v_mfma_f32_16x16x32_bf16 v[82:85], v[170:173], v[218:221], v[82:85]
	v_mfma_f32_16x16x32_bf16 v[82:85], v[174:177], v[222:225], v[82:85]
	v_mfma_f32_16x16x32_bf16 v[70:73], v[178:181], v[218:221], v[70:73]
	v_mfma_f32_16x16x32_bf16 v[70:73], v[182:185], v[222:225], v[70:73]
	v_mfma_f32_16x16x32_bf16 v[66:69], v[186:189], v[218:221], v[66:69]
	v_mfma_f32_16x16x32_bf16 v[66:69], v[190:193], v[222:225], v[66:69]
	s_barrier
	s_setprio 0
	s_add_i32 s59, s42, s31
	v_lshl_add_u64 v[226:227], s[24:25], 0, v[130:131]
	s_mov_b32 m0, s59
	ds_read_b128 v[194:197], v161 offset:16384
	ds_read_b128 v[198:201], v161 offset:17408
	ds_read_b128 v[202:205], v161 offset:18432
	ds_read_b128 v[206:209], v161 offset:19456
	ds_read_b128 v[210:213], v161 offset:20480
	ds_read_b128 v[214:217], v161 offset:21504
	ds_read_b128 v[218:221], v161 offset:22528
	ds_read_b128 v[222:225], v161 offset:23552
	global_load_lds_dwordx4 v[226:227], off
	s_add_i32 m0, s59, 0x2000
	s_add_u32 s60, s24, 0x4000
	v_lshl_add_u64 v[226:227], s[24:25], 0, v[132:133]
	s_addc_u32 s61, s25, 0
	s_add_i32 s59, s43, s31
	global_load_lds_dwordx4 v[226:227], off
	v_lshl_add_u64 v[226:227], s[60:61], 0, v[130:131]
	s_mov_b32 m0, s59
	v_lshl_add_u64 v[228:229], s[26:27], 0, v[134:135]
	global_load_lds_dwordx4 v[226:227], off
	v_lshl_add_u64 v[226:227], s[60:61], 0, v[132:133]
	s_add_i32 m0, s59, 0x2000
	s_nop 0
	global_load_lds_dwordx4 v[226:227], off
	v_lshl_add_u64 v[226:227], s[26:27], 0, v[136:137]
	s_mov_b32 m0, s13
	s_nop 0
	global_load_lds_dwordx4 v[226:227], off
	s_mov_b32 m0, s34
	s_nop 0
	global_load_lds_dwordx4 v[228:229], off
	s_waitcnt vmcnt(8)
	s_waitcnt lgkmcnt(0)
	s_setprio 1
	s_barrier
; #define PG8_STAGE(bufoff, gbase, voff) do { _Pragma("unroll") for (int _i = 0; _i < 2; ++_i) \
;         __builtin_amdgcn_global_load_lds((const unsigned*)((const char*)(gbase) + (voff)[_i]), (PG8_LAS unsigned*)(lds + (bufoff) + ldsw + _i * 8192), 16, 0, 0); } while (0)
; #define PG8_LDA(dst, b, h) do { _Pragma("unroll") for (int m = 0; m < 4; ++m) _Pragma("unroll") for (int k = 0; k < 2; ++k) dst[m][k] = *(const PG8_LAS bf16x8*)(lds + PG8_SA(b, h) + aoff + m * 2048 + k * 1024); } while (0)
; #define PG8_WAIT_V(n) asm volatile("s_waitcnt vmcnt(" #n ")" ::: "memory")
; #define PG8_WAIT_L(n) asm volatile("s_waitcnt lgkmcnt(" #n ")" ::: "memory")
; #define PG8_BAR __builtin_amdgcn_s_barrier()
; template <class Epi, class Sched, bool ALIGN_EPI = false, bool SP2 = false, bool A_TILED = false>
; __device__ __forceinline__ void gemm_phase(PG8_LAS unsigned char* lds, const Gemm g, const Sched& S, const Epi& E) {
;     ...
;         for (int t = 0; t < nt; t += 2) {
;             const bool last = (t == nt - 2);
;             const char* a1 = cA + (size_t)(t + 1) * kstepA;
;             const char* a2 = last ? nA : cA + (size_t)(t + 2) * kstepA; const char* b2 = last ? nB : cB + (size_t)(t + 2) * kstepB;
;             const char* a3 = a2 + kstepA; const char* b3 = b2 + kstepB;
;             if (last && has_next) S.a_ready(nxt);
;             if constexpr (SP2) {
;             PG8_LDB(B0, 0, 0); PG8_LDB(B1, 0, 1); PG8_SCHED; PG8_LDA(At, 0, 0); PG8_STAGE(PG8_SA(1, 1), a1 + hstepA, voffA);
;             PG8_WAIT_V(8); PG8_WAIT_L(0); PG8_BAR; PG8_MMA(0, 0, At, B0); PG8_MMA(0, 1, At, B1); PG8_BAR; PG8_SCHED;
;             PG8_LDA(At, 0, 1); PG8_STAGE(PG8_SB(0, 0), b2, voffB); PG8_STAGE(PG8_SB(0, 1), b2 + hstepB, voffB); PG8_STAGE(PG8_SA(0, 0), a2, voffA);
;             PG8_WAIT_V(8); PG8_WAIT_L(0); PG8_BAR; PG8_MMA(1, 0, At, B0); PG8_MMA(1, 1, At, B1); PG8_BAR; PG8_SCHED;
;             PG8_LDB(B0, 1, 0); PG8_LDB(B1, 1, 1); PG8_SCHED; PG8_LDA(At, 1, 0); PG8_STAGE(PG8_SA(0, 1), a2 + hstepA, voffA);
;             PG8_WAIT_V(8); PG8_WAIT_L(0); PG8_BAR; PG8_MMA(0, 0, At, B0); PG8_MMA(0, 1, At, B1); PG8_BAR; PG8_SCHED;
;             PG8_LDA(At, 1, 1); PG8_STAGE(PG8_SB(1, 0), b3, voffB); PG8_STAGE(PG8_SB(1, 1), b3 + hstepB, voffB); PG8_STAGE(PG8_SA(1, 0), a3, voffA);
;             PG8_WAIT_V(8); PG8_WAIT_L(0); PG8_BAR; PG8_MMA(1, 0, At, B0); PG8_MMA(1, 1, At, B1); PG8_BAR; PG8_SCHED;
	v_mfma_f32_16x16x32_bf16 v[62:65], v[162:165], v[194:197], v[62:65]
	v_mfma_f32_16x16x32_bf16 v[62:65], v[166:169], v[198:201], v[62:65]
	v_mfma_f32_16x16x32_bf16 v[58:61], v[170:173], v[194:197], v[58:61]
	v_mfma_f32_16x16x32_bf16 v[58:61], v[174:177], v[198:201], v[58:61]
	v_mfma_f32_16x16x32_bf16 v[46:49], v[178:181], v[194:197], v[46:49]
	v_mfma_f32_16x16x32_bf16 v[46:49], v[182:185], v[198:201], v[46:49]
	v_mfma_f32_16x16x32_bf16 v[42:45], v[186:189], v[194:197], v[42:45]
	v_mfma_f32_16x16x32_bf16 v[42:45], v[190:193], v[198:201], v[42:45]
	v_mfma_f32_16x16x32_bf16 v[54:57], v[162:165], v[202:205], v[54:57]
	v_mfma_f32_16x16x32_bf16 v[54:57], v[166:169], v[206:209], v[54:57]
	v_mfma_f32_16x16x32_bf16 v[50:53], v[170:173], v[202:205], v[50:53]
	v_mfma_f32_16x16x32_bf16 v[50:53], v[174:177], v[206:209], v[50:53]
	v_mfma_f32_16x16x32_bf16 v[30:33], v[178:181], v[202:205], v[30:33]
	v_mfma_f32_16x16x32_bf16 v[30:33], v[182:185], v[206:209], v[30:33]
	v_mfma_f32_16x16x32_bf16 v[26:29], v[186:189], v[202:205], v[26:29]
	v_mfma_f32_16x16x32_bf16 v[26:29], v[190:193], v[206:209], v[26:29]
	v_mfma_f32_16x16x32_bf16 v[38:41], v[162:165], v[210:213], v[38:41]
	v_mfma_f32_16x16x32_bf16 v[38:41], v[166:169], v[214:217], v[38:41]
	v_mfma_f32_16x16x32_bf16 v[34:37], v[170:173], v[210:213], v[34:37]
	v_mfma_f32_16x16x32_bf16 v[34:37], v[174:177], v[214:217], v[34:37]
	v_mfma_f32_16x16x32_bf16 v[14:17], v[178:181], v[210:213], v[14:17]
	v_mfma_f32_16x16x32_bf16 v[14:17], v[182:185], v[214:217], v[14:17]
	v_mfma_f32_16x16x32_bf16 v[10:13], v[186:189], v[210:213], v[10:13]
	v_mfma_f32_16x16x32_bf16 v[10:13], v[190:193], v[214:217], v[10:13]
	v_mfma_f32_16x16x32_bf16 v[22:25], v[162:165], v[218:221], v[22:25]
	v_mfma_f32_16x16x32_bf16 v[22:25], v[166:169], v[222:225], v[22:25]
	v_mfma_f32_16x16x32_bf16 v[18:21], v[170:173], v[218:221], v[18:21]
	v_mfma_f32_16x16x32_bf16 v[18:21], v[174:177], v[222:225], v[18:21]
	v_mfma_f32_16x16x32_bf16 v[6:9], v[178:181], v[218:221], v[6:9]
	v_mfma_f32_16x16x32_bf16 v[6:9], v[182:185], v[222:225], v[6:9]
	v_mfma_f32_16x16x32_bf16 v[2:5], v[186:189], v[218:221], v[2:5]
	v_mfma_f32_16x16x32_bf16 v[2:5], v[190:193], v[222:225], v[2:5]
	s_barrier
	s_setprio 0
	s_add_i32 s59, 0, 0x18000
	s_add_i32 s60, 0, 0x1c000
	v_add_u32_e32 v174, s59, v157
	v_add_u32_e32 v190, s60, v157
	ds_read_b128 v[162:165], v174
	ds_read_b128 v[166:169], v174 offset:1024
	ds_read_b128 v[170:173], v174 offset:2048
	ds_read_b128 v[174:177], v174 offset:3072
	ds_read_b128 v[178:181], v190
	ds_read_b128 v[182:185], v190 offset:1024
	ds_read_b128 v[186:189], v190 offset:2048
	ds_read_b128 v[190:193], v190 offset:3072
	s_add_u32 s26, s26, 0x40000
	s_addc_u32 s27, s27, 0
	s_mov_b32 m0, s35
	v_lshl_add_u64 v[230:231], s[26:27], 0, v[136:137]
	ds_read_b128 v[194:197], v161 offset:32768
	ds_read_b128 v[198:201], v161 offset:33792
	ds_read_b128 v[202:205], v161 offset:34816
	ds_read_b128 v[206:209], v161 offset:35840
	ds_read_b128 v[210:213], v161 offset:36864
	ds_read_b128 v[214:217], v161 offset:37888
	ds_read_b128 v[218:221], v161 offset:38912
	ds_read_b128 v[222:225], v161 offset:39936
	global_load_lds_dwordx4 v[230:231], off
	v_lshl_add_u64 v[230:231], s[26:27], 0, v[134:135]
	s_mov_b32 m0, s36
	s_nop 0
	global_load_lds_dwordx4 v[230:231], off
	s_waitcnt vmcnt(8)
	s_waitcnt lgkmcnt(0)
	s_setprio 1
	s_barrier
	v_mfma_f32_16x16x32_bf16 v[126:129], v[162:165], v[194:197], v[126:129]
	v_mfma_f32_16x16x32_bf16 v[126:129], v[166:169], v[198:201], v[126:129]
	v_mfma_f32_16x16x32_bf16 v[122:125], v[170:173], v[194:197], v[122:125]
	v_mfma_f32_16x16x32_bf16 v[122:125], v[174:177], v[198:201], v[122:125]
	v_mfma_f32_16x16x32_bf16 v[110:113], v[178:181], v[194:197], v[110:113]
	v_mfma_f32_16x16x32_bf16 v[110:113], v[182:185], v[198:201], v[110:113]
	v_mfma_f32_16x16x32_bf16 v[106:109], v[186:189], v[194:197], v[106:109]
	v_mfma_f32_16x16x32_bf16 v[106:109], v[190:193], v[198:201], v[106:109]
	v_mfma_f32_16x16x32_bf16 v[118:121], v[162:165], v[202:205], v[118:121]
	v_mfma_f32_16x16x32_bf16 v[118:121], v[166:169], v[206:209], v[118:121]
	v_mfma_f32_16x16x32_bf16 v[114:117], v[170:173], v[202:205], v[114:117]
	v_mfma_f32_16x16x32_bf16 v[114:117], v[174:177], v[206:209], v[114:117]
	v_mfma_f32_16x16x32_bf16 v[94:97], v[178:181], v[202:205], v[94:97]
	v_mfma_f32_16x16x32_bf16 v[94:97], v[182:185], v[206:209], v[94:97]
	v_mfma_f32_16x16x32_bf16 v[90:93], v[186:189], v[202:205], v[90:93]
	v_mfma_f32_16x16x32_bf16 v[90:93], v[190:193], v[206:209], v[90:93]
	v_mfma_f32_16x16x32_bf16 v[102:105], v[162:165], v[210:213], v[102:105]
	v_mfma_f32_16x16x32_bf16 v[102:105], v[166:169], v[214:217], v[102:105]
	v_mfma_f32_16x16x32_bf16 v[98:101], v[170:173], v[210:213], v[98:101]
	v_mfma_f32_16x16x32_bf16 v[98:101], v[174:177], v[214:217], v[98:101]
	v_mfma_f32_16x16x32_bf16 v[78:81], v[178:181], v[210:213], v[78:81]
	v_mfma_f32_16x16x32_bf16 v[78:81], v[182:185], v[214:217], v[78:81]
	v_mfma_f32_16x16x32_bf16 v[74:77], v[186:189], v[210:213], v[74:77]
	v_mfma_f32_16x16x32_bf16 v[74:77], v[190:193], v[214:217], v[74:77]
	v_mfma_f32_16x16x32_bf16 v[86:89], v[162:165], v[218:221], v[86:89]
	v_mfma_f32_16x16x32_bf16 v[86:89], v[166:169], v[222:225], v[86:89]
	v_mfma_f32_16x16x32_bf16 v[82:85], v[170:173], v[218:221], v[82:85]
	v_mfma_f32_16x16x32_bf16 v[82:85], v[174:177], v[222:225], v[82:85]
	v_mfma_f32_16x16x32_bf16 v[70:73], v[178:181], v[218:221], v[70:73]
	v_mfma_f32_16x16x32_bf16 v[70:73], v[182:185], v[222:225], v[70:73]
	v_mfma_f32_16x16x32_bf16 v[66:69], v[186:189], v[218:221], v[66:69]
	v_mfma_f32_16x16x32_bf16 v[66:69], v[190:193], v[222:225], v[66:69]
	s_barrier
; #define PG8_STAGE(bufoff, gbase, voff) do { _Pragma("unroll") for (int _i = 0; _i < 2; ++_i) \
;         __builtin_amdgcn_global_load_lds((const unsigned*)((const char*)(gbase) + (voff)[_i]), (PG8_LAS unsigned*)(lds + (bufoff) + ldsw + _i * 8192), 16, 0, 0); } while (0)
; #define PG8_LDA(dst, b, h) do { _Pragma("unroll") for (int m = 0; m < 4; ++m) _Pragma("unroll") for (int k = 0; k < 2; ++k) dst[m][k] = *(const PG8_LAS bf16x8*)(lds + PG8_SA(b, h) + aoff + m * 2048 + k * 1024); } while (0)
; #define PG8_WAIT_V(n) asm volatile("s_waitcnt vmcnt(" #n ")" ::: "memory")
; #define PG8_WAIT_L(n) asm volatile("s_waitcnt lgkmcnt(" #n ")" ::: "memory")
; #define PG8_BAR __builtin_amdgcn_s_barrier()
; template <class Epi, class Sched, bool ALIGN_EPI = false, bool SP2 = false, bool A_TILED = false>
; __device__ __forceinline__ void gemm_phase(PG8_LAS unsigned char* lds, const Gemm g, const Sched& S, const Epi& E) {
;     ...
;         for (int t = 0; t < nt; t += 2) {
;             const bool last = (t == nt - 2);
;             const char* a1 = cA + (size_t)(t + 1) * kstepA;
;             const char* a2 = last ? nA : cA + (size_t)(t + 2) * kstepA; const char* b2 = last ? nB : cB + (size_t)(t + 2) * kstepB;
;             const char* a3 = a2 + kstepA; const char* b3 = b2 + kstepB;
;             if (last && has_next) S.a_ready(nxt);
;             if constexpr (SP2) {
;             PG8_LDB(B0, 0, 0); PG8_LDB(B1, 0, 1); PG8_SCHED; PG8_LDA(At, 0, 0); PG8_STAGE(PG8_SA(1, 1), a1 + hstepA, voffA);
;             PG8_WAIT_V(8); PG8_WAIT_L(0); PG8_BAR; PG8_MMA(0, 0, At, B0); PG8_MMA(0, 1, At, B1); PG8_BAR; PG8_SCHED;
;             PG8_LDA(At, 0, 1); PG8_STAGE(PG8_SB(0, 0), b2, voffB); PG8_STAGE(PG8_SB(0, 1), b2 + hstepB, voffB); PG8_STAGE(PG8_SA(0, 0), a2, voffA);
;             PG8_WAIT_V(8); PG8_WAIT_L(0); PG8_BAR; PG8_MMA(1, 0, At, B0); PG8_MMA(1, 1, At, B1); PG8_BAR; PG8_SCHED;
;             PG8_LDB(B0, 1, 0); PG8_LDB(B1, 1, 1); PG8_SCHED; PG8_LDA(At, 1, 0); PG8_STAGE(PG8_SA(0, 1), a2 + hstepA, voffA);
;             PG8_WAIT_V(8); PG8_WAIT_L(0); PG8_BAR; PG8_MMA(0, 0, At, B0); PG8_MMA(0, 1, At, B1); PG8_BAR; PG8_SCHED;
;             PG8_LDA(At, 1, 1); PG8_STAGE(PG8_SB(1, 0), b3, voffB); PG8_STAGE(PG8_SB(1, 1), b3 + hstepB, voffB); PG8_STAGE(PG8_SA(1, 0), a3, voffA);
;             PG8_WAIT_V(8); PG8_WAIT_L(0); PG8_BAR; PG8_MMA(1, 0, At, B0); PG8_MMA(1, 1, At, B1); PG8_BAR; PG8_SCHED;
	s_setprio 0
	s_add_u32 s26, s24, 0x8000
	s_addc_u32 s27, s25, 0
	s_add_i32 s59, s59, s31
	v_lshl_add_u64 v[230:231], s[26:27], 0, v[130:131]
	s_mov_b32 m0, s59
	ds_read_b128 v[194:197], v161 offset:49152
	ds_read_b128 v[198:201], v161 offset:50176
	ds_read_b128 v[202:205], v161 offset:51200
	ds_read_b128 v[206:209], v161 offset:52224
	ds_read_b128 v[210:213], v161 offset:53248
	ds_read_b128 v[214:217], v161 offset:54272
	ds_read_b128 v[218:221], v161 offset:55296
	ds_read_b128 v[222:225], v161 offset:56320
	global_load_lds_dwordx4 v[230:231], off
	s_add_i32 m0, s59, 0x2000
	s_add_u32 s24, s24, 0xc000
	v_lshl_add_u64 v[230:231], s[26:27], 0, v[132:133]
	s_addc_u32 s25, s25, 0
	s_add_i32 s26, s60, s31
	global_load_lds_dwordx4 v[230:231], off
	v_lshl_add_u64 v[230:231], s[24:25], 0, v[130:131]
	s_mov_b32 m0, s26
	v_lshl_add_u64 v[226:227], v[226:227], 0, s[8:9]
	global_load_lds_dwordx4 v[230:231], off
	v_lshl_add_u64 v[230:231], s[24:25], 0, v[132:133]
	s_add_i32 m0, s26, 0x2000
	s_nop 0
	global_load_lds_dwordx4 v[230:231], off
	s_mov_b32 m0, s38
	s_nop 0
	global_load_lds_dwordx4 v[226:227], off
	v_lshl_add_u64 v[226:227], v[228:229], 0, s[8:9]
	s_mov_b32 m0, s39
	s_nop 0
	global_load_lds_dwordx4 v[226:227], off
	s_waitcnt vmcnt(8)
	s_waitcnt lgkmcnt(0)
	s_setprio 1
	s_barrier
	v_mfma_f32_16x16x32_bf16 v[62:65], v[162:165], v[194:197], v[62:65]
	v_mfma_f32_16x16x32_bf16 v[62:65], v[166:169], v[198:201], v[62:65]
	v_mfma_f32_16x16x32_bf16 v[58:61], v[170:173], v[194:197], v[58:61]
	v_mfma_f32_16x16x32_bf16 v[58:61], v[174:177], v[198:201], v[58:61]
	v_mfma_f32_16x16x32_bf16 v[46:49], v[178:181], v[194:197], v[46:49]
	v_mfma_f32_16x16x32_bf16 v[46:49], v[182:185], v[198:201], v[46:49]
	v_mfma_f32_16x16x32_bf16 v[42:45], v[186:189], v[194:197], v[42:45]
	v_mfma_f32_16x16x32_bf16 v[42:45], v[190:193], v[198:201], v[42:45]
	v_mfma_f32_16x16x32_bf16 v[54:57], v[162:165], v[202:205], v[54:57]
	v_mfma_f32_16x16x32_bf16 v[54:57], v[166:169], v[206:209], v[54:57]
	v_mfma_f32_16x16x32_bf16 v[50:53], v[170:173], v[202:205], v[50:53]
	v_mfma_f32_16x16x32_bf16 v[50:53], v[174:177], v[206:209], v[50:53]
	v_mfma_f32_16x16x32_bf16 v[30:33], v[178:181], v[202:205], v[30:33]
	v_mfma_f32_16x16x32_bf16 v[30:33], v[182:185], v[206:209], v[30:33]
	v_mfma_f32_16x16x32_bf16 v[26:29], v[186:189], v[202:205], v[26:29]
	v_mfma_f32_16x16x32_bf16 v[26:29], v[190:193], v[206:209], v[26:29]
	v_mfma_f32_16x16x32_bf16 v[38:41], v[162:165], v[210:213], v[38:41]
	v_mfma_f32_16x16x32_bf16 v[38:41], v[166:169], v[214:217], v[38:41]
	v_mfma_f32_16x16x32_bf16 v[34:37], v[170:173], v[210:213], v[34:37]
	v_mfma_f32_16x16x32_bf16 v[34:37], v[174:177], v[214:217], v[34:37]
	v_mfma_f32_16x16x32_bf16 v[14:17], v[178:181], v[210:213], v[14:17]
	v_mfma_f32_16x16x32_bf16 v[14:17], v[182:185], v[214:217], v[14:17]
	v_mfma_f32_16x16x32_bf16 v[10:13], v[186:189], v[210:213], v[10:13]
	v_mfma_f32_16x16x32_bf16 v[10:13], v[190:193], v[214:217], v[10:13]
	v_mfma_f32_16x16x32_bf16 v[22:25], v[162:165], v[218:221], v[22:25]
	v_mfma_f32_16x16x32_bf16 v[22:25], v[166:169], v[222:225], v[22:25]
	v_mfma_f32_16x16x32_bf16 v[18:21], v[170:173], v[218:221], v[18:21]
	v_mfma_f32_16x16x32_bf16 v[18:21], v[174:177], v[222:225], v[18:21]
	v_mfma_f32_16x16x32_bf16 v[6:9], v[178:181], v[218:221], v[6:9]
	v_mfma_f32_16x16x32_bf16 v[6:9], v[182:185], v[222:225], v[6:9]
	v_mfma_f32_16x16x32_bf16 v[2:5], v[186:189], v[218:221], v[2:5]
	v_mfma_f32_16x16x32_bf16 v[2:5], v[190:193], v[222:225], v[2:5]
	s_barrier
	s_setprio 0
	s_add_i32 s58, s58, 2
	s_add_u32 s56, s56, 0x10000
	s_addc_u32 s57, s57, 0
	s_add_u32 s22, s22, 0x100
	s_addc_u32 s23, s23, 0
	s_cmp_gt_u32 s58, 13
	s_cbranch_scc0 .LBB0_849
	s_and_b64 vcc, exec, s[10:11]
	s_cbranch_vccz .LBB0_852
	s_barrier

; #define PG8_STAGE(bufoff, gbase, voff) do { _Pragma("unroll") for (int _i = 0; _i < 2; ++_i) \
;         __builtin_amdgcn_global_load_lds((const unsigned*)((const char*)(gbase) + (voff)[_i]), (PG8_LAS unsigned*)(lds + (bufoff) + ldsw + _i * 8192), 16, 0, 0); } while (0)
; #define PG8_LDA(dst, b, h) do { _Pragma("unroll") for (int m = 0; m < 4; ++m) _Pragma("unroll") for (int k = 0; k < 2; ++k) dst[m][k] = *(const PG8_LAS bf16x8*)(lds + PG8_SA(b, h) + aoff + m * 2048 + k * 1024); } while (0)
; #define PG8_WAIT_V(n) asm volatile("s_waitcnt vmcnt(" #n ")" ::: "memory")
; #define PG8_WAIT_L(n) asm volatile("s_waitcnt lgkmcnt(" #n ")" ::: "memory")
; #define PG8_BAR __builtin_amdgcn_s_barrier()
; template <class Epi, class Sched, bool ALIGN_EPI = false, bool SP2 = false, bool A_TILED = false>
; __device__ __forceinline__ void gemm_phase(PG8_LAS unsigned char* lds, const Gemm g, const Sched& S, const Epi& E) {
;     ...
;         for (int t = 0; t < nt; t += 2) {
;             const bool last = (t == nt - 2);
;             const char* a1 = cA + (size_t)(t + 1) * kstepA;
;             const char* a2 = last ? nA : cA + (size_t)(t + 2) * kstepA; const char* b2 = last ? nB : cB + (size_t)(t + 2) * kstepB;
;             const char* a3 = a2 + kstepA; const char* b3 = b2 + kstepB;
;             if (last && has_next) S.a_ready(nxt);
;             if constexpr (SP2) {
;             PG8_LDB(B0, 0, 0); PG8_LDB(B1, 0, 1); PG8_SCHED; PG8_LDA(At, 0, 0); PG8_STAGE(PG8_SA(1, 1), a1 + hstepA, voffA);
;             PG8_WAIT_V(8); PG8_WAIT_L(0); PG8_BAR; PG8_MMA(0, 0, At, B0); PG8_MMA(0, 1, At, B1); PG8_BAR; PG8_SCHED;
;             PG8_LDA(At, 0, 1); PG8_STAGE(PG8_SB(0, 0), b2, voffB); PG8_STAGE(PG8_SB(0, 1), b2 + hstepB, voffB); PG8_STAGE(PG8_SA(0, 0), a2, voffA);
;             PG8_WAIT_V(8); PG8_WAIT_L(0); PG8_BAR; PG8_MMA(1, 0, At, B0); PG8_MMA(1, 1, At, B1); PG8_BAR; PG8_SCHED;
;             PG8_LDB(B0, 1, 0); PG8_LDB(B1, 1, 1); PG8_SCHED; PG8_LDA(At, 1, 0); PG8_STAGE(PG8_SA(0, 1), a2 + hstepA, voffA);
;             PG8_WAIT_V(8); PG8_WAIT_L(0); PG8_BAR; PG8_MMA(0, 0, At, B0); PG8_MMA(0, 1, At, B1); PG8_BAR; PG8_SCHED;
;             PG8_LDA(At, 1, 1); PG8_STAGE(PG8_SB(1, 0), b3, voffB); PG8_STAGE(PG8_SB(1, 1), b3 + hstepB, voffB); PG8_STAGE(PG8_SA(1, 0), a3, voffA);
;             PG8_WAIT_V(8); PG8_WAIT_L(0); PG8_BAR; PG8_MMA(1, 0, At, B0); PG8_MMA(1, 1, At, B1); PG8_BAR; PG8_SCHED;
.LBB0_873:
	ds_read_b128 v[154:157], v1
	ds_read_b128 v[158:161], v1 offset:1024
	ds_read_b128 v[162:165], v1 offset:2048
	ds_read_b128 v[166:169], v1 offset:3072
	ds_read_b128 v[170:173], v146
	ds_read_b128 v[174:177], v146 offset:1024
	ds_read_b128 v[178:181], v146 offset:2048
	ds_read_b128 v[182:185], v146 offset:3072
	s_add_u32 s36, s34, 0xfffe0080
	s_addc_u32 s37, s35, -1
	s_cmp_eq_u32 s75, 4
	s_cselect_b32 s39, s27, s37
	s_cselect_b32 s38, s71, s36
	s_cselect_b32 s37, s25, s74
	s_cselect_b32 s36, s72, s73
	v_lshl_add_u64 v[218:219], s[34:35], 0, v[138:139]
	s_add_i32 m0, s23, 0xc000
	ds_read_b128 v[186:189], v147
	ds_read_b128 v[190:193], v147 offset:1024
	ds_read_b128 v[194:197], v147 offset:2048
	ds_read_b128 v[198:201], v147 offset:3072
	ds_read_b128 v[202:205], v147 offset:4096
	ds_read_b128 v[206:209], v147 offset:5120
	ds_read_b128 v[210:213], v147 offset:6144
	ds_read_b128 v[214:217], v147 offset:7168
	global_load_lds_dwordx4 v[218:219], off
	v_lshl_add_u64 v[218:219], s[34:35], 0, v[140:141]
	s_add_i32 m0, s23, 0xe000
	s_nop 0
	global_load_lds_dwordx4 v[218:219], off
	s_waitcnt vmcnt(8)
	s_waitcnt lgkmcnt(0)
	s_barrier
	s_setprio 1
	s_waitcnt lgkmcnt(0)
	v_mfma_f32_16x16x32_bf16 v[126:129], v[154:157], v[186:189], v[126:129]
	v_mfma_f32_16x16x32_bf16 v[122:125], v[162:165], v[186:189], v[122:125]
	v_mfma_f32_16x16x32_bf16 v[118:121], v[154:157], v[194:197], v[118:121]
	v_mfma_f32_16x16x32_bf16 v[114:117], v[162:165], v[194:197], v[114:117]
	v_mfma_f32_16x16x32_bf16 v[102:105], v[154:157], v[202:205], v[102:105]
	v_mfma_f32_16x16x32_bf16 v[98:101], v[162:165], v[202:205], v[98:101]
	v_mfma_f32_16x16x32_bf16 v[86:89], v[154:157], v[210:213], v[86:89]
	v_mfma_f32_16x16x32_bf16 v[82:85], v[162:165], v[210:213], v[82:85]
	v_mfma_f32_16x16x32_bf16 v[126:129], v[158:161], v[190:193], v[126:129]
	v_mfma_f32_16x16x32_bf16 v[122:125], v[166:169], v[190:193], v[122:125]
	v_mfma_f32_16x16x32_bf16 v[118:121], v[158:161], v[198:201], v[118:121]
	v_mfma_f32_16x16x32_bf16 v[114:117], v[166:169], v[198:201], v[114:117]
	v_mfma_f32_16x16x32_bf16 v[102:105], v[158:161], v[206:209], v[102:105]
	v_mfma_f32_16x16x32_bf16 v[98:101], v[166:169], v[206:209], v[98:101]
	v_mfma_f32_16x16x32_bf16 v[86:89], v[158:161], v[214:217], v[86:89]
	v_mfma_f32_16x16x32_bf16 v[82:85], v[166:169], v[214:217], v[82:85]
	s_setprio 0
	s_setprio 1
	v_mfma_f32_16x16x32_bf16 v[110:113], v[170:173], v[186:189], v[110:113]
	v_mfma_f32_16x16x32_bf16 v[106:109], v[178:181], v[186:189], v[106:109]
	v_mfma_f32_16x16x32_bf16 v[94:97], v[170:173], v[194:197], v[94:97]
	v_mfma_f32_16x16x32_bf16 v[90:93], v[178:181], v[194:197], v[90:93]
	v_mfma_f32_16x16x32_bf16 v[78:81], v[170:173], v[202:205], v[78:81]
	v_mfma_f32_16x16x32_bf16 v[74:77], v[178:181], v[202:205], v[74:77]
	v_mfma_f32_16x16x32_bf16 v[70:73], v[170:173], v[210:213], v[70:73]
	v_mfma_f32_16x16x32_bf16 v[66:69], v[178:181], v[210:213], v[66:69]
	v_mfma_f32_16x16x32_bf16 v[110:113], v[174:177], v[190:193], v[110:113]
	v_mfma_f32_16x16x32_bf16 v[106:109], v[182:185], v[190:193], v[106:109]
	v_mfma_f32_16x16x32_bf16 v[94:97], v[174:177], v[198:201], v[94:97]
	v_mfma_f32_16x16x32_bf16 v[90:93], v[182:185], v[198:201], v[90:93]
	v_mfma_f32_16x16x32_bf16 v[78:81], v[174:177], v[206:209], v[78:81]
	v_mfma_f32_16x16x32_bf16 v[74:77], v[182:185], v[206:209], v[74:77]
	v_mfma_f32_16x16x32_bf16 v[70:73], v[174:177], v[214:217], v[70:73]
	v_mfma_f32_16x16x32_bf16 v[66:69], v[182:185], v[214:217], v[66:69]
	s_setprio 0
	s_barrier
	s_add_i32 s76, s59, s43
	v_lshl_add_u64 v[218:219], s[36:37], 0, v[130:131]
	s_mov_b32 m0, s76
	ds_read_b128 v[186:189], v147 offset:16384
	ds_read_b128 v[190:193], v147 offset:17408
	ds_read_b128 v[194:197], v147 offset:18432
	ds_read_b128 v[198:201], v147 offset:19456
	ds_read_b128 v[202:205], v147 offset:20480
	ds_read_b128 v[206:209], v147 offset:21504
	ds_read_b128 v[210:213], v147 offset:22528
	ds_read_b128 v[214:217], v147 offset:23552
	global_load_lds_dwordx4 v[218:219], off
	s_add_i32 m0, s76, 0x2000
	s_add_u32 s76, s36, 0x4000
	v_lshl_add_u64 v[218:219], s[36:37], 0, v[132:133]
	s_addc_u32 s77, s37, 0
	s_add_i32 s80, s60, s43
	global_load_lds_dwordx4 v[218:219], off
	v_lshl_add_u64 v[218:219], s[76:77], 0, v[130:131]
	s_mov_b32 m0, s80
	v_lshl_add_u64 v[220:221], s[38:39], 0, v[136:137]
	global_load_lds_dwordx4 v[218:219], off
	v_lshl_add_u64 v[218:219], s[76:77], 0, v[132:133]
	s_add_i32 m0, s80, 0x2000
	s_nop 0
	global_load_lds_dwordx4 v[218:219], off
	v_lshl_add_u64 v[218:219], s[38:39], 0, v[134:135]
	s_mov_b32 m0, s23
	s_nop 0
	global_load_lds_dwordx4 v[218:219], off
	s_mov_b32 m0, s44
	s_nop 0
	global_load_lds_dwordx4 v[220:221], off
	s_waitcnt vmcnt(8)
	s_waitcnt lgkmcnt(0)
	s_setprio 1
	s_barrier
; #define PG8_STAGE(bufoff, gbase, voff) do { _Pragma("unroll") for (int _i = 0; _i < 2; ++_i) \
;         __builtin_amdgcn_global_load_lds((const unsigned*)((const char*)(gbase) + (voff)[_i]), (PG8_LAS unsigned*)(lds + (bufoff) + ldsw + _i * 8192), 16, 0, 0); } while (0)
; #define PG8_LDA(dst, b, h) do { _Pragma("unroll") for (int m = 0; m < 4; ++m) _Pragma("unroll") for (int k = 0; k < 2; ++k) dst[m][k] = *(const PG8_LAS bf16x8*)(lds + PG8_SA(b, h) + aoff + m * 2048 + k * 1024); } while (0)
; #define PG8_WAIT_V(n) asm volatile("s_waitcnt vmcnt(" #n ")" ::: "memory")
; #define PG8_WAIT_L(n) asm volatile("s_waitcnt lgkmcnt(" #n ")" ::: "memory")
; #define PG8_BAR __builtin_amdgcn_s_barrier()
; template <class Epi, class Sched, bool ALIGN_EPI = false, bool SP2 = false, bool A_TILED = false>
; __device__ __forceinline__ void gemm_phase(PG8_LAS unsigned char* lds, const Gemm g, const Sched& S, const Epi& E) {
;     ...
;         for (int t = 0; t < nt; t += 2) {
;             const bool last = (t == nt - 2);
;             const char* a1 = cA + (size_t)(t + 1) * kstepA;
;             const char* a2 = last ? nA : cA + (size_t)(t + 2) * kstepA; const char* b2 = last ? nB : cB + (size_t)(t + 2) * kstepB;
;             const char* a3 = a2 + kstepA; const char* b3 = b2 + kstepB;
;             if (last && has_next) S.a_ready(nxt);
;             if constexpr (SP2) {
;             PG8_LDB(B0, 0, 0); PG8_LDB(B1, 0, 1); PG8_SCHED; PG8_LDA(At, 0, 0); PG8_STAGE(PG8_SA(1, 1), a1 + hstepA, voffA);
;             PG8_WAIT_V(8); PG8_WAIT_L(0); PG8_BAR; PG8_MMA(0, 0, At, B0); PG8_MMA(0, 1, At, B1); PG8_BAR; PG8_SCHED;
;             PG8_LDA(At, 0, 1); PG8_STAGE(PG8_SB(0, 0), b2, voffB); PG8_STAGE(PG8_SB(0, 1), b2 + hstepB, voffB); PG8_STAGE(PG8_SA(0, 0), a2, voffA);
;             PG8_WAIT_V(8); PG8_WAIT_L(0); PG8_BAR; PG8_MMA(1, 0, At, B0); PG8_MMA(1, 1, At, B1); PG8_BAR; PG8_SCHED;
;             PG8_LDB(B0, 1, 0); PG8_LDB(B1, 1, 1); PG8_SCHED; PG8_LDA(At, 1, 0); PG8_STAGE(PG8_SA(0, 1), a2 + hstepA, voffA);
;             PG8_WAIT_V(8); PG8_WAIT_L(0); PG8_BAR; PG8_MMA(0, 0, At, B0); PG8_MMA(0, 1, At, B1); PG8_BAR; PG8_SCHED;
;             PG8_LDA(At, 1, 1); PG8_STAGE(PG8_SB(1, 0), b3, voffB); PG8_STAGE(PG8_SB(1, 1), b3 + hstepB, voffB); PG8_STAGE(PG8_SA(1, 0), a3, voffA);
;             PG8_WAIT_V(8); PG8_WAIT_L(0); PG8_BAR; PG8_MMA(1, 0, At, B0); PG8_MMA(1, 1, At, B1); PG8_BAR; PG8_SCHED;
	v_mfma_f32_16x16x32_bf16 v[62:65], v[154:157], v[186:189], v[62:65]
	v_mfma_f32_16x16x32_bf16 v[62:65], v[158:161], v[190:193], v[62:65]
	v_mfma_f32_16x16x32_bf16 v[58:61], v[162:165], v[186:189], v[58:61]
	v_mfma_f32_16x16x32_bf16 v[58:61], v[166:169], v[190:193], v[58:61]
	v_mfma_f32_16x16x32_bf16 v[46:49], v[170:173], v[186:189], v[46:49]
	v_mfma_f32_16x16x32_bf16 v[46:49], v[174:177], v[190:193], v[46:49]
	v_mfma_f32_16x16x32_bf16 v[42:45], v[178:181], v[186:189], v[42:45]
	v_mfma_f32_16x16x32_bf16 v[42:45], v[182:185], v[190:193], v[42:45]
	v_mfma_f32_16x16x32_bf16 v[54:57], v[154:157], v[194:197], v[54:57]
	v_mfma_f32_16x16x32_bf16 v[54:57], v[158:161], v[198:201], v[54:57]
	v_mfma_f32_16x16x32_bf16 v[50:53], v[162:165], v[194:197], v[50:53]
	v_mfma_f32_16x16x32_bf16 v[50:53], v[166:169], v[198:201], v[50:53]
	v_mfma_f32_16x16x32_bf16 v[30:33], v[170:173], v[194:197], v[30:33]
	v_mfma_f32_16x16x32_bf16 v[30:33], v[174:177], v[198:201], v[30:33]
	v_mfma_f32_16x16x32_bf16 v[26:29], v[178:181], v[194:197], v[26:29]
	v_mfma_f32_16x16x32_bf16 v[26:29], v[182:185], v[198:201], v[26:29]
	v_mfma_f32_16x16x32_bf16 v[38:41], v[154:157], v[202:205], v[38:41]
	v_mfma_f32_16x16x32_bf16 v[38:41], v[158:161], v[206:209], v[38:41]
	v_mfma_f32_16x16x32_bf16 v[34:37], v[162:165], v[202:205], v[34:37]
	v_mfma_f32_16x16x32_bf16 v[34:37], v[166:169], v[206:209], v[34:37]
	v_mfma_f32_16x16x32_bf16 v[14:17], v[170:173], v[202:205], v[14:17]
	v_mfma_f32_16x16x32_bf16 v[14:17], v[174:177], v[206:209], v[14:17]
	v_mfma_f32_16x16x32_bf16 v[10:13], v[178:181], v[202:205], v[10:13]
	v_mfma_f32_16x16x32_bf16 v[10:13], v[182:185], v[206:209], v[10:13]
	v_mfma_f32_16x16x32_bf16 v[22:25], v[154:157], v[210:213], v[22:25]
	v_mfma_f32_16x16x32_bf16 v[22:25], v[158:161], v[214:217], v[22:25]
	v_mfma_f32_16x16x32_bf16 v[18:21], v[162:165], v[210:213], v[18:21]
	v_mfma_f32_16x16x32_bf16 v[18:21], v[166:169], v[214:217], v[18:21]
	v_mfma_f32_16x16x32_bf16 v[6:9], v[170:173], v[210:213], v[6:9]
	v_mfma_f32_16x16x32_bf16 v[6:9], v[174:177], v[214:217], v[6:9]
	v_mfma_f32_16x16x32_bf16 v[2:5], v[178:181], v[210:213], v[2:5]
	v_mfma_f32_16x16x32_bf16 v[2:5], v[182:185], v[214:217], v[2:5]
	s_barrier
	s_setprio 0
	s_add_i32 s76, 0, 0x18000
	v_add_u32_e32 v148, s76, v150
	s_add_i32 s77, 0, 0x1c000
	ds_read_b128 v[154:157], v148
	ds_read_b128 v[158:161], v148 offset:1024
	ds_read_b128 v[162:165], v148 offset:2048
	ds_read_b128 v[166:169], v148 offset:3072
	v_add_u32_e32 v148, s77, v150
	ds_read_b128 v[170:173], v148
	ds_read_b128 v[174:177], v148 offset:1024
	ds_read_b128 v[178:181], v148 offset:2048
	ds_read_b128 v[182:185], v148 offset:3072
	s_add_u32 s38, s38, 0x20000
	s_addc_u32 s39, s39, 0
	s_mov_b32 m0, s45
	v_lshl_add_u64 v[222:223], s[38:39], 0, v[134:135]
	ds_read_b128 v[186:189], v147 offset:32768
	ds_read_b128 v[190:193], v147 offset:33792
	ds_read_b128 v[194:197], v147 offset:34816
	ds_read_b128 v[198:201], v147 offset:35840
	ds_read_b128 v[202:205], v147 offset:36864
	ds_read_b128 v[206:209], v147 offset:37888
	ds_read_b128 v[210:213], v147 offset:38912
	ds_read_b128 v[214:217], v147 offset:39936
	global_load_lds_dwordx4 v[222:223], off
	v_lshl_add_u64 v[222:223], s[38:39], 0, v[136:137]
	s_mov_b32 m0, s54
	s_nop 0
	global_load_lds_dwordx4 v[222:223], off
	s_waitcnt vmcnt(8)
	s_waitcnt lgkmcnt(0)
	s_setprio 1
	s_barrier
	v_mfma_f32_16x16x32_bf16 v[126:129], v[154:157], v[186:189], v[126:129]
	v_mfma_f32_16x16x32_bf16 v[126:129], v[158:161], v[190:193], v[126:129]
	v_mfma_f32_16x16x32_bf16 v[122:125], v[162:165], v[186:189], v[122:125]
	v_mfma_f32_16x16x32_bf16 v[122:125], v[166:169], v[190:193], v[122:125]
	v_mfma_f32_16x16x32_bf16 v[110:113], v[170:173], v[186:189], v[110:113]
	v_mfma_f32_16x16x32_bf16 v[110:113], v[174:177], v[190:193], v[110:113]
	v_mfma_f32_16x16x32_bf16 v[106:109], v[178:181], v[186:189], v[106:109]
	v_mfma_f32_16x16x32_bf16 v[106:109], v[182:185], v[190:193], v[106:109]
	v_mfma_f32_16x16x32_bf16 v[118:121], v[154:157], v[194:197], v[118:121]
	v_mfma_f32_16x16x32_bf16 v[118:121], v[158:161], v[198:201], v[118:121]
	v_mfma_f32_16x16x32_bf16 v[114:117], v[162:165], v[194:197], v[114:117]
	v_mfma_f32_16x16x32_bf16 v[114:117], v[166:169], v[198:201], v[114:117]
	v_mfma_f32_16x16x32_bf16 v[94:97], v[170:173], v[194:197], v[94:97]
	v_mfma_f32_16x16x32_bf16 v[94:97], v[174:177], v[198:201], v[94:97]
	v_mfma_f32_16x16x32_bf16 v[90:93], v[178:181], v[194:197], v[90:93]
	v_mfma_f32_16x16x32_bf16 v[90:93], v[182:185], v[198:201], v[90:93]
	v_mfma_f32_16x16x32_bf16 v[102:105], v[154:157], v[202:205], v[102:105]
	v_mfma_f32_16x16x32_bf16 v[102:105], v[158:161], v[206:209], v[102:105]
	v_mfma_f32_16x16x32_bf16 v[98:101], v[162:165], v[202:205], v[98:101]
	v_mfma_f32_16x16x32_bf16 v[98:101], v[166:169], v[206:209], v[98:101]
	v_mfma_f32_16x16x32_bf16 v[78:81], v[170:173], v[202:205], v[78:81]
	v_mfma_f32_16x16x32_bf16 v[78:81], v[174:177], v[206:209], v[78:81]
	v_mfma_f32_16x16x32_bf16 v[74:77], v[178:181], v[202:205], v[74:77]
	v_mfma_f32_16x16x32_bf16 v[74:77], v[182:185], v[206:209], v[74:77]
	v_mfma_f32_16x16x32_bf16 v[86:89], v[154:157], v[210:213], v[86:89]
	v_mfma_f32_16x16x32_bf16 v[86:89], v[158:161], v[214:217], v[86:89]
	v_mfma_f32_16x16x32_bf16 v[82:85], v[162:165], v[210:213], v[82:85]
	v_mfma_f32_16x16x32_bf16 v[82:85], v[166:169], v[214:217], v[82:85]
	v_mfma_f32_16x16x32_bf16 v[70:73], v[170:173], v[210:213], v[70:73]
	v_mfma_f32_16x16x32_bf16 v[70:73], v[174:177], v[214:217], v[70:73]
	v_mfma_f32_16x16x32_bf16 v[66:69], v[178:181], v[210:213], v[66:69]
	v_mfma_f32_16x16x32_bf16 v[66:69], v[182:185], v[214:217], v[66:69]
	s_barrier
; #define PG8_STAGE(bufoff, gbase, voff) do { _Pragma("unroll") for (int _i = 0; _i < 2; ++_i) \
;         __builtin_amdgcn_global_load_lds((const unsigned*)((const char*)(gbase) + (voff)[_i]), (PG8_LAS unsigned*)(lds + (bufoff) + ldsw + _i * 8192), 16, 0, 0); } while (0)
; #define PG8_LDA(dst, b, h) do { _Pragma("unroll") for (int m = 0; m < 4; ++m) _Pragma("unroll") for (int k = 0; k < 2; ++k) dst[m][k] = *(const PG8_LAS bf16x8*)(lds + PG8_SA(b, h) + aoff + m * 2048 + k * 1024); } while (0)
; #define PG8_WAIT_V(n) asm volatile("s_waitcnt vmcnt(" #n ")" ::: "memory")
; #define PG8_WAIT_L(n) asm volatile("s_waitcnt lgkmcnt(" #n ")" ::: "memory")
; #define PG8_BAR __builtin_amdgcn_s_barrier()
; template <class Epi, class Sched, bool ALIGN_EPI = false, bool SP2 = false, bool A_TILED = false>
; __device__ __forceinline__ void gemm_phase(PG8_LAS unsigned char* lds, const Gemm g, const Sched& S, const Epi& E) {
;     ...
;         for (int t = 0; t < nt; t += 2) {
;             const bool last = (t == nt - 2);
;             const char* a1 = cA + (size_t)(t + 1) * kstepA;
;             const char* a2 = last ? nA : cA + (size_t)(t + 2) * kstepA; const char* b2 = last ? nB : cB + (size_t)(t + 2) * kstepB;
;             const char* a3 = a2 + kstepA; const char* b3 = b2 + kstepB;
;             if (last && has_next) S.a_ready(nxt);
;             if constexpr (SP2) {
;             PG8_LDB(B0, 0, 0); PG8_LDB(B1, 0, 1); PG8_SCHED; PG8_LDA(At, 0, 0); PG8_STAGE(PG8_SA(1, 1), a1 + hstepA, voffA);
;             PG8_WAIT_V(8); PG8_WAIT_L(0); PG8_BAR; PG8_MMA(0, 0, At, B0); PG8_MMA(0, 1, At, B1); PG8_BAR; PG8_SCHED;
;             PG8_LDA(At, 0, 1); PG8_STAGE(PG8_SB(0, 0), b2, voffB); PG8_STAGE(PG8_SB(0, 1), b2 + hstepB, voffB); PG8_STAGE(PG8_SA(0, 0), a2, voffA);
;             PG8_WAIT_V(8); PG8_WAIT_L(0); PG8_BAR; PG8_MMA(1, 0, At, B0); PG8_MMA(1, 1, At, B1); PG8_BAR; PG8_SCHED;
;             PG8_LDB(B0, 1, 0); PG8_LDB(B1, 1, 1); PG8_SCHED; PG8_LDA(At, 1, 0); PG8_STAGE(PG8_SA(0, 1), a2 + hstepA, voffA);
;             PG8_WAIT_V(8); PG8_WAIT_L(0); PG8_BAR; PG8_MMA(0, 0, At, B0); PG8_MMA(0, 1, At, B1); PG8_BAR; PG8_SCHED;
;             PG8_LDA(At, 1, 1); PG8_STAGE(PG8_SB(1, 0), b3, voffB); PG8_STAGE(PG8_SB(1, 1), b3 + hstepB, voffB); PG8_STAGE(PG8_SA(1, 0), a3, voffA);
;             PG8_WAIT_V(8); PG8_WAIT_L(0); PG8_BAR; PG8_MMA(1, 0, At, B0); PG8_MMA(1, 1, At, B1); PG8_BAR; PG8_SCHED;
	s_setprio 0
	s_add_u32 s38, s36, 0x8000
	s_addc_u32 s39, s37, 0
	s_add_i32 s76, s76, s43
	v_lshl_add_u64 v[222:223], s[38:39], 0, v[130:131]
	s_mov_b32 m0, s76
	ds_read_b128 v[186:189], v147 offset:49152
	ds_read_b128 v[190:193], v147 offset:50176
	ds_read_b128 v[194:197], v147 offset:51200
	ds_read_b128 v[198:201], v147 offset:52224
	ds_read_b128 v[202:205], v147 offset:53248
	ds_read_b128 v[206:209], v147 offset:54272
	ds_read_b128 v[210:213], v147 offset:55296
	ds_read_b128 v[214:217], v147 offset:56320
	global_load_lds_dwordx4 v[222:223], off
	s_add_i32 m0, s76, 0x2000
	s_add_u32 s36, s36, 0xc000
	v_lshl_add_u64 v[222:223], s[38:39], 0, v[132:133]
	s_addc_u32 s37, s37, 0
	s_add_i32 s38, s77, s43
	global_load_lds_dwordx4 v[222:223], off
	v_lshl_add_u64 v[222:223], s[36:37], 0, v[130:131]
	s_mov_b32 m0, s38
	v_lshl_add_u64 v[218:219], v[218:219], 0, s[10:11]
	global_load_lds_dwordx4 v[222:223], off
	v_lshl_add_u64 v[222:223], s[36:37], 0, v[132:133]
	s_add_i32 m0, s38, 0x2000
	s_nop 0
	global_load_lds_dwordx4 v[222:223], off
	s_mov_b32 m0, s56
	s_nop 0
	global_load_lds_dwordx4 v[218:219], off
	v_lshl_add_u64 v[218:219], v[220:221], 0, s[10:11]
	s_mov_b32 m0, s57
	s_nop 0
	global_load_lds_dwordx4 v[218:219], off
	s_waitcnt vmcnt(8)
	s_waitcnt lgkmcnt(0)
	s_setprio 1
	s_barrier
	v_mfma_f32_16x16x32_bf16 v[62:65], v[154:157], v[186:189], v[62:65]
	v_mfma_f32_16x16x32_bf16 v[62:65], v[158:161], v[190:193], v[62:65]
	v_mfma_f32_16x16x32_bf16 v[58:61], v[162:165], v[186:189], v[58:61]
	v_mfma_f32_16x16x32_bf16 v[58:61], v[166:169], v[190:193], v[58:61]
	v_mfma_f32_16x16x32_bf16 v[46:49], v[170:173], v[186:189], v[46:49]
	v_mfma_f32_16x16x32_bf16 v[46:49], v[174:177], v[190:193], v[46:49]
	v_mfma_f32_16x16x32_bf16 v[42:45], v[178:181], v[186:189], v[42:45]
	v_mfma_f32_16x16x32_bf16 v[42:45], v[182:185], v[190:193], v[42:45]
	v_mfma_f32_16x16x32_bf16 v[54:57], v[154:157], v[194:197], v[54:57]
	v_mfma_f32_16x16x32_bf16 v[54:57], v[158:161], v[198:201], v[54:57]
	v_mfma_f32_16x16x32_bf16 v[50:53], v[162:165], v[194:197], v[50:53]
	v_mfma_f32_16x16x32_bf16 v[50:53], v[166:169], v[198:201], v[50:53]
	v_mfma_f32_16x16x32_bf16 v[30:33], v[170:173], v[194:197], v[30:33]
	v_mfma_f32_16x16x32_bf16 v[30:33], v[174:177], v[198:201], v[30:33]
	v_mfma_f32_16x16x32_bf16 v[26:29], v[178:181], v[194:197], v[26:29]
	v_mfma_f32_16x16x32_bf16 v[26:29], v[182:185], v[198:201], v[26:29]
	v_mfma_f32_16x16x32_bf16 v[38:41], v[154:157], v[202:205], v[38:41]
	v_mfma_f32_16x16x32_bf16 v[38:41], v[158:161], v[206:209], v[38:41]
	v_mfma_f32_16x16x32_bf16 v[34:37], v[162:165], v[202:205], v[34:37]
	v_mfma_f32_16x16x32_bf16 v[34:37], v[166:169], v[206:209], v[34:37]
	v_mfma_f32_16x16x32_bf16 v[14:17], v[170:173], v[202:205], v[14:17]
	v_mfma_f32_16x16x32_bf16 v[14:17], v[174:177], v[206:209], v[14:17]
	v_mfma_f32_16x16x32_bf16 v[10:13], v[178:181], v[202:205], v[10:13]
	v_mfma_f32_16x16x32_bf16 v[10:13], v[182:185], v[206:209], v[10:13]
	v_mfma_f32_16x16x32_bf16 v[22:25], v[154:157], v[210:213], v[22:25]
	v_mfma_f32_16x16x32_bf16 v[22:25], v[158:161], v[214:217], v[22:25]
	v_mfma_f32_16x16x32_bf16 v[18:21], v[162:165], v[210:213], v[18:21]
	v_mfma_f32_16x16x32_bf16 v[18:21], v[166:169], v[214:217], v[18:21]
	v_mfma_f32_16x16x32_bf16 v[6:9], v[170:173], v[210:213], v[6:9]
	v_mfma_f32_16x16x32_bf16 v[6:9], v[174:177], v[214:217], v[6:9]
	v_mfma_f32_16x16x32_bf16 v[2:5], v[178:181], v[210:213], v[2:5]
	v_mfma_f32_16x16x32_bf16 v[2:5], v[182:185], v[214:217], v[2:5]
	s_barrier
	s_setprio 0
	s_add_i32 s75, s75, 2
	s_add_u32 s73, s73, 0x10000
	s_addc_u32 s74, s74, 0
	s_add_u32 s34, s34, 0x100
	s_addc_u32 s35, s35, 0
	s_cmp_gt_u32 s75, 5
	s_cbranch_scc0 .LBB0_873
	s_and_b64 vcc, exec, s[12:13]
	s_cbranch_vccz .LBB0_876
	s_barrier

; #define LAS __attribute__((address_space(3)))
; __device__ __forceinline__ void attn_issue_v(const Frame& F, const unsigned char* vtile, LAS unsigned char* buf) {
;     unsigned lo = F.lane * 16; asm volatile("" : "+v"(lo));
; #pragma unroll
;     for (int j = 0; j < 2; ++j) __builtin_amdgcn_global_load_lds((const unsigned*)(vtile + (size_t)(F.wave * 2 + j) * 1024 + lo), (LAS unsigned*)(buf + (F.wave * 2 + j) * 1024), 16, 0, 0);
; }
.LBB0_1013:
	s_lshl_b32 s89, s89, 14
	s_add_u32 s92, s42, s89
	s_addc_u32 s93, s43, 0
	s_lshl_b32 s89, s75, 14
	s_waitcnt vmcnt(8)
	s_add_i32 s89, s89, 0
	v_mov_b32_e32 v2, v164
	s_waitcnt lgkmcnt(0)
	s_barrier
	s_add_i32 s89, s89, 0x12000
	s_add_i32 m0, s89, s59
	v_lshl_add_u64 v[4:5], s[92:93], 0, v[2:3]
	v_lshl_add_u64 v[6:7], v[4:5], 0, s[14:15]
	global_load_lds_dwordx4 v[6:7], off
	v_lshl_add_u64 v[4:5], v[4:5], 0, s[16:17]
	s_add_i32 m0, s89, s60
	s_cmp_gt_i32 s90, s70
	global_load_lds_dwordx4 v[4:5], off
	s_cbranch_scc1 .LBB0_1015
	s_mul_i32 s89, s0, 0x6000
	v_add_u32_e32 v2, s89, v174
	v_add_u32_e32 v16, s89, v175
	ds_read_b128 v[4:7], v2
	ds_read_b128 v[8:11], v2 offset:12288
	ds_read_b128 v[12:15], v16
	ds_read_b128 v[186:189], v16 offset:12288
	v_add_u32_e32 v17, s89, v176
	v_add_u32_e32 v185, s89, v177
	ds_read_b128 v[190:193], v17
	ds_read_b128 v[194:197], v17 offset:12288
	ds_read_b128 v[198:201], v185
	ds_read_b128 v[202:205], v185 offset:12288
	ds_read_b128 v[206:209], v2 offset:128
	ds_read_b128 v[210:213], v2 offset:12416
	ds_read_b128 v[214:217], v16 offset:128
	ds_read_b128 v[218:221], v16 offset:12416
	s_waitcnt lgkmcnt(8)
	v_mfma_f32_32x32x16_bf16 v[98:113], v[4:7], v[114:117], 0
	v_mfma_f32_32x32x16_bf16 v[98:113], v[12:15], v[118:121], v[98:113]
	v_mfma_f32_32x32x16_bf16 v[82:97], v[8:11], v[114:117], 0
	v_mfma_f32_32x32x16_bf16 v[82:97], v[186:189], v[118:121], v[82:97]
	ds_read_b128 v[4:7], v17 offset:128
	ds_read_b128 v[8:11], v17 offset:12416
	ds_read_b128 v[12:15], v185 offset:128
	ds_read_b128 v[186:189], v185 offset:12416
	s_waitcnt lgkmcnt(8)
	v_mfma_f32_32x32x16_bf16 v[98:113], v[190:193], v[122:125], v[98:113]
	v_mfma_f32_32x32x16_bf16 v[98:113], v[198:201], v[126:129], v[98:113]
	v_mfma_f32_32x32x16_bf16 v[82:97], v[194:197], v[122:125], v[82:97]
	v_mfma_f32_32x32x16_bf16 v[82:97], v[202:205], v[126:129], v[82:97]
	ds_read_b128 v[190:193], v2 offset:256
	ds_read_b128 v[194:197], v2 offset:12544
	ds_read_b128 v[198:201], v16 offset:256
	ds_read_b128 v[202:205], v16 offset:12544
	s_waitcnt lgkmcnt(8)
	v_mfma_f32_32x32x16_bf16 v[98:113], v[206:209], v[130:133], v[98:113]
	v_mfma_f32_32x32x16_bf16 v[98:113], v[214:217], v[134:137], v[98:113]
	v_mfma_f32_32x32x16_bf16 v[82:97], v[210:213], v[130:133], v[82:97]
	v_mfma_f32_32x32x16_bf16 v[82:97], v[218:221], v[134:137], v[82:97]
	ds_read_b128 v[206:209], v17 offset:256
	ds_read_b128 v[210:213], v17 offset:12544
	ds_read_b128 v[214:217], v185 offset:256
	ds_read_b128 v[218:221], v185 offset:12544
	s_waitcnt lgkmcnt(8)
	v_mfma_f32_32x32x16_bf16 v[98:113], v[4:7], v[138:141], v[98:113]
	v_mfma_f32_32x32x16_bf16 v[98:113], v[12:15], v[142:145], v[98:113]
	v_mfma_f32_32x32x16_bf16 v[82:97], v[8:11], v[138:141], v[82:97]
	v_mfma_f32_32x32x16_bf16 v[82:97], v[186:189], v[142:145], v[82:97]
	s_waitcnt lgkmcnt(4)
	v_mfma_f32_32x32x16_bf16 v[98:113], v[190:193], v[146:149], v[98:113]
	v_mfma_f32_32x32x16_bf16 v[98:113], v[198:201], v[154:157], v[98:113]
	v_mfma_f32_32x32x16_bf16 v[82:97], v[194:197], v[146:149], v[82:97]
	v_mfma_f32_32x32x16_bf16 v[82:97], v[202:205], v[154:157], v[82:97]
	s_waitcnt lgkmcnt(0)
	v_mfma_f32_32x32x16_bf16 v[98:113], v[206:209], v[150:153], v[98:113]
	v_mfma_f32_32x32x16_bf16 v[98:113], v[214:217], v[158:161], v[98:113]
	v_mfma_f32_32x32x16_bf16 v[82:97], v[210:213], v[150:153], v[82:97]
	v_mfma_f32_32x32x16_bf16 v[82:97], v[218:221], v[158:161], v[82:97]
	s_branch .LBB0_1016

; #define LAS __attribute__((address_space(3)))
; __device__ __forceinline__ void attn_issue_k(const Frame& F, const unsigned char* ktile, LAS unsigned char* buf) {
;     unsigned lo = F.lane * 16; asm volatile("" : "+v"(lo));
; #pragma unroll
;     for (int j = 0; j < 3; ++j) __builtin_amdgcn_global_load_lds((const unsigned*)(ktile + (size_t)(F.wave * 3 + j) * 1024 + lo), (LAS unsigned*)(buf + (F.wave * 3 + j) * 1024), 16, 0, 0);
; }
.LBB0_1027:
	s_min_u32 s75, s33, s45
	s_mul_i32 s0, s75, 0x6000
	s_add_u32 s0, s40, s0
	s_addc_u32 s1, s41, 0
	s_mul_i32 s88, s74, 0x6000
	v_mov_b32_e32 v2, v164
	s_add_i32 s88, s88, 0
	s_add_i32 m0, s88, s56
	v_lshl_add_u64 v[4:5], s[0:1], 0, v[2:3]
	v_lshl_add_u64 v[6:7], v[4:5], 0, s[8:9]
	global_load_lds_dwordx4 v[6:7], off
	v_lshl_add_u64 v[6:7], v[4:5], 0, s[10:11]
	s_add_i32 m0, s88, s57
	v_lshl_add_u64 v[4:5], v[4:5], 0, s[12:13]
	global_load_lds_dwordx4 v[6:7], off
	s_add_i32 m0, s88, s58
	s_cmp_le_u32 s72, s70
	global_load_lds_dwordx4 v[4:5], off
	s_cselect_b64 s[0:1], -1, 0
	s_cmp_gt_u32 s72, s70
	s_cbranch_scc1 .LBB0_1029
	s_mul_i32 s88, s73, 0x6000
	v_add_u32_e32 v2, s88, v174
	v_add_u32_e32 v16, s88, v175
	ds_read_b128 v[4:7], v2
	ds_read_b128 v[8:11], v2 offset:12288
	ds_read_b128 v[12:15], v16
	ds_read_b128 v[180:183], v16 offset:12288
	v_add_u32_e32 v17, s88, v176
	v_add_u32_e32 v179, s88, v177
	ds_read_b128 v[184:187], v17
	ds_read_b128 v[188:191], v17 offset:12288
	ds_read_b128 v[192:195], v179
	ds_read_b128 v[196:199], v179 offset:12288
	ds_read_b128 v[200:203], v2 offset:128
	ds_read_b128 v[204:207], v2 offset:12416
	ds_read_b128 v[208:211], v16 offset:128
	ds_read_b128 v[212:215], v16 offset:12416
	s_waitcnt lgkmcnt(8)
	v_mfma_f32_32x32x16_bf16 v[98:113], v[4:7], v[114:117], 0
	v_mfma_f32_32x32x16_bf16 v[98:113], v[12:15], v[118:121], v[98:113]
	v_mfma_f32_32x32x16_bf16 v[82:97], v[8:11], v[114:117], 0
	v_mfma_f32_32x32x16_bf16 v[82:97], v[180:183], v[118:121], v[82:97]
	ds_read_b128 v[4:7], v17 offset:128
	ds_read_b128 v[8:11], v17 offset:12416
	ds_read_b128 v[12:15], v179 offset:128
	ds_read_b128 v[180:183], v179 offset:12416
	s_waitcnt lgkmcnt(8)
	v_mfma_f32_32x32x16_bf16 v[98:113], v[184:187], v[122:125], v[98:113]
	v_mfma_f32_32x32x16_bf16 v[98:113], v[192:195], v[126:129], v[98:113]
	v_mfma_f32_32x32x16_bf16 v[82:97], v[188:191], v[122:125], v[82:97]
	v_mfma_f32_32x32x16_bf16 v[82:97], v[196:199], v[126:129], v[82:97]
	ds_read_b128 v[184:187], v2 offset:256
	ds_read_b128 v[188:191], v2 offset:12544
	ds_read_b128 v[192:195], v16 offset:256
	ds_read_b128 v[196:199], v16 offset:12544
	s_waitcnt lgkmcnt(8)
	v_mfma_f32_32x32x16_bf16 v[98:113], v[200:203], v[130:133], v[98:113]
	v_mfma_f32_32x32x16_bf16 v[98:113], v[208:211], v[134:137], v[98:113]
	v_mfma_f32_32x32x16_bf16 v[82:97], v[204:207], v[130:133], v[82:97]
	v_mfma_f32_32x32x16_bf16 v[82:97], v[212:215], v[134:137], v[82:97]
	ds_read_b128 v[200:203], v17 offset:256
	ds_read_b128 v[204:207], v17 offset:12544
	ds_read_b128 v[208:211], v179 offset:256
	ds_read_b128 v[212:215], v179 offset:12544
	s_waitcnt lgkmcnt(8)
	v_mfma_f32_32x32x16_bf16 v[98:113], v[4:7], v[138:141], v[98:113]
	v_mfma_f32_32x32x16_bf16 v[98:113], v[12:15], v[142:145], v[98:113]
	v_mfma_f32_32x32x16_bf16 v[82:97], v[8:11], v[138:141], v[82:97]
	v_mfma_f32_32x32x16_bf16 v[82:97], v[180:183], v[142:145], v[82:97]
	s_waitcnt lgkmcnt(4)
	v_mfma_f32_32x32x16_bf16 v[98:113], v[184:187], v[146:149], v[98:113]
	v_mfma_f32_32x32x16_bf16 v[98:113], v[192:195], v[154:157], v[98:113]
	v_mfma_f32_32x32x16_bf16 v[82:97], v[188:191], v[146:149], v[82:97]
	v_mfma_f32_32x32x16_bf16 v[82:97], v[196:199], v[154:157], v[82:97]
	s_waitcnt lgkmcnt(0)
	v_mfma_f32_32x32x16_bf16 v[98:113], v[200:203], v[150:153], v[98:113]
	v_mfma_f32_32x32x16_bf16 v[98:113], v[208:211], v[158:161], v[98:113]
	v_mfma_f32_32x32x16_bf16 v[82:97], v[204:207], v[150:153], v[82:97]
	v_mfma_f32_32x32x16_bf16 v[82:97], v[212:215], v[158:161], v[82:97]
	s_branch .LBB0_1030

; #define PG8_STAGE(bufoff, gbase, voff) do { _Pragma("unroll") for (int _i = 0; _i < 2; ++_i) \
;         __builtin_amdgcn_global_load_lds((const unsigned*)((const char*)(gbase) + (voff)[_i]), (PG8_LAS unsigned*)(lds + (bufoff) + ldsw + _i * 8192), 16, 0, 0); } while (0)
; #define PG8_LDA(dst, b, h) do { _Pragma("unroll") for (int m = 0; m < 4; ++m) _Pragma("unroll") for (int k = 0; k < 2; ++k) dst[m][k] = *(const PG8_LAS bf16x8*)(lds + PG8_SA(b, h) + aoff + m * 2048 + k * 1024); } while (0)
; #define PG8_WAIT_V(n) asm volatile("s_waitcnt vmcnt(" #n ")" ::: "memory")
; #define PG8_WAIT_L(n) asm volatile("s_waitcnt lgkmcnt(" #n ")" ::: "memory")
; #define PG8_BAR __builtin_amdgcn_s_barrier()
; template <class Epi, class Sched, bool ALIGN_EPI = false, bool SP2 = false, bool A_TILED = false>
; __device__ __forceinline__ void gemm_phase(PG8_LAS unsigned char* lds, const Gemm g, const Sched& S, const Epi& E) {
;     ...
;         for (int t = 0; t < nt; t += 2) {
;             const bool last = (t == nt - 2);
;             const char* a1 = cA + (size_t)(t + 1) * kstepA;
;             const char* a2 = last ? nA : cA + (size_t)(t + 2) * kstepA; const char* b2 = last ? nB : cB + (size_t)(t + 2) * kstepB;
;             const char* a3 = a2 + kstepA; const char* b3 = b2 + kstepB;
;             if (last && has_next) S.a_ready(nxt);
;             if constexpr (SP2) {
;             PG8_LDB(B0, 0, 0); PG8_LDB(B1, 0, 1); PG8_SCHED; PG8_LDA(At, 0, 0); PG8_STAGE(PG8_SA(1, 1), a1 + hstepA, voffA);
;             PG8_WAIT_V(8); PG8_WAIT_L(0); PG8_BAR; PG8_MMA(0, 0, At, B0); PG8_MMA(0, 1, At, B1); PG8_BAR; PG8_SCHED;
;             PG8_LDA(At, 0, 1); PG8_STAGE(PG8_SB(0, 0), b2, voffB); PG8_STAGE(PG8_SB(0, 1), b2 + hstepB, voffB); PG8_STAGE(PG8_SA(0, 0), a2, voffA);
;             PG8_WAIT_V(8); PG8_WAIT_L(0); PG8_BAR; PG8_MMA(1, 0, At, B0); PG8_MMA(1, 1, At, B1); PG8_BAR; PG8_SCHED;
;             PG8_LDB(B0, 1, 0); PG8_LDB(B1, 1, 1); PG8_SCHED; PG8_LDA(At, 1, 0); PG8_STAGE(PG8_SA(0, 1), a2 + hstepA, voffA);
;             PG8_WAIT_V(8); PG8_WAIT_L(0); PG8_BAR; PG8_MMA(0, 0, At, B0); PG8_MMA(0, 1, At, B1); PG8_BAR; PG8_SCHED;
;             PG8_LDA(At, 1, 1); PG8_STAGE(PG8_SB(1, 0), b3, voffB); PG8_STAGE(PG8_SB(1, 1), b3 + hstepB, voffB); PG8_STAGE(PG8_SA(1, 0), a3, voffA);
;             PG8_WAIT_V(8); PG8_WAIT_L(0); PG8_BAR; PG8_MMA(1, 0, At, B0); PG8_MMA(1, 1, At, B1); PG8_BAR; PG8_SCHED;
.LBB0_1103:
	ds_read_b128 v[130:133], v197
	ds_read_b128 v[134:137], v197 offset:1024
	ds_read_b128 v[138:141], v197 offset:2048
	ds_read_b128 v[142:145], v197 offset:3072
	ds_read_b128 v[146:149], v237
	ds_read_b128 v[150:153], v237 offset:1024
	ds_read_b128 v[154:157], v237 offset:2048
	ds_read_b128 v[158:161], v237 offset:3072
	s_add_u32 s40, s38, 0xfff00080
	s_addc_u32 s41, s39, -1
	s_cmp_eq_u32 s72, 60
	s_cselect_b32 s43, s29, s41
	s_cselect_b32 s42, s37, s40
	s_cselect_b32 s41, s27, s71
	s_cselect_b32 s40, s69, s70
	v_lshl_add_u64 v[228:229], s[38:39], 0, v[214:215]
	s_add_i32 m0, s55, 0xc000
	ds_read_b128 v[162:165], v238
	ds_read_b128 v[166:169], v238 offset:1024
	ds_read_b128 v[170:173], v238 offset:2048
	ds_read_b128 v[174:177], v238 offset:3072
	ds_read_b128 v[178:181], v238 offset:4096
	ds_read_b128 v[182:185], v238 offset:5120
	ds_read_b128 v[220:223], v238 offset:6144
	ds_read_b128 v[224:227], v238 offset:7168
	global_load_lds_dwordx4 v[228:229], off
	v_lshl_add_u64 v[228:229], s[38:39], 0, v[216:217]
	s_add_i32 m0, s55, 0xe000
	s_nop 0
	global_load_lds_dwordx4 v[228:229], off
	s_waitcnt vmcnt(8)
	s_waitcnt lgkmcnt(0)
	s_barrier
	s_setprio 1
	s_waitcnt lgkmcnt(0)
	v_mfma_f32_16x16x32_bf16 v[90:93], v[130:133], v[162:165], v[90:93]
	v_mfma_f32_16x16x32_bf16 v[98:101], v[138:141], v[162:165], v[98:101]
	v_mfma_f32_16x16x32_bf16 v[122:125], v[130:133], v[170:173], v[122:125]
	v_mfma_f32_16x16x32_bf16 v[126:129], v[138:141], v[170:173], v[126:129]
	v_mfma_f32_16x16x32_bf16 v[102:105], v[130:133], v[178:181], v[102:105]
	v_mfma_f32_16x16x32_bf16 v[94:97], v[138:141], v[178:181], v[94:97]
	v_mfma_f32_16x16x32_bf16 v[78:81], v[130:133], v[220:223], v[78:81]
	v_mfma_f32_16x16x32_bf16 v[74:77], v[138:141], v[220:223], v[74:77]
	v_mfma_f32_16x16x32_bf16 v[90:93], v[134:137], v[166:169], v[90:93]
	v_mfma_f32_16x16x32_bf16 v[98:101], v[142:145], v[166:169], v[98:101]
	v_mfma_f32_16x16x32_bf16 v[122:125], v[134:137], v[174:177], v[122:125]
	v_mfma_f32_16x16x32_bf16 v[126:129], v[142:145], v[174:177], v[126:129]
	v_mfma_f32_16x16x32_bf16 v[102:105], v[134:137], v[182:185], v[102:105]
	v_mfma_f32_16x16x32_bf16 v[94:97], v[142:145], v[182:185], v[94:97]
	v_mfma_f32_16x16x32_bf16 v[78:81], v[134:137], v[224:227], v[78:81]
	v_mfma_f32_16x16x32_bf16 v[74:77], v[142:145], v[224:227], v[74:77]
	s_setprio 0
	s_setprio 1
	v_mfma_f32_16x16x32_bf16 v[106:109], v[146:149], v[162:165], v[106:109]
	v_mfma_f32_16x16x32_bf16 v[114:117], v[154:157], v[162:165], v[114:117]
	v_mfma_f32_16x16x32_bf16 v[118:121], v[146:149], v[170:173], v[118:121]
	v_mfma_f32_16x16x32_bf16 v[110:113], v[154:157], v[170:173], v[110:113]
	v_mfma_f32_16x16x32_bf16 v[86:89], v[146:149], v[178:181], v[86:89]
	v_mfma_f32_16x16x32_bf16 v[82:85], v[154:157], v[178:181], v[82:85]
	v_mfma_f32_16x16x32_bf16 v[70:73], v[146:149], v[220:223], v[70:73]
	v_mfma_f32_16x16x32_bf16 v[66:69], v[154:157], v[220:223], v[66:69]
	v_mfma_f32_16x16x32_bf16 v[106:109], v[150:153], v[166:169], v[106:109]
	v_mfma_f32_16x16x32_bf16 v[114:117], v[158:161], v[166:169], v[114:117]
	v_mfma_f32_16x16x32_bf16 v[118:121], v[150:153], v[174:177], v[118:121]
	v_mfma_f32_16x16x32_bf16 v[110:113], v[158:161], v[174:177], v[110:113]
	v_mfma_f32_16x16x32_bf16 v[86:89], v[150:153], v[182:185], v[86:89]
	v_mfma_f32_16x16x32_bf16 v[82:85], v[158:161], v[182:185], v[82:85]
	v_mfma_f32_16x16x32_bf16 v[70:73], v[150:153], v[224:227], v[70:73]
	v_mfma_f32_16x16x32_bf16 v[66:69], v[158:161], v[224:227], v[66:69]
	s_setprio 0
	s_barrier
	s_add_i32 s73, s66, s54
	v_lshl_add_u64 v[228:229], s[40:41], 0, v[188:189]
	s_mov_b32 m0, s73
	ds_read_b128 v[162:165], v238 offset:16384
	ds_read_b128 v[166:169], v238 offset:17408
	ds_read_b128 v[170:173], v238 offset:18432
	ds_read_b128 v[174:177], v238 offset:19456
	ds_read_b128 v[178:181], v238 offset:20480
	ds_read_b128 v[182:185], v238 offset:21504
	ds_read_b128 v[220:223], v238 offset:22528
	ds_read_b128 v[224:227], v238 offset:23552
	global_load_lds_dwordx4 v[228:229], off
	s_add_i32 m0, s73, 0x2000
	s_add_u32 s74, s40, 0x4000
	v_lshl_add_u64 v[228:229], s[40:41], 0, v[192:193]
	s_addc_u32 s75, s41, 0
	s_add_i32 s73, s67, s54
	global_load_lds_dwordx4 v[228:229], off
	v_lshl_add_u64 v[228:229], s[74:75], 0, v[188:189]
	s_mov_b32 m0, s73
	v_lshl_add_u64 v[230:231], s[42:43], 0, v[190:191]
	global_load_lds_dwordx4 v[228:229], off
	v_lshl_add_u64 v[228:229], s[74:75], 0, v[192:193]
	s_add_i32 m0, s73, 0x2000
	s_nop 0
	global_load_lds_dwordx4 v[228:229], off
	v_lshl_add_u64 v[228:229], s[42:43], 0, v[186:187]
	s_mov_b32 m0, s55
	s_nop 0
	global_load_lds_dwordx4 v[228:229], off
	s_mov_b32 m0, s56
	s_nop 0
	global_load_lds_dwordx4 v[230:231], off
	s_waitcnt vmcnt(8)
	s_waitcnt lgkmcnt(0)
	s_setprio 1
	s_barrier
; #define PG8_STAGE(bufoff, gbase, voff) do { _Pragma("unroll") for (int _i = 0; _i < 2; ++_i) \
;         __builtin_amdgcn_global_load_lds((const unsigned*)((const char*)(gbase) + (voff)[_i]), (PG8_LAS unsigned*)(lds + (bufoff) + ldsw + _i * 8192), 16, 0, 0); } while (0)
; #define PG8_LDA(dst, b, h) do { _Pragma("unroll") for (int m = 0; m < 4; ++m) _Pragma("unroll") for (int k = 0; k < 2; ++k) dst[m][k] = *(const PG8_LAS bf16x8*)(lds + PG8_SA(b, h) + aoff + m * 2048 + k * 1024); } while (0)
; #define PG8_LDB(dst, b, h) do { _Pragma("unroll") for (int n = 0; n < 2; ++n) _Pragma("unroll") for (int k = 0; k < 2; ++k) dst[n][k] = *(const PG8_LAS bf16x8*)(lds + PG8_SB(b, h) + boff + n * 2048 + k * 1024); } while (0)
; #define PG8_MMA(ai, bj, At, Bt) do { __builtin_amdgcn_s_setprio(1); _Pragma("unroll") for (int m = 0; m < 4; ++m) _Pragma("unroll") for (int n = 0; n < 2; ++n) _Pragma("unroll") for (int k = 0; k < 2; ++k) \
;         acc[ai][bj][m][n] = __builtin_amdgcn_mfma_f32_16x16x32_bf16(Bt[n][k], At[m][k], acc[ai][bj][m][n], 0, 0, 0); __builtin_amdgcn_s_setprio(0); } while (0)
; #define PG8_WAIT_V(n) asm volatile("s_waitcnt vmcnt(" #n ")" ::: "memory")
; #define PG8_WAIT_L(n) asm volatile("s_waitcnt lgkmcnt(" #n ")" ::: "memory")
; #define PG8_BAR __builtin_amdgcn_s_barrier()
; #define PG8_SCHED __builtin_amdgcn_sched_barrier(0)
; template <class Epi, class Sched, bool ALIGN_EPI = false, bool SP2 = false, bool A_TILED = false>
; __device__ __forceinline__ void gemm_phase(PG8_LAS unsigned char* lds, const Gemm g, const Sched& S, const Epi& E) {
;     ...
;             PG8_WAIT_V(8); PG8_WAIT_L(0); PG8_BAR; PG8_MMA(1, 0, At, B0); PG8_MMA(1, 1, At, B1); PG8_BAR; PG8_SCHED;
;             PG8_LDB(B0, 1, 0); PG8_LDB(B1, 1, 1); PG8_SCHED; PG8_LDA(At, 1, 0); PG8_STAGE(PG8_SA(0, 1), a2 + hstepA, voffA);
;             PG8_WAIT_V(8); PG8_WAIT_L(0); PG8_BAR; PG8_MMA(0, 0, At, B0); PG8_MMA(0, 1, At, B1); PG8_BAR; PG8_SCHED;
	v_mfma_f32_16x16x32_bf16 v[62:65], v[130:133], v[162:165], v[62:65]
	v_mfma_f32_16x16x32_bf16 v[62:65], v[134:137], v[166:169], v[62:65]
	v_mfma_f32_16x16x32_bf16 v[58:61], v[138:141], v[162:165], v[58:61]
	v_mfma_f32_16x16x32_bf16 v[58:61], v[142:145], v[166:169], v[58:61]
	v_mfma_f32_16x16x32_bf16 v[54:57], v[146:149], v[162:165], v[54:57]
	v_mfma_f32_16x16x32_bf16 v[54:57], v[150:153], v[166:169], v[54:57]
	v_mfma_f32_16x16x32_bf16 v[50:53], v[154:157], v[162:165], v[50:53]
	v_mfma_f32_16x16x32_bf16 v[50:53], v[158:161], v[166:169], v[50:53]
	v_mfma_f32_16x16x32_bf16 v[46:49], v[130:133], v[170:173], v[46:49]
	v_mfma_f32_16x16x32_bf16 v[46:49], v[134:137], v[174:177], v[46:49]
	v_mfma_f32_16x16x32_bf16 v[42:45], v[138:141], v[170:173], v[42:45]
	v_mfma_f32_16x16x32_bf16 v[42:45], v[142:145], v[174:177], v[42:45]
	v_mfma_f32_16x16x32_bf16 v[38:41], v[146:149], v[170:173], v[38:41]
	v_mfma_f32_16x16x32_bf16 v[38:41], v[150:153], v[174:177], v[38:41]
	v_mfma_f32_16x16x32_bf16 v[34:37], v[154:157], v[170:173], v[34:37]
	v_mfma_f32_16x16x32_bf16 v[34:37], v[158:161], v[174:177], v[34:37]
	v_mfma_f32_16x16x32_bf16 v[30:33], v[130:133], v[178:181], v[30:33]
	v_mfma_f32_16x16x32_bf16 v[30:33], v[134:137], v[182:185], v[30:33]
	v_mfma_f32_16x16x32_bf16 v[26:29], v[138:141], v[178:181], v[26:29]
	v_mfma_f32_16x16x32_bf16 v[26:29], v[142:145], v[182:185], v[26:29]
	v_mfma_f32_16x16x32_bf16 v[22:25], v[146:149], v[178:181], v[22:25]
	v_mfma_f32_16x16x32_bf16 v[22:25], v[150:153], v[182:185], v[22:25]
	v_mfma_f32_16x16x32_bf16 v[18:21], v[154:157], v[178:181], v[18:21]
	v_mfma_f32_16x16x32_bf16 v[18:21], v[158:161], v[182:185], v[18:21]
	v_mfma_f32_16x16x32_bf16 v[14:17], v[130:133], v[220:223], v[14:17]
	v_mfma_f32_16x16x32_bf16 v[14:17], v[134:137], v[224:227], v[14:17]
	v_mfma_f32_16x16x32_bf16 v[10:13], v[138:141], v[220:223], v[10:13]
	v_mfma_f32_16x16x32_bf16 v[10:13], v[142:145], v[224:227], v[10:13]
	v_mfma_f32_16x16x32_bf16 v[6:9], v[146:149], v[220:223], v[6:9]
	v_mfma_f32_16x16x32_bf16 v[6:9], v[150:153], v[224:227], v[6:9]
	v_mfma_f32_16x16x32_bf16 v[2:5], v[154:157], v[220:223], v[2:5]
	v_mfma_f32_16x16x32_bf16 v[2:5], v[158:161], v[224:227], v[2:5]
	s_barrier
	s_setprio 0
	s_add_i32 s73, 0, 0x18000
	s_add_i32 s74, 0, 0x1c000
	v_add_u32_e32 v142, s73, v1
	v_add_u32_e32 v158, s74, v1
	ds_read_b128 v[130:133], v142
	ds_read_b128 v[134:137], v142 offset:1024
	ds_read_b128 v[138:141], v142 offset:2048
	ds_read_b128 v[142:145], v142 offset:3072
	ds_read_b128 v[146:149], v158
	ds_read_b128 v[150:153], v158 offset:1024
	ds_read_b128 v[154:157], v158 offset:2048
	ds_read_b128 v[158:161], v158 offset:3072
	s_add_u32 s42, s42, 0x100000
	s_addc_u32 s43, s43, 0
	s_mov_b32 m0, s57
	v_lshl_add_u64 v[232:233], s[42:43], 0, v[186:187]
	ds_read_b128 v[162:165], v238 offset:32768
	ds_read_b128 v[166:169], v238 offset:33792
	ds_read_b128 v[170:173], v238 offset:34816
	ds_read_b128 v[174:177], v238 offset:35840
	ds_read_b128 v[178:181], v238 offset:36864
	ds_read_b128 v[182:185], v238 offset:37888
	ds_read_b128 v[220:223], v238 offset:38912
	ds_read_b128 v[224:227], v238 offset:39936
	global_load_lds_dwordx4 v[232:233], off
	v_lshl_add_u64 v[232:233], s[42:43], 0, v[190:191]
	s_mov_b32 m0, s58
	s_nop 0
	global_load_lds_dwordx4 v[232:233], off
	s_waitcnt vmcnt(8)
	s_waitcnt lgkmcnt(0)
	s_setprio 1
	s_barrier
	v_mfma_f32_16x16x32_bf16 v[90:93], v[130:133], v[162:165], v[90:93]
	v_mfma_f32_16x16x32_bf16 v[90:93], v[134:137], v[166:169], v[90:93]
	v_mfma_f32_16x16x32_bf16 v[98:101], v[138:141], v[162:165], v[98:101]
	v_mfma_f32_16x16x32_bf16 v[98:101], v[142:145], v[166:169], v[98:101]
	v_mfma_f32_16x16x32_bf16 v[106:109], v[146:149], v[162:165], v[106:109]
	v_mfma_f32_16x16x32_bf16 v[106:109], v[150:153], v[166:169], v[106:109]
	v_mfma_f32_16x16x32_bf16 v[114:117], v[154:157], v[162:165], v[114:117]
	v_mfma_f32_16x16x32_bf16 v[114:117], v[158:161], v[166:169], v[114:117]
	v_mfma_f32_16x16x32_bf16 v[122:125], v[130:133], v[170:173], v[122:125]
	v_mfma_f32_16x16x32_bf16 v[122:125], v[134:137], v[174:177], v[122:125]
	v_mfma_f32_16x16x32_bf16 v[126:129], v[138:141], v[170:173], v[126:129]
	v_mfma_f32_16x16x32_bf16 v[126:129], v[142:145], v[174:177], v[126:129]
	v_mfma_f32_16x16x32_bf16 v[118:121], v[146:149], v[170:173], v[118:121]
	v_mfma_f32_16x16x32_bf16 v[118:121], v[150:153], v[174:177], v[118:121]
	v_mfma_f32_16x16x32_bf16 v[110:113], v[154:157], v[170:173], v[110:113]
	v_mfma_f32_16x16x32_bf16 v[110:113], v[158:161], v[174:177], v[110:113]
	v_mfma_f32_16x16x32_bf16 v[102:105], v[130:133], v[178:181], v[102:105]
	v_mfma_f32_16x16x32_bf16 v[102:105], v[134:137], v[182:185], v[102:105]
	v_mfma_f32_16x16x32_bf16 v[94:97], v[138:141], v[178:181], v[94:97]
	v_mfma_f32_16x16x32_bf16 v[94:97], v[142:145], v[182:185], v[94:97]
	v_mfma_f32_16x16x32_bf16 v[86:89], v[146:149], v[178:181], v[86:89]
	v_mfma_f32_16x16x32_bf16 v[86:89], v[150:153], v[182:185], v[86:89]
	v_mfma_f32_16x16x32_bf16 v[82:85], v[154:157], v[178:181], v[82:85]
	v_mfma_f32_16x16x32_bf16 v[82:85], v[158:161], v[182:185], v[82:85]
	v_mfma_f32_16x16x32_bf16 v[78:81], v[130:133], v[220:223], v[78:81]
	v_mfma_f32_16x16x32_bf16 v[78:81], v[134:137], v[224:227], v[78:81]
	v_mfma_f32_16x16x32_bf16 v[74:77], v[138:141], v[220:223], v[74:77]
	v_mfma_f32_16x16x32_bf16 v[74:77], v[142:145], v[224:227], v[74:77]
	v_mfma_f32_16x16x32_bf16 v[70:73], v[146:149], v[220:223], v[70:73]
	v_mfma_f32_16x16x32_bf16 v[70:73], v[150:153], v[224:227], v[70:73]
	v_mfma_f32_16x16x32_bf16 v[66:69], v[154:157], v[220:223], v[66:69]
	v_mfma_f32_16x16x32_bf16 v[66:69], v[158:161], v[224:227], v[66:69]
	s_barrier
; #define PG8_STAGE(bufoff, gbase, voff) do { _Pragma("unroll") for (int _i = 0; _i < 2; ++_i) \
;         __builtin_amdgcn_global_load_lds((const unsigned*)((const char*)(gbase) + (voff)[_i]), (PG8_LAS unsigned*)(lds + (bufoff) + ldsw + _i * 8192), 16, 0, 0); } while (0)
; #define PG8_LDA(dst, b, h) do { _Pragma("unroll") for (int m = 0; m < 4; ++m) _Pragma("unroll") for (int k = 0; k < 2; ++k) dst[m][k] = *(const PG8_LAS bf16x8*)(lds + PG8_SA(b, h) + aoff + m * 2048 + k * 1024); } while (0)
; #define PG8_MMA(ai, bj, At, Bt) do { __builtin_amdgcn_s_setprio(1); _Pragma("unroll") for (int m = 0; m < 4; ++m) _Pragma("unroll") for (int n = 0; n < 2; ++n) _Pragma("unroll") for (int k = 0; k < 2; ++k) \
;         acc[ai][bj][m][n] = __builtin_amdgcn_mfma_f32_16x16x32_bf16(Bt[n][k], At[m][k], acc[ai][bj][m][n], 0, 0, 0); __builtin_amdgcn_s_setprio(0); } while (0)
; #define PG8_WAIT_V(n) asm volatile("s_waitcnt vmcnt(" #n ")" ::: "memory")
; #define PG8_WAIT_L(n) asm volatile("s_waitcnt lgkmcnt(" #n ")" ::: "memory")
; #define PG8_BAR __builtin_amdgcn_s_barrier()
; #define PG8_SCHED __builtin_amdgcn_sched_barrier(0)
; template <class Epi, class Sched, bool ALIGN_EPI = false, bool SP2 = false, bool A_TILED = false>
; __device__ __forceinline__ void gemm_phase(PG8_LAS unsigned char* lds, const Gemm g, const Sched& S, const Epi& E) {
;     ...
;             PG8_LDA(At, 1, 1); PG8_STAGE(PG8_SB(1, 0), b3, voffB); PG8_STAGE(PG8_SB(1, 1), b3 + hstepB, voffB); PG8_STAGE(PG8_SA(1, 0), a3, voffA);
;             PG8_WAIT_V(8); PG8_WAIT_L(0); PG8_BAR; PG8_MMA(1, 0, At, B0); PG8_MMA(1, 1, At, B1); PG8_BAR; PG8_SCHED;
	s_setprio 0
	s_add_u32 s42, s40, 0x8000
	s_addc_u32 s43, s41, 0
	s_add_i32 s73, s73, s54
	v_lshl_add_u64 v[232:233], s[42:43], 0, v[188:189]
	s_mov_b32 m0, s73
	ds_read_b128 v[162:165], v238 offset:49152
	ds_read_b128 v[166:169], v238 offset:50176
	ds_read_b128 v[170:173], v238 offset:51200
	ds_read_b128 v[174:177], v238 offset:52224
	ds_read_b128 v[178:181], v238 offset:53248
	ds_read_b128 v[182:185], v238 offset:54272
	ds_read_b128 v[220:223], v238 offset:55296
	ds_read_b128 v[224:227], v238 offset:56320
	global_load_lds_dwordx4 v[232:233], off
	s_add_i32 m0, s73, 0x2000
	s_add_u32 s40, s40, 0xc000
	v_lshl_add_u64 v[232:233], s[42:43], 0, v[192:193]
	s_addc_u32 s41, s41, 0
	s_add_i32 s42, s74, s54
	global_load_lds_dwordx4 v[232:233], off
	v_lshl_add_u64 v[232:233], s[40:41], 0, v[188:189]
	s_mov_b32 m0, s42
	v_lshl_add_u64 v[228:229], v[228:229], 0, s[12:13]
	global_load_lds_dwordx4 v[232:233], off
	v_lshl_add_u64 v[232:233], s[40:41], 0, v[192:193]
	s_add_i32 m0, s42, 0x2000
	s_nop 0
	global_load_lds_dwordx4 v[232:233], off
	s_mov_b32 m0, s61
	s_nop 0
	global_load_lds_dwordx4 v[228:229], off
	v_lshl_add_u64 v[228:229], v[230:231], 0, s[12:13]
	s_mov_b32 m0, s62
	s_nop 0
	global_load_lds_dwordx4 v[228:229], off
	s_waitcnt vmcnt(8)
	s_waitcnt lgkmcnt(0)
	s_setprio 1
	s_barrier
	v_mfma_f32_16x16x32_bf16 v[62:65], v[130:133], v[162:165], v[62:65]
	v_mfma_f32_16x16x32_bf16 v[62:65], v[134:137], v[166:169], v[62:65]
	v_mfma_f32_16x16x32_bf16 v[58:61], v[138:141], v[162:165], v[58:61]
	v_mfma_f32_16x16x32_bf16 v[58:61], v[142:145], v[166:169], v[58:61]
	v_mfma_f32_16x16x32_bf16 v[54:57], v[146:149], v[162:165], v[54:57]
	v_mfma_f32_16x16x32_bf16 v[54:57], v[150:153], v[166:169], v[54:57]
	v_mfma_f32_16x16x32_bf16 v[50:53], v[154:157], v[162:165], v[50:53]
	v_mfma_f32_16x16x32_bf16 v[50:53], v[158:161], v[166:169], v[50:53]
	v_mfma_f32_16x16x32_bf16 v[46:49], v[130:133], v[170:173], v[46:49]
	v_mfma_f32_16x16x32_bf16 v[46:49], v[134:137], v[174:177], v[46:49]
	v_mfma_f32_16x16x32_bf16 v[42:45], v[138:141], v[170:173], v[42:45]
	v_mfma_f32_16x16x32_bf16 v[42:45], v[142:145], v[174:177], v[42:45]
	v_mfma_f32_16x16x32_bf16 v[38:41], v[146:149], v[170:173], v[38:41]
	v_mfma_f32_16x16x32_bf16 v[38:41], v[150:153], v[174:177], v[38:41]
	v_mfma_f32_16x16x32_bf16 v[34:37], v[154:157], v[170:173], v[34:37]
	v_mfma_f32_16x16x32_bf16 v[34:37], v[158:161], v[174:177], v[34:37]
	v_mfma_f32_16x16x32_bf16 v[30:33], v[130:133], v[178:181], v[30:33]
	v_mfma_f32_16x16x32_bf16 v[30:33], v[134:137], v[182:185], v[30:33]
	v_mfma_f32_16x16x32_bf16 v[26:29], v[138:141], v[178:181], v[26:29]
	v_mfma_f32_16x16x32_bf16 v[26:29], v[142:145], v[182:185], v[26:29]
	v_mfma_f32_16x16x32_bf16 v[22:25], v[146:149], v[178:181], v[22:25]
	v_mfma_f32_16x16x32_bf16 v[22:25], v[150:153], v[182:185], v[22:25]
	v_mfma_f32_16x16x32_bf16 v[18:21], v[154:157], v[178:181], v[18:21]
	v_mfma_f32_16x16x32_bf16 v[18:21], v[158:161], v[182:185], v[18:21]
	v_mfma_f32_16x16x32_bf16 v[14:17], v[130:133], v[220:223], v[14:17]
	v_mfma_f32_16x16x32_bf16 v[14:17], v[134:137], v[224:227], v[14:17]
	v_mfma_f32_16x16x32_bf16 v[10:13], v[138:141], v[220:223], v[10:13]
	v_mfma_f32_16x16x32_bf16 v[10:13], v[142:145], v[224:227], v[10:13]
	v_mfma_f32_16x16x32_bf16 v[6:9], v[146:149], v[220:223], v[6:9]
	v_mfma_f32_16x16x32_bf16 v[6:9], v[150:153], v[224:227], v[6:9]
	v_mfma_f32_16x16x32_bf16 v[2:5], v[154:157], v[220:223], v[2:5]
	v_mfma_f32_16x16x32_bf16 v[2:5], v[158:161], v[224:227], v[2:5]
	s_barrier
	s_setprio 0
	s_add_i32 s72, s72, 2
	s_add_u32 s70, s70, 0x10000
	s_addc_u32 s71, s71, 0
	s_add_u32 s38, s38, 0x100
	s_addc_u32 s39, s39, 0
	s_cmp_gt_u32 s72, 61
	s_cbranch_scc0 .LBB0_1103
	s_and_b64 vcc, exec, s[14:15]
	s_cbranch_vccz .LBB0_1106
	s_barrier

; #define PG8_STAGE(bufoff, gbase, voff) do { _Pragma("unroll") for (int _i = 0; _i < 2; ++_i) \
;         __builtin_amdgcn_global_load_lds((const unsigned*)((const char*)(gbase) + (voff)[_i]), (PG8_LAS unsigned*)(lds + (bufoff) + ldsw + _i * 8192), 16, 0, 0); } while (0)
; #define PG8_LDA(dst, b, h) do { _Pragma("unroll") for (int m = 0; m < 4; ++m) _Pragma("unroll") for (int k = 0; k < 2; ++k) dst[m][k] = *(const PG8_LAS bf16x8*)(lds + PG8_SA(b, h) + aoff + m * 2048 + k * 1024); } while (0)
; #define PG8_LDB(dst, b, h) do { _Pragma("unroll") for (int n = 0; n < 2; ++n) _Pragma("unroll") for (int k = 0; k < 2; ++k) dst[n][k] = *(const PG8_LAS bf16x8*)(lds + PG8_SB(b, h) + boff + n * 2048 + k * 1024); } while (0)
; #define PG8_MMA(ai, bj, At, Bt) do { __builtin_amdgcn_s_setprio(1); _Pragma("unroll") for (int m = 0; m < 4; ++m) _Pragma("unroll") for (int n = 0; n < 2; ++n) _Pragma("unroll") for (int k = 0; k < 2; ++k) \
;         acc[ai][bj][m][n] = __builtin_amdgcn_mfma_f32_16x16x32_bf16(Bt[n][k], At[m][k], acc[ai][bj][m][n], 0, 0, 0); __builtin_amdgcn_s_setprio(0); } while (0)
; #define PG8_WAIT_V(n) asm volatile("s_waitcnt vmcnt(" #n ")" ::: "memory")
; #define PG8_WAIT_L(n) asm volatile("s_waitcnt lgkmcnt(" #n ")" ::: "memory")
; #define PG8_BAR __builtin_amdgcn_s_barrier()
; #define PG8_SCHED __builtin_amdgcn_sched_barrier(0)
; template <class Epi, class Sched, bool ALIGN_EPI = false, bool SP2 = false, bool A_TILED = false>
; __device__ __forceinline__ void gemm_phase(PG8_LAS unsigned char* lds, const Gemm g, const Sched& S, const Epi& E) {
;     ...
;             PG8_LDB(B0, 0, 0); PG8_LDB(B1, 0, 1); PG8_SCHED; PG8_LDA(At, 0, 0); PG8_STAGE(PG8_SA(1, 1), a1 + hstepA, voffA);
;             PG8_WAIT_V(8); PG8_WAIT_L(0); PG8_BAR; PG8_MMA(0, 0, At, B0); PG8_MMA(0, 1, At, B1); PG8_BAR; PG8_SCHED;
;             PG8_LDA(At, 0, 1); PG8_STAGE(PG8_SB(0, 0), b2, voffB); PG8_STAGE(PG8_SB(0, 1), b2 + hstepB, voffB); PG8_STAGE(PG8_SA(0, 0), a2, voffA);
;             PG8_WAIT_V(8); PG8_WAIT_L(0); PG8_BAR; PG8_MMA(1, 0, At, B0); PG8_MMA(1, 1, At, B1); PG8_BAR; PG8_SCHED;
.LBB0_1172:
	ds_read_b128 v[152:155], v141
	ds_read_b128 v[160:163], v141 offset:1024
	ds_read_b128 v[164:167], v141 offset:2048
	ds_read_b128 v[168:171], v141 offset:3072
	ds_read_b128 v[172:175], v156
	ds_read_b128 v[176:179], v156 offset:1024
	ds_read_b128 v[180:183], v156 offset:2048
	ds_read_b128 v[184:187], v156 offset:3072
	s_add_u32 s24, s22, 0x4000
	s_addc_u32 s25, s23, 0
	s_cmp_eq_u32 s61, 60
	s_cselect_b32 s28, s33, s24
	s_cselect_b32 s29, s17, s25
	s_cselect_b32 s26, s58, s59
	s_cselect_b32 s27, s15, s60
	s_add_u32 s24, s28, 0x8000
	s_addc_u32 s25, s29, 0
	s_add_i32 m0, s38, 0xc000
	ds_read_b128 v[188:191], v157
	ds_read_b128 v[192:195], v157 offset:1024
	ds_read_b128 v[196:199], v157 offset:2048
	ds_read_b128 v[200:203], v157 offset:3072
	ds_read_b128 v[204:207], v157 offset:4096
	ds_read_b128 v[208:211], v157 offset:5120
	ds_read_b128 v[212:215], v157 offset:6144
	ds_read_b128 v[216:219], v157 offset:7168
	global_load_lds_dwordx4 v144, s[22:23]
	s_add_i32 m0, s38, 0xe000
	s_nop 0
	global_load_lds_dwordx4 v146, s[22:23]
	s_waitcnt vmcnt(8)
	s_waitcnt lgkmcnt(0)
	s_barrier
	s_setprio 1
	s_waitcnt lgkmcnt(0)
	v_mfma_f32_16x16x32_bf16 v[126:129], v[152:155], v[188:191], v[126:129]
	v_mfma_f32_16x16x32_bf16 v[122:125], v[164:167], v[188:191], v[122:125]
	v_mfma_f32_16x16x32_bf16 v[110:113], v[152:155], v[196:199], v[110:113]
	v_mfma_f32_16x16x32_bf16 v[106:109], v[164:167], v[196:199], v[106:109]
	v_mfma_f32_16x16x32_bf16 v[94:97], v[152:155], v[204:207], v[94:97]
	v_mfma_f32_16x16x32_bf16 v[90:93], v[164:167], v[204:207], v[90:93]
	v_mfma_f32_16x16x32_bf16 v[78:81], v[152:155], v[212:215], v[78:81]
	v_mfma_f32_16x16x32_bf16 v[74:77], v[164:167], v[212:215], v[74:77]
	v_mfma_f32_16x16x32_bf16 v[126:129], v[160:163], v[192:195], v[126:129]
	v_mfma_f32_16x16x32_bf16 v[122:125], v[168:171], v[192:195], v[122:125]
	v_mfma_f32_16x16x32_bf16 v[110:113], v[160:163], v[200:203], v[110:113]
	v_mfma_f32_16x16x32_bf16 v[106:109], v[168:171], v[200:203], v[106:109]
	v_mfma_f32_16x16x32_bf16 v[94:97], v[160:163], v[208:211], v[94:97]
	v_mfma_f32_16x16x32_bf16 v[90:93], v[168:171], v[208:211], v[90:93]
	v_mfma_f32_16x16x32_bf16 v[78:81], v[160:163], v[216:219], v[78:81]
	v_mfma_f32_16x16x32_bf16 v[74:77], v[168:171], v[216:219], v[74:77]
	s_setprio 0
	s_setprio 1
	v_mfma_f32_16x16x32_bf16 v[118:121], v[172:175], v[188:191], v[118:121]
	v_mfma_f32_16x16x32_bf16 v[114:117], v[180:183], v[188:191], v[114:117]
	v_mfma_f32_16x16x32_bf16 v[102:105], v[172:175], v[196:199], v[102:105]
	v_mfma_f32_16x16x32_bf16 v[98:101], v[180:183], v[196:199], v[98:101]
	v_mfma_f32_16x16x32_bf16 v[86:89], v[172:175], v[204:207], v[86:89]
	v_mfma_f32_16x16x32_bf16 v[82:85], v[180:183], v[204:207], v[82:85]
	v_mfma_f32_16x16x32_bf16 v[70:73], v[172:175], v[212:215], v[70:73]
	v_mfma_f32_16x16x32_bf16 v[66:69], v[180:183], v[212:215], v[66:69]
	v_mfma_f32_16x16x32_bf16 v[118:121], v[176:179], v[192:195], v[118:121]
	v_mfma_f32_16x16x32_bf16 v[114:117], v[184:187], v[192:195], v[114:117]
	v_mfma_f32_16x16x32_bf16 v[102:105], v[176:179], v[200:203], v[102:105]
	v_mfma_f32_16x16x32_bf16 v[98:101], v[184:187], v[200:203], v[98:101]
	v_mfma_f32_16x16x32_bf16 v[86:89], v[176:179], v[208:211], v[86:89]
	v_mfma_f32_16x16x32_bf16 v[82:85], v[184:187], v[208:211], v[82:85]
	v_mfma_f32_16x16x32_bf16 v[70:73], v[176:179], v[216:219], v[70:73]
	v_mfma_f32_16x16x32_bf16 v[66:69], v[184:187], v[216:219], v[66:69]
	s_setprio 0
	s_barrier
	s_add_i32 s62, s55, s35
	s_mov_b32 m0, s62
	ds_read_b128 v[188:191], v157 offset:16384
	ds_read_b128 v[192:195], v157 offset:17408
	ds_read_b128 v[196:199], v157 offset:18432
	ds_read_b128 v[200:203], v157 offset:19456
	ds_read_b128 v[204:207], v157 offset:20480
	ds_read_b128 v[208:211], v157 offset:21504
	ds_read_b128 v[212:215], v157 offset:22528
	ds_read_b128 v[216:219], v157 offset:23552
	global_load_lds_dwordx4 v132, s[26:27]
	s_add_i32 m0, s62, 0x2000
	s_add_u32 s62, s26, 0x4000
	s_addc_u32 s63, s27, 0
	s_add_i32 s64, s56, s35
	global_load_lds_dwordx4 v136, s[26:27]
	s_mov_b32 m0, s64
	s_nop 0
	global_load_lds_dwordx4 v132, s[62:63]
	s_add_i32 m0, s64, 0x2000
	s_nop 0
	global_load_lds_dwordx4 v136, s[62:63]
	s_mov_b32 m0, s38
	s_nop 0
	global_load_lds_dwordx4 v130, s[28:29]
	s_mov_b32 m0, s39
	s_nop 0
	global_load_lds_dwordx4 v134, s[28:29]
	s_waitcnt vmcnt(8)
	s_waitcnt lgkmcnt(0)
	s_setprio 1
	s_barrier
	v_mfma_f32_16x16x32_bf16 v[62:65], v[152:155], v[188:191], v[62:65]
	v_mfma_f32_16x16x32_bf16 v[62:65], v[160:163], v[192:195], v[62:65]
	v_mfma_f32_16x16x32_bf16 v[58:61], v[164:167], v[188:191], v[58:61]
	v_mfma_f32_16x16x32_bf16 v[58:61], v[168:171], v[192:195], v[58:61]
	v_mfma_f32_16x16x32_bf16 v[54:57], v[172:175], v[188:191], v[54:57]
	v_mfma_f32_16x16x32_bf16 v[54:57], v[176:179], v[192:195], v[54:57]
	v_mfma_f32_16x16x32_bf16 v[50:53], v[180:183], v[188:191], v[50:53]
	v_mfma_f32_16x16x32_bf16 v[50:53], v[184:187], v[192:195], v[50:53]
	v_mfma_f32_16x16x32_bf16 v[46:49], v[152:155], v[196:199], v[46:49]
	v_mfma_f32_16x16x32_bf16 v[46:49], v[160:163], v[200:203], v[46:49]
	v_mfma_f32_16x16x32_bf16 v[42:45], v[164:167], v[196:199], v[42:45]
	v_mfma_f32_16x16x32_bf16 v[42:45], v[168:171], v[200:203], v[42:45]
	v_mfma_f32_16x16x32_bf16 v[38:41], v[172:175], v[196:199], v[38:41]
	v_mfma_f32_16x16x32_bf16 v[38:41], v[176:179], v[200:203], v[38:41]
	v_mfma_f32_16x16x32_bf16 v[34:37], v[180:183], v[196:199], v[34:37]
	v_mfma_f32_16x16x32_bf16 v[34:37], v[184:187], v[200:203], v[34:37]
	v_mfma_f32_16x16x32_bf16 v[30:33], v[152:155], v[204:207], v[30:33]
	v_mfma_f32_16x16x32_bf16 v[30:33], v[160:163], v[208:211], v[30:33]
	v_mfma_f32_16x16x32_bf16 v[26:29], v[164:167], v[204:207], v[26:29]
	v_mfma_f32_16x16x32_bf16 v[26:29], v[168:171], v[208:211], v[26:29]
	v_mfma_f32_16x16x32_bf16 v[22:25], v[172:175], v[204:207], v[22:25]
	v_mfma_f32_16x16x32_bf16 v[22:25], v[176:179], v[208:211], v[22:25]
	v_mfma_f32_16x16x32_bf16 v[18:21], v[180:183], v[204:207], v[18:21]
	v_mfma_f32_16x16x32_bf16 v[18:21], v[184:187], v[208:211], v[18:21]
	v_mfma_f32_16x16x32_bf16 v[14:17], v[152:155], v[212:215], v[14:17]
	v_mfma_f32_16x16x32_bf16 v[14:17], v[160:163], v[216:219], v[14:17]
	v_mfma_f32_16x16x32_bf16 v[10:13], v[164:167], v[212:215], v[10:13]
	v_mfma_f32_16x16x32_bf16 v[10:13], v[168:171], v[216:219], v[10:13]
	v_mfma_f32_16x16x32_bf16 v[6:9], v[172:175], v[212:215], v[6:9]
	v_mfma_f32_16x16x32_bf16 v[6:9], v[176:179], v[216:219], v[6:9]
	v_mfma_f32_16x16x32_bf16 v[2:5], v[180:183], v[212:215], v[2:5]
	v_mfma_f32_16x16x32_bf16 v[2:5], v[184:187], v[216:219], v[2:5]
	s_barrier
; #define PG8_STAGE(bufoff, gbase, voff) do { _Pragma("unroll") for (int _i = 0; _i < 2; ++_i) \
;         __builtin_amdgcn_global_load_lds((const unsigned*)((const char*)(gbase) + (voff)[_i]), (PG8_LAS unsigned*)(lds + (bufoff) + ldsw + _i * 8192), 16, 0, 0); } while (0)
; #define PG8_LDA(dst, b, h) do { _Pragma("unroll") for (int m = 0; m < 4; ++m) _Pragma("unroll") for (int k = 0; k < 2; ++k) dst[m][k] = *(const PG8_LAS bf16x8*)(lds + PG8_SA(b, h) + aoff + m * 2048 + k * 1024); } while (0)
; #define PG8_LDB(dst, b, h) do { _Pragma("unroll") for (int n = 0; n < 2; ++n) _Pragma("unroll") for (int k = 0; k < 2; ++k) dst[n][k] = *(const PG8_LAS bf16x8*)(lds + PG8_SB(b, h) + boff + n * 2048 + k * 1024); } while (0)
; #define PG8_MMA(ai, bj, At, Bt) do { __builtin_amdgcn_s_setprio(1); _Pragma("unroll") for (int m = 0; m < 4; ++m) _Pragma("unroll") for (int n = 0; n < 2; ++n) _Pragma("unroll") for (int k = 0; k < 2; ++k) \
;         acc[ai][bj][m][n] = __builtin_amdgcn_mfma_f32_16x16x32_bf16(Bt[n][k], At[m][k], acc[ai][bj][m][n], 0, 0, 0); __builtin_amdgcn_s_setprio(0); } while (0)
; #define PG8_WAIT_V(n) asm volatile("s_waitcnt vmcnt(" #n ")" ::: "memory")
; #define PG8_WAIT_L(n) asm volatile("s_waitcnt lgkmcnt(" #n ")" ::: "memory")
; #define PG8_BAR __builtin_amdgcn_s_barrier()
; #define PG8_SCHED __builtin_amdgcn_sched_barrier(0)
; template <class Epi, class Sched, bool ALIGN_EPI = false, bool SP2 = false, bool A_TILED = false>
; __device__ __forceinline__ void gemm_phase(PG8_LAS unsigned char* lds, const Gemm g, const Sched& S, const Epi& E) {
;     ...
;             PG8_LDB(B0, 1, 0); PG8_LDB(B1, 1, 1); PG8_SCHED; PG8_LDA(At, 1, 0); PG8_STAGE(PG8_SA(0, 1), a2 + hstepA, voffA);
;             PG8_WAIT_V(8); PG8_WAIT_L(0); PG8_BAR; PG8_MMA(0, 0, At, B0); PG8_MMA(0, 1, At, B1); PG8_BAR; PG8_SCHED;
;             PG8_LDA(At, 1, 1); PG8_STAGE(PG8_SB(1, 0), b3, voffB); PG8_STAGE(PG8_SB(1, 1), b3 + hstepB, voffB); PG8_STAGE(PG8_SA(1, 0), a3, voffA);
;             PG8_WAIT_V(8); PG8_WAIT_L(0); PG8_BAR; PG8_MMA(1, 0, At, B0); PG8_MMA(1, 1, At, B1); PG8_BAR; PG8_SCHED;
	s_setprio 0
	s_add_i32 s62, 0, 0x18000
	s_add_i32 s63, 0, 0x1c000
	v_add_u32_e32 v168, s62, v1
	v_add_u32_e32 v184, s63, v1
	ds_read_b128 v[152:155], v168
	ds_read_b128 v[160:163], v168 offset:1024
	ds_read_b128 v[164:167], v168 offset:2048
	ds_read_b128 v[168:171], v168 offset:3072
	ds_read_b128 v[172:175], v184
	ds_read_b128 v[176:179], v184 offset:1024
	ds_read_b128 v[180:183], v184 offset:2048
	ds_read_b128 v[184:187], v184 offset:3072
	s_add_u32 s28, s28, 0x4000
	s_addc_u32 s29, s29, 0
	s_mov_b32 m0, s40
	ds_read_b128 v[188:191], v157 offset:32768
	ds_read_b128 v[192:195], v157 offset:33792
	ds_read_b128 v[196:199], v157 offset:34816
	ds_read_b128 v[200:203], v157 offset:35840
	ds_read_b128 v[204:207], v157 offset:36864
	ds_read_b128 v[208:211], v157 offset:37888
	ds_read_b128 v[212:215], v157 offset:38912
	ds_read_b128 v[216:219], v157 offset:39936
	global_load_lds_dwordx4 v130, s[28:29]
	s_mov_b32 m0, s41
	s_nop 0
	global_load_lds_dwordx4 v134, s[28:29]
	s_waitcnt vmcnt(8)
	s_waitcnt lgkmcnt(0)
	s_setprio 1
	s_barrier
	v_mfma_f32_16x16x32_bf16 v[126:129], v[152:155], v[188:191], v[126:129]
	v_mfma_f32_16x16x32_bf16 v[126:129], v[160:163], v[192:195], v[126:129]
	v_mfma_f32_16x16x32_bf16 v[122:125], v[164:167], v[188:191], v[122:125]
	v_mfma_f32_16x16x32_bf16 v[122:125], v[168:171], v[192:195], v[122:125]
	v_mfma_f32_16x16x32_bf16 v[118:121], v[172:175], v[188:191], v[118:121]
	v_mfma_f32_16x16x32_bf16 v[118:121], v[176:179], v[192:195], v[118:121]
	v_mfma_f32_16x16x32_bf16 v[114:117], v[180:183], v[188:191], v[114:117]
	v_mfma_f32_16x16x32_bf16 v[114:117], v[184:187], v[192:195], v[114:117]
	v_mfma_f32_16x16x32_bf16 v[110:113], v[152:155], v[196:199], v[110:113]
	v_mfma_f32_16x16x32_bf16 v[110:113], v[160:163], v[200:203], v[110:113]
	v_mfma_f32_16x16x32_bf16 v[106:109], v[164:167], v[196:199], v[106:109]
	v_mfma_f32_16x16x32_bf16 v[106:109], v[168:171], v[200:203], v[106:109]
	v_mfma_f32_16x16x32_bf16 v[102:105], v[172:175], v[196:199], v[102:105]
	v_mfma_f32_16x16x32_bf16 v[102:105], v[176:179], v[200:203], v[102:105]
	v_mfma_f32_16x16x32_bf16 v[98:101], v[180:183], v[196:199], v[98:101]
	v_mfma_f32_16x16x32_bf16 v[98:101], v[184:187], v[200:203], v[98:101]
	v_mfma_f32_16x16x32_bf16 v[94:97], v[152:155], v[204:207], v[94:97]
	v_mfma_f32_16x16x32_bf16 v[94:97], v[160:163], v[208:211], v[94:97]
	v_mfma_f32_16x16x32_bf16 v[90:93], v[164:167], v[204:207], v[90:93]
	v_mfma_f32_16x16x32_bf16 v[90:93], v[168:171], v[208:211], v[90:93]
	v_mfma_f32_16x16x32_bf16 v[86:89], v[172:175], v[204:207], v[86:89]
	v_mfma_f32_16x16x32_bf16 v[86:89], v[176:179], v[208:211], v[86:89]
	v_mfma_f32_16x16x32_bf16 v[82:85], v[180:183], v[204:207], v[82:85]
	v_mfma_f32_16x16x32_bf16 v[82:85], v[184:187], v[208:211], v[82:85]
	v_mfma_f32_16x16x32_bf16 v[78:81], v[152:155], v[212:215], v[78:81]
	v_mfma_f32_16x16x32_bf16 v[78:81], v[160:163], v[216:219], v[78:81]
	v_mfma_f32_16x16x32_bf16 v[74:77], v[164:167], v[212:215], v[74:77]
	v_mfma_f32_16x16x32_bf16 v[74:77], v[168:171], v[216:219], v[74:77]
	v_mfma_f32_16x16x32_bf16 v[70:73], v[172:175], v[212:215], v[70:73]
	v_mfma_f32_16x16x32_bf16 v[70:73], v[176:179], v[216:219], v[70:73]
	v_mfma_f32_16x16x32_bf16 v[66:69], v[180:183], v[212:215], v[66:69]
	v_mfma_f32_16x16x32_bf16 v[66:69], v[184:187], v[216:219], v[66:69]
	s_barrier
	s_setprio 0
	s_add_u32 s28, s26, 0x8000
	s_addc_u32 s29, s27, 0
	s_add_i32 s62, s62, s35
	s_mov_b32 m0, s62
	ds_read_b128 v[188:191], v157 offset:49152
	ds_read_b128 v[192:195], v157 offset:50176
	ds_read_b128 v[196:199], v157 offset:51200
	ds_read_b128 v[200:203], v157 offset:52224
	ds_read_b128 v[204:207], v157 offset:53248
	ds_read_b128 v[208:211], v157 offset:54272
	ds_read_b128 v[212:215], v157 offset:55296
	ds_read_b128 v[216:219], v157 offset:56320
	global_load_lds_dwordx4 v132, s[28:29]
	s_add_i32 m0, s62, 0x2000
	s_add_u32 s26, s26, 0xc000
	v_lshl_add_u64 v[220:221], s[28:29], 0, v[136:137]
	s_addc_u32 s27, s27, 0
	s_add_i32 s28, s63, s35
	global_load_lds_dwordx4 v[220:221], off
	s_mov_b32 m0, s28
	s_nop 0
	global_load_lds_dwordx4 v132, s[26:27]
	s_add_i32 m0, s28, 0x2000
	s_nop 0
	global_load_lds_dwordx4 v136, s[26:27]
	s_mov_b32 m0, s45
	s_nop 0
	global_load_lds_dwordx4 v130, s[24:25]
	s_mov_b32 m0, s54
	s_nop 0
	global_load_lds_dwordx4 v134, s[24:25]
	s_waitcnt vmcnt(8)
	s_waitcnt lgkmcnt(0)
	s_setprio 1
	s_barrier
	v_mfma_f32_16x16x32_bf16 v[62:65], v[152:155], v[188:191], v[62:65]
	v_mfma_f32_16x16x32_bf16 v[62:65], v[160:163], v[192:195], v[62:65]
	v_mfma_f32_16x16x32_bf16 v[58:61], v[164:167], v[188:191], v[58:61]
	v_mfma_f32_16x16x32_bf16 v[58:61], v[168:171], v[192:195], v[58:61]
	v_mfma_f32_16x16x32_bf16 v[54:57], v[172:175], v[188:191], v[54:57]
	v_mfma_f32_16x16x32_bf16 v[54:57], v[176:179], v[192:195], v[54:57]
	v_mfma_f32_16x16x32_bf16 v[50:53], v[180:183], v[188:191], v[50:53]
	v_mfma_f32_16x16x32_bf16 v[50:53], v[184:187], v[192:195], v[50:53]
	v_mfma_f32_16x16x32_bf16 v[46:49], v[152:155], v[196:199], v[46:49]
	v_mfma_f32_16x16x32_bf16 v[46:49], v[160:163], v[200:203], v[46:49]
	v_mfma_f32_16x16x32_bf16 v[42:45], v[164:167], v[196:199], v[42:45]
	v_mfma_f32_16x16x32_bf16 v[42:45], v[168:171], v[200:203], v[42:45]
	v_mfma_f32_16x16x32_bf16 v[38:41], v[172:175], v[196:199], v[38:41]
	v_mfma_f32_16x16x32_bf16 v[38:41], v[176:179], v[200:203], v[38:41]
	v_mfma_f32_16x16x32_bf16 v[34:37], v[180:183], v[196:199], v[34:37]
	v_mfma_f32_16x16x32_bf16 v[34:37], v[184:187], v[200:203], v[34:37]
	v_mfma_f32_16x16x32_bf16 v[30:33], v[152:155], v[204:207], v[30:33]
	v_mfma_f32_16x16x32_bf16 v[30:33], v[160:163], v[208:211], v[30:33]
	v_mfma_f32_16x16x32_bf16 v[26:29], v[164:167], v[204:207], v[26:29]
	v_mfma_f32_16x16x32_bf16 v[26:29], v[168:171], v[208:211], v[26:29]
	v_mfma_f32_16x16x32_bf16 v[22:25], v[172:175], v[204:207], v[22:25]
	v_mfma_f32_16x16x32_bf16 v[22:25], v[176:179], v[208:211], v[22:25]
	v_mfma_f32_16x16x32_bf16 v[18:21], v[180:183], v[204:207], v[18:21]
	v_mfma_f32_16x16x32_bf16 v[18:21], v[184:187], v[208:211], v[18:21]
	v_mfma_f32_16x16x32_bf16 v[14:17], v[152:155], v[212:215], v[14:17]
	v_mfma_f32_16x16x32_bf16 v[14:17], v[160:163], v[216:219], v[14:17]
	v_mfma_f32_16x16x32_bf16 v[10:13], v[164:167], v[212:215], v[10:13]
	v_mfma_f32_16x16x32_bf16 v[10:13], v[168:171], v[216:219], v[10:13]
	v_mfma_f32_16x16x32_bf16 v[6:9], v[172:175], v[212:215], v[6:9]
	v_mfma_f32_16x16x32_bf16 v[6:9], v[176:179], v[216:219], v[6:9]
	v_mfma_f32_16x16x32_bf16 v[2:5], v[180:183], v[212:215], v[2:5]
	v_mfma_f32_16x16x32_bf16 v[2:5], v[184:187], v[216:219], v[2:5]
	s_barrier
	s_setprio 0
	s_add_i32 s61, s61, 2
	s_add_u32 s22, s22, 0x10000
	s_addc_u32 s23, s23, 0
	s_add_u32 s59, s59, 0x10000
	s_addc_u32 s60, s60, 0
	s_cmp_gt_u32 s61, 61
	s_cbranch_scc0 .LBB0_1172
	s_and_b64 vcc, exec, s[12:13]
	s_cbranch_vccz .LBB0_1175
	s_barrier

; #define PG8_STAGE(bufoff, gbase, voff) do { _Pragma("unroll") for (int _i = 0; _i < 2; ++_i) \
;         __builtin_amdgcn_global_load_lds((const unsigned*)((const char*)(gbase) + (voff)[_i]), (PG8_LAS unsigned*)(lds + (bufoff) + ldsw + _i * 8192), 16, 0, 0); } while (0)
; #define PG8_LDA(dst, b, h) do { _Pragma("unroll") for (int m = 0; m < 4; ++m) _Pragma("unroll") for (int k = 0; k < 2; ++k) dst[m][k] = *(const PG8_LAS bf16x8*)(lds + PG8_SA(b, h) + aoff + m * 2048 + k * 1024); } while (0)
; #define PG8_LDB(dst, b, h) do { _Pragma("unroll") for (int n = 0; n < 2; ++n) _Pragma("unroll") for (int k = 0; k < 2; ++k) dst[n][k] = *(const PG8_LAS bf16x8*)(lds + PG8_SB(b, h) + boff + n * 2048 + k * 1024); } while (0)
; #define PG8_MMA(ai, bj, At, Bt) do { __builtin_amdgcn_s_setprio(1); _Pragma("unroll") for (int m = 0; m < 4; ++m) _Pragma("unroll") for (int n = 0; n < 2; ++n) _Pragma("unroll") for (int k = 0; k < 2; ++k) \
;         acc[ai][bj][m][n] = __builtin_amdgcn_mfma_f32_16x16x32_bf16(Bt[n][k], At[m][k], acc[ai][bj][m][n], 0, 0, 0); __builtin_amdgcn_s_setprio(0); } while (0)
; #define PG8_WAIT_V(n) asm volatile("s_waitcnt vmcnt(" #n ")" ::: "memory")
; #define PG8_WAIT_L(n) asm volatile("s_waitcnt lgkmcnt(" #n ")" ::: "memory")
; #define PG8_BAR __builtin_amdgcn_s_barrier()
; #define PG8_SCHED __builtin_amdgcn_sched_barrier(0)
; template <class Epi, class Sched, bool ALIGN_EPI = false, bool SP2 = false, bool A_TILED = false>
; __device__ __forceinline__ void gemm_phase(PG8_LAS unsigned char* lds, const Gemm g, const Sched& S, const Epi& E) {
;     ...
;             PG8_LDB(B0, 0, 0); PG8_LDB(B1, 0, 1); PG8_SCHED; PG8_LDA(At, 0, 0); PG8_STAGE(PG8_SA(1, 1), a1 + hstepA, voffA);
;             PG8_WAIT_V(8); PG8_WAIT_L(0); PG8_BAR; PG8_MMA(0, 0, At, B0); PG8_MMA(0, 1, At, B1); PG8_BAR; PG8_SCHED;
;             PG8_LDA(At, 0, 1); PG8_STAGE(PG8_SB(0, 0), b2, voffB); PG8_STAGE(PG8_SB(0, 1), b2 + hstepB, voffB); PG8_STAGE(PG8_SA(0, 0), a2, voffA);
;             PG8_WAIT_V(8); PG8_WAIT_L(0); PG8_BAR; PG8_MMA(1, 0, At, B0); PG8_MMA(1, 1, At, B1); PG8_BAR; PG8_SCHED;
.LBB0_1247:
	ds_read_b128 v[142:145], v156
	ds_read_b128 v[146:149], v156 offset:1024
	ds_read_b128 v[150:153], v156 offset:2048
	ds_read_b128 v[160:163], v156 offset:3072
	ds_read_b128 v[164:167], v157
	ds_read_b128 v[168:171], v157 offset:1024
	ds_read_b128 v[172:175], v157 offset:2048
	ds_read_b128 v[176:179], v157 offset:3072
	s_add_u32 s24, s22, 0x4000
	s_addc_u32 s25, s23, 0
	s_cmpk_eq_i32 s58, 0xa8
	s_cselect_b32 s28, s4, s24
	s_cselect_b32 s29, s5, s25
	s_cselect_b32 s26, s20, s56
	s_cselect_b32 s27, s21, s57
	s_add_u32 s24, s28, 0x8000
	s_addc_u32 s25, s29, 0
	s_add_i32 m0, s35, 0xc000
	ds_read_b128 v[180:183], v158
	ds_read_b128 v[184:187], v158 offset:1024
	ds_read_b128 v[188:191], v158 offset:2048
	ds_read_b128 v[192:195], v158 offset:3072
	ds_read_b128 v[196:199], v158 offset:4096
	ds_read_b128 v[200:203], v158 offset:5120
	ds_read_b128 v[204:207], v158 offset:6144
	ds_read_b128 v[208:211], v158 offset:7168
	global_load_lds_dwordx4 v134, s[22:23]
	s_add_i32 m0, s35, 0xe000
	s_nop 0
	global_load_lds_dwordx4 v136, s[22:23]
	s_waitcnt vmcnt(8)
	s_waitcnt lgkmcnt(0)
	s_barrier
	s_setprio 1
	s_waitcnt lgkmcnt(0)
	v_mfma_f32_16x16x32_bf16 v[126:129], v[142:145], v[180:183], v[126:129]
	v_mfma_f32_16x16x32_bf16 v[122:125], v[150:153], v[180:183], v[122:125]
	v_mfma_f32_16x16x32_bf16 v[118:121], v[142:145], v[188:191], v[118:121]
	v_mfma_f32_16x16x32_bf16 v[114:117], v[150:153], v[188:191], v[114:117]
	v_mfma_f32_16x16x32_bf16 v[94:97], v[142:145], v[196:199], v[94:97]
	v_mfma_f32_16x16x32_bf16 v[90:93], v[150:153], v[196:199], v[90:93]
	v_mfma_f32_16x16x32_bf16 v[86:89], v[142:145], v[204:207], v[86:89]
	v_mfma_f32_16x16x32_bf16 v[82:85], v[150:153], v[204:207], v[82:85]
	v_mfma_f32_16x16x32_bf16 v[126:129], v[146:149], v[184:187], v[126:129]
	v_mfma_f32_16x16x32_bf16 v[122:125], v[160:163], v[184:187], v[122:125]
	v_mfma_f32_16x16x32_bf16 v[118:121], v[146:149], v[192:195], v[118:121]
	v_mfma_f32_16x16x32_bf16 v[114:117], v[160:163], v[192:195], v[114:117]
	v_mfma_f32_16x16x32_bf16 v[94:97], v[146:149], v[200:203], v[94:97]
	v_mfma_f32_16x16x32_bf16 v[90:93], v[160:163], v[200:203], v[90:93]
	v_mfma_f32_16x16x32_bf16 v[86:89], v[146:149], v[208:211], v[86:89]
	v_mfma_f32_16x16x32_bf16 v[82:85], v[160:163], v[208:211], v[82:85]
	s_setprio 0
	s_setprio 1
	v_mfma_f32_16x16x32_bf16 v[110:113], v[164:167], v[180:183], v[110:113]
	v_mfma_f32_16x16x32_bf16 v[106:109], v[172:175], v[180:183], v[106:109]
	v_mfma_f32_16x16x32_bf16 v[102:105], v[164:167], v[188:191], v[102:105]
	v_mfma_f32_16x16x32_bf16 v[98:101], v[172:175], v[188:191], v[98:101]
	v_mfma_f32_16x16x32_bf16 v[78:81], v[164:167], v[196:199], v[78:81]
	v_mfma_f32_16x16x32_bf16 v[74:77], v[172:175], v[196:199], v[74:77]
	v_mfma_f32_16x16x32_bf16 v[70:73], v[164:167], v[204:207], v[70:73]
	v_mfma_f32_16x16x32_bf16 v[66:69], v[172:175], v[204:207], v[66:69]
	v_mfma_f32_16x16x32_bf16 v[110:113], v[168:171], v[184:187], v[110:113]
	v_mfma_f32_16x16x32_bf16 v[106:109], v[176:179], v[184:187], v[106:109]
	v_mfma_f32_16x16x32_bf16 v[102:105], v[168:171], v[192:195], v[102:105]
	v_mfma_f32_16x16x32_bf16 v[98:101], v[176:179], v[192:195], v[98:101]
	v_mfma_f32_16x16x32_bf16 v[78:81], v[168:171], v[200:203], v[78:81]
	v_mfma_f32_16x16x32_bf16 v[74:77], v[176:179], v[200:203], v[74:77]
	v_mfma_f32_16x16x32_bf16 v[70:73], v[168:171], v[208:211], v[70:73]
	v_mfma_f32_16x16x32_bf16 v[66:69], v[176:179], v[208:211], v[66:69]
	s_setprio 0
	s_barrier
	s_add_i32 s59, s42, s31
	s_mov_b32 m0, s59
	ds_read_b128 v[180:183], v158 offset:16384
	ds_read_b128 v[184:187], v158 offset:17408
	ds_read_b128 v[188:191], v158 offset:18432
	ds_read_b128 v[192:195], v158 offset:19456
	ds_read_b128 v[196:199], v158 offset:20480
	ds_read_b128 v[200:203], v158 offset:21504
	ds_read_b128 v[204:207], v158 offset:22528
	ds_read_b128 v[208:211], v158 offset:23552
	global_load_lds_dwordx4 v130, s[26:27]
	s_add_i32 m0, s59, 0x2000
	s_add_u32 s60, s26, 0x4000
	s_addc_u32 s61, s27, 0
	s_add_i32 s59, s43, s31
	global_load_lds_dwordx4 v132, s[26:27]
	s_mov_b32 m0, s59
	s_nop 0
	global_load_lds_dwordx4 v130, s[60:61]
	s_add_i32 m0, s59, 0x2000
	s_nop 0
	global_load_lds_dwordx4 v132, s[60:61]
	s_mov_b32 m0, s35
	s_nop 0
	global_load_lds_dwordx4 v130, s[28:29]
	s_mov_b32 m0, s36
	s_nop 0
	global_load_lds_dwordx4 v132, s[28:29]
	s_waitcnt vmcnt(8)
	s_waitcnt lgkmcnt(0)
	s_setprio 1
	s_barrier
	v_mfma_f32_16x16x32_bf16 v[62:65], v[142:145], v[180:183], v[62:65]
	v_mfma_f32_16x16x32_bf16 v[62:65], v[146:149], v[184:187], v[62:65]
	v_mfma_f32_16x16x32_bf16 v[58:61], v[150:153], v[180:183], v[58:61]
	v_mfma_f32_16x16x32_bf16 v[58:61], v[160:163], v[184:187], v[58:61]
	v_mfma_f32_16x16x32_bf16 v[50:53], v[164:167], v[180:183], v[50:53]
	v_mfma_f32_16x16x32_bf16 v[50:53], v[168:171], v[184:187], v[50:53]
	v_mfma_f32_16x16x32_bf16 v[42:45], v[172:175], v[180:183], v[42:45]
	v_mfma_f32_16x16x32_bf16 v[42:45], v[176:179], v[184:187], v[42:45]
	v_mfma_f32_16x16x32_bf16 v[54:57], v[142:145], v[188:191], v[54:57]
	v_mfma_f32_16x16x32_bf16 v[54:57], v[146:149], v[192:195], v[54:57]
	v_mfma_f32_16x16x32_bf16 v[46:49], v[150:153], v[188:191], v[46:49]
	v_mfma_f32_16x16x32_bf16 v[46:49], v[160:163], v[192:195], v[46:49]
	v_mfma_f32_16x16x32_bf16 v[34:37], v[164:167], v[188:191], v[34:37]
	v_mfma_f32_16x16x32_bf16 v[34:37], v[168:171], v[192:195], v[34:37]
	v_mfma_f32_16x16x32_bf16 v[26:29], v[172:175], v[188:191], v[26:29]
	v_mfma_f32_16x16x32_bf16 v[26:29], v[176:179], v[192:195], v[26:29]
	v_mfma_f32_16x16x32_bf16 v[38:41], v[142:145], v[196:199], v[38:41]
	v_mfma_f32_16x16x32_bf16 v[38:41], v[146:149], v[200:203], v[38:41]
	v_mfma_f32_16x16x32_bf16 v[30:33], v[150:153], v[196:199], v[30:33]
	v_mfma_f32_16x16x32_bf16 v[30:33], v[160:163], v[200:203], v[30:33]
	v_mfma_f32_16x16x32_bf16 v[18:21], v[164:167], v[196:199], v[18:21]
	v_mfma_f32_16x16x32_bf16 v[18:21], v[168:171], v[200:203], v[18:21]
	v_mfma_f32_16x16x32_bf16 v[10:13], v[172:175], v[196:199], v[10:13]
	v_mfma_f32_16x16x32_bf16 v[10:13], v[176:179], v[200:203], v[10:13]
	v_mfma_f32_16x16x32_bf16 v[22:25], v[142:145], v[204:207], v[22:25]
	v_mfma_f32_16x16x32_bf16 v[22:25], v[146:149], v[208:211], v[22:25]
	v_mfma_f32_16x16x32_bf16 v[14:17], v[150:153], v[204:207], v[14:17]
	v_mfma_f32_16x16x32_bf16 v[14:17], v[160:163], v[208:211], v[14:17]
	v_mfma_f32_16x16x32_bf16 v[6:9], v[164:167], v[204:207], v[6:9]
	v_mfma_f32_16x16x32_bf16 v[6:9], v[168:171], v[208:211], v[6:9]
	v_mfma_f32_16x16x32_bf16 v[2:5], v[172:175], v[204:207], v[2:5]
	v_mfma_f32_16x16x32_bf16 v[2:5], v[176:179], v[208:211], v[2:5]
	s_barrier
; #define PG8_STAGE(bufoff, gbase, voff) do { _Pragma("unroll") for (int _i = 0; _i < 2; ++_i) \
;         __builtin_amdgcn_global_load_lds((const unsigned*)((const char*)(gbase) + (voff)[_i]), (PG8_LAS unsigned*)(lds + (bufoff) + ldsw + _i * 8192), 16, 0, 0); } while (0)
; #define PG8_LDA(dst, b, h) do { _Pragma("unroll") for (int m = 0; m < 4; ++m) _Pragma("unroll") for (int k = 0; k < 2; ++k) dst[m][k] = *(const PG8_LAS bf16x8*)(lds + PG8_SA(b, h) + aoff + m * 2048 + k * 1024); } while (0)
; #define PG8_LDB(dst, b, h) do { _Pragma("unroll") for (int n = 0; n < 2; ++n) _Pragma("unroll") for (int k = 0; k < 2; ++k) dst[n][k] = *(const PG8_LAS bf16x8*)(lds + PG8_SB(b, h) + boff + n * 2048 + k * 1024); } while (0)
; #define PG8_MMA(ai, bj, At, Bt) do { __builtin_amdgcn_s_setprio(1); _Pragma("unroll") for (int m = 0; m < 4; ++m) _Pragma("unroll") for (int n = 0; n < 2; ++n) _Pragma("unroll") for (int k = 0; k < 2; ++k) \
;         acc[ai][bj][m][n] = __builtin_amdgcn_mfma_f32_16x16x32_bf16(Bt[n][k], At[m][k], acc[ai][bj][m][n], 0, 0, 0); __builtin_amdgcn_s_setprio(0); } while (0)
; #define PG8_WAIT_V(n) asm volatile("s_waitcnt vmcnt(" #n ")" ::: "memory")
; #define PG8_WAIT_L(n) asm volatile("s_waitcnt lgkmcnt(" #n ")" ::: "memory")
; #define PG8_BAR __builtin_amdgcn_s_barrier()
; #define PG8_SCHED __builtin_amdgcn_sched_barrier(0)
; template <class Epi, class Sched, bool ALIGN_EPI = false, bool SP2 = false, bool A_TILED = false>
; __device__ __forceinline__ void gemm_phase(PG8_LAS unsigned char* lds, const Gemm g, const Sched& S, const Epi& E) {
;     ...
;             PG8_LDB(B0, 1, 0); PG8_LDB(B1, 1, 1); PG8_SCHED; PG8_LDA(At, 1, 0); PG8_STAGE(PG8_SA(0, 1), a2 + hstepA, voffA);
;             PG8_WAIT_V(8); PG8_WAIT_L(0); PG8_BAR; PG8_MMA(0, 0, At, B0); PG8_MMA(0, 1, At, B1); PG8_BAR; PG8_SCHED;
;             PG8_LDA(At, 1, 1); PG8_STAGE(PG8_SB(1, 0), b3, voffB); PG8_STAGE(PG8_SB(1, 1), b3 + hstepB, voffB); PG8_STAGE(PG8_SA(1, 0), a3, voffA);
;             PG8_WAIT_V(8); PG8_WAIT_L(0); PG8_BAR; PG8_MMA(1, 0, At, B0); PG8_MMA(1, 1, At, B1); PG8_BAR; PG8_SCHED;
	s_setprio 0
	s_add_i32 s59, 0, 0x18000
	v_add_u32_e32 v159, s59, v154
	s_add_i32 s60, 0, 0x1c000
	ds_read_b128 v[142:145], v159
	ds_read_b128 v[146:149], v159 offset:1024
	ds_read_b128 v[150:153], v159 offset:2048
	ds_read_b128 v[160:163], v159 offset:3072
	v_add_u32_e32 v159, s60, v154
	ds_read_b128 v[164:167], v159
	ds_read_b128 v[168:171], v159 offset:1024
	ds_read_b128 v[172:175], v159 offset:2048
	ds_read_b128 v[176:179], v159 offset:3072
	s_add_u32 s28, s28, 0x4000
	s_addc_u32 s29, s29, 0
	s_mov_b32 m0, s37
	ds_read_b128 v[180:183], v158 offset:32768
	ds_read_b128 v[184:187], v158 offset:33792
	ds_read_b128 v[188:191], v158 offset:34816
	ds_read_b128 v[192:195], v158 offset:35840
	ds_read_b128 v[196:199], v158 offset:36864
	ds_read_b128 v[200:203], v158 offset:37888
	ds_read_b128 v[204:207], v158 offset:38912
	ds_read_b128 v[208:211], v158 offset:39936
	global_load_lds_dwordx4 v130, s[28:29]
	s_mov_b32 m0, s38
	s_nop 0
	global_load_lds_dwordx4 v132, s[28:29]
	s_waitcnt vmcnt(8)
	s_waitcnt lgkmcnt(0)
	s_setprio 1
	s_barrier
	v_mfma_f32_16x16x32_bf16 v[126:129], v[142:145], v[180:183], v[126:129]
	v_mfma_f32_16x16x32_bf16 v[126:129], v[146:149], v[184:187], v[126:129]
	v_mfma_f32_16x16x32_bf16 v[122:125], v[150:153], v[180:183], v[122:125]
	v_mfma_f32_16x16x32_bf16 v[122:125], v[160:163], v[184:187], v[122:125]
	v_mfma_f32_16x16x32_bf16 v[110:113], v[164:167], v[180:183], v[110:113]
	v_mfma_f32_16x16x32_bf16 v[110:113], v[168:171], v[184:187], v[110:113]
	v_mfma_f32_16x16x32_bf16 v[106:109], v[172:175], v[180:183], v[106:109]
	v_mfma_f32_16x16x32_bf16 v[106:109], v[176:179], v[184:187], v[106:109]
	v_mfma_f32_16x16x32_bf16 v[118:121], v[142:145], v[188:191], v[118:121]
	v_mfma_f32_16x16x32_bf16 v[118:121], v[146:149], v[192:195], v[118:121]
	v_mfma_f32_16x16x32_bf16 v[114:117], v[150:153], v[188:191], v[114:117]
	v_mfma_f32_16x16x32_bf16 v[114:117], v[160:163], v[192:195], v[114:117]
	v_mfma_f32_16x16x32_bf16 v[102:105], v[164:167], v[188:191], v[102:105]
	v_mfma_f32_16x16x32_bf16 v[102:105], v[168:171], v[192:195], v[102:105]
	v_mfma_f32_16x16x32_bf16 v[98:101], v[172:175], v[188:191], v[98:101]
	v_mfma_f32_16x16x32_bf16 v[98:101], v[176:179], v[192:195], v[98:101]
	v_mfma_f32_16x16x32_bf16 v[94:97], v[142:145], v[196:199], v[94:97]
	v_mfma_f32_16x16x32_bf16 v[94:97], v[146:149], v[200:203], v[94:97]
	v_mfma_f32_16x16x32_bf16 v[90:93], v[150:153], v[196:199], v[90:93]
	v_mfma_f32_16x16x32_bf16 v[90:93], v[160:163], v[200:203], v[90:93]
	v_mfma_f32_16x16x32_bf16 v[78:81], v[164:167], v[196:199], v[78:81]
	v_mfma_f32_16x16x32_bf16 v[78:81], v[168:171], v[200:203], v[78:81]
	v_mfma_f32_16x16x32_bf16 v[74:77], v[172:175], v[196:199], v[74:77]
	v_mfma_f32_16x16x32_bf16 v[74:77], v[176:179], v[200:203], v[74:77]
	v_mfma_f32_16x16x32_bf16 v[86:89], v[142:145], v[204:207], v[86:89]
	v_mfma_f32_16x16x32_bf16 v[86:89], v[146:149], v[208:211], v[86:89]
	v_mfma_f32_16x16x32_bf16 v[82:85], v[150:153], v[204:207], v[82:85]
	v_mfma_f32_16x16x32_bf16 v[82:85], v[160:163], v[208:211], v[82:85]
	v_mfma_f32_16x16x32_bf16 v[70:73], v[164:167], v[204:207], v[70:73]
	v_mfma_f32_16x16x32_bf16 v[70:73], v[168:171], v[208:211], v[70:73]
	v_mfma_f32_16x16x32_bf16 v[66:69], v[172:175], v[204:207], v[66:69]
	v_mfma_f32_16x16x32_bf16 v[66:69], v[176:179], v[208:211], v[66:69]
	s_barrier
	s_setprio 0
	s_add_u32 s28, s26, 0x8000
	s_addc_u32 s29, s27, 0
	s_add_i32 s59, s59, s31
	s_mov_b32 m0, s59
	ds_read_b128 v[180:183], v158 offset:49152
	ds_read_b128 v[184:187], v158 offset:50176
	ds_read_b128 v[188:191], v158 offset:51200
	ds_read_b128 v[192:195], v158 offset:52224
	ds_read_b128 v[196:199], v158 offset:53248
	ds_read_b128 v[200:203], v158 offset:54272
	ds_read_b128 v[204:207], v158 offset:55296
	ds_read_b128 v[208:211], v158 offset:56320
	global_load_lds_dwordx4 v130, s[28:29]
	s_add_i32 m0, s59, 0x2000
	s_add_u32 s26, s26, 0xc000
	v_lshl_add_u64 v[212:213], s[28:29], 0, v[132:133]
	s_addc_u32 s27, s27, 0
	s_add_i32 s28, s60, s31
	global_load_lds_dwordx4 v[212:213], off
	s_mov_b32 m0, s28
	s_nop 0
	global_load_lds_dwordx4 v130, s[26:27]
	s_add_i32 m0, s28, 0x2000
	s_nop 0
	global_load_lds_dwordx4 v132, s[26:27]
	s_mov_b32 m0, s40
	s_nop 0
	global_load_lds_dwordx4 v130, s[24:25]
	s_mov_b32 m0, s41
	s_nop 0
	global_load_lds_dwordx4 v132, s[24:25]
	s_waitcnt vmcnt(8)
	s_waitcnt lgkmcnt(0)
	s_setprio 1
	s_barrier
	v_mfma_f32_16x16x32_bf16 v[62:65], v[142:145], v[180:183], v[62:65]
	v_mfma_f32_16x16x32_bf16 v[62:65], v[146:149], v[184:187], v[62:65]
	v_mfma_f32_16x16x32_bf16 v[58:61], v[150:153], v[180:183], v[58:61]
	v_mfma_f32_16x16x32_bf16 v[58:61], v[160:163], v[184:187], v[58:61]
	v_mfma_f32_16x16x32_bf16 v[50:53], v[164:167], v[180:183], v[50:53]
	v_mfma_f32_16x16x32_bf16 v[50:53], v[168:171], v[184:187], v[50:53]
	v_mfma_f32_16x16x32_bf16 v[42:45], v[172:175], v[180:183], v[42:45]
	v_mfma_f32_16x16x32_bf16 v[42:45], v[176:179], v[184:187], v[42:45]
	v_mfma_f32_16x16x32_bf16 v[54:57], v[142:145], v[188:191], v[54:57]
	v_mfma_f32_16x16x32_bf16 v[54:57], v[146:149], v[192:195], v[54:57]
	v_mfma_f32_16x16x32_bf16 v[46:49], v[150:153], v[188:191], v[46:49]
	v_mfma_f32_16x16x32_bf16 v[46:49], v[160:163], v[192:195], v[46:49]
	v_mfma_f32_16x16x32_bf16 v[34:37], v[164:167], v[188:191], v[34:37]
	v_mfma_f32_16x16x32_bf16 v[34:37], v[168:171], v[192:195], v[34:37]
	v_mfma_f32_16x16x32_bf16 v[26:29], v[172:175], v[188:191], v[26:29]
	v_mfma_f32_16x16x32_bf16 v[26:29], v[176:179], v[192:195], v[26:29]
	v_mfma_f32_16x16x32_bf16 v[38:41], v[142:145], v[196:199], v[38:41]
	v_mfma_f32_16x16x32_bf16 v[38:41], v[146:149], v[200:203], v[38:41]
	v_mfma_f32_16x16x32_bf16 v[30:33], v[150:153], v[196:199], v[30:33]
	v_mfma_f32_16x16x32_bf16 v[30:33], v[160:163], v[200:203], v[30:33]
	v_mfma_f32_16x16x32_bf16 v[18:21], v[164:167], v[196:199], v[18:21]
	v_mfma_f32_16x16x32_bf16 v[18:21], v[168:171], v[200:203], v[18:21]
	v_mfma_f32_16x16x32_bf16 v[10:13], v[172:175], v[196:199], v[10:13]
	v_mfma_f32_16x16x32_bf16 v[10:13], v[176:179], v[200:203], v[10:13]
	v_mfma_f32_16x16x32_bf16 v[22:25], v[142:145], v[204:207], v[22:25]
	v_mfma_f32_16x16x32_bf16 v[22:25], v[146:149], v[208:211], v[22:25]
	v_mfma_f32_16x16x32_bf16 v[14:17], v[150:153], v[204:207], v[14:17]
	v_mfma_f32_16x16x32_bf16 v[14:17], v[160:163], v[208:211], v[14:17]
	v_mfma_f32_16x16x32_bf16 v[6:9], v[164:167], v[204:207], v[6:9]
	v_mfma_f32_16x16x32_bf16 v[6:9], v[168:171], v[208:211], v[6:9]
	v_mfma_f32_16x16x32_bf16 v[2:5], v[172:175], v[204:207], v[2:5]
	v_mfma_f32_16x16x32_bf16 v[2:5], v[176:179], v[208:211], v[2:5]
	s_barrier
	s_setprio 0
	s_add_i32 s58, s58, 2
	s_add_u32 s22, s22, 0x10000
	s_addc_u32 s23, s23, 0
	s_add_u32 s56, s56, 0x10000
	s_addc_u32 s57, s57, 0
	s_cmpk_gt_u32 s58, 0xa9
	s_cbranch_scc0 .LBB0_1247
	s_and_b64 vcc, exec, s[10:11]
	s_cbranch_vccz .LBB0_1250
	s_barrier
